# GEMM phases: first unit's accumulators v32-v127 zeroed in the phase prologue under the first tile DMAs (flag-skipped in the unit loop)
# baseline (speedup 1.0000x reference)
.LBB0_169:
	s_lshl_b32 s3, s3, 5
	s_mov_b64 s[8:9], 0x80
	s_and_b32 s14, s3, 0x60
	s_add_i32 m0, s21, 0x18000
	v_lshl_add_u64 v[6:7], v[6:7], 0, s[8:9]
	s_lshl_b32 s11, s10, 13
	s_lshl_b32 s15, s14, 7
	s_mov_b32 s98, 1
	v_mov_b32_e32 v32, 0
	v_mov_b32_e32 v33, 0
	v_mov_b32_e32 v34, 0
	v_mov_b32_e32 v35, 0
	v_mov_b32_e32 v36, 0
	v_mov_b32_e32 v37, 0
	v_mov_b32_e32 v38, 0
	v_mov_b32_e32 v39, 0
	v_mov_b32_e32 v40, 0
	v_mov_b32_e32 v41, 0
	v_mov_b32_e32 v42, 0
	v_mov_b32_e32 v43, 0
	v_mov_b32_e32 v44, 0
	v_mov_b32_e32 v45, 0
	v_mov_b32_e32 v46, 0
	v_mov_b32_e32 v47, 0
	v_mov_b32_e32 v48, 0
	v_mov_b32_e32 v49, 0
	v_mov_b32_e32 v50, 0
	v_mov_b32_e32 v51, 0
	v_mov_b32_e32 v52, 0
	v_mov_b32_e32 v53, 0
	v_mov_b32_e32 v54, 0
	v_mov_b32_e32 v55, 0
	v_mov_b32_e32 v56, 0
	v_mov_b32_e32 v57, 0
	v_mov_b32_e32 v58, 0
	v_mov_b32_e32 v59, 0
	v_mov_b32_e32 v60, 0
	v_mov_b32_e32 v61, 0
	v_mov_b32_e32 v62, 0
	v_mov_b32_e32 v63, 0
	v_mov_b32_e32 v64, 0
	v_mov_b32_e32 v65, 0
	v_mov_b32_e32 v66, 0
	v_mov_b32_e32 v67, 0
	v_mov_b32_e32 v68, 0
	v_mov_b32_e32 v69, 0
	v_mov_b32_e32 v70, 0
	v_mov_b32_e32 v71, 0
	v_mov_b32_e32 v72, 0
	v_mov_b32_e32 v73, 0
	v_mov_b32_e32 v74, 0
	v_mov_b32_e32 v75, 0
	v_mov_b32_e32 v76, 0
	v_mov_b32_e32 v77, 0
	v_mov_b32_e32 v78, 0
	v_mov_b32_e32 v79, 0
	v_mov_b32_e32 v80, 0
	v_mov_b32_e32 v81, 0
	v_mov_b32_e32 v82, 0
	v_mov_b32_e32 v83, 0
	v_mov_b32_e32 v84, 0
	v_mov_b32_e32 v85, 0
	v_mov_b32_e32 v86, 0
	v_mov_b32_e32 v87, 0
	v_mov_b32_e32 v88, 0
	v_mov_b32_e32 v89, 0
	v_mov_b32_e32 v90, 0
	v_mov_b32_e32 v91, 0
	v_mov_b32_e32 v92, 0
	v_mov_b32_e32 v93, 0
	v_mov_b32_e32 v94, 0
	v_mov_b32_e32 v95, 0
	v_mov_b32_e32 v96, 0
	v_mov_b32_e32 v97, 0
	v_mov_b32_e32 v98, 0
	v_mov_b32_e32 v99, 0
	v_mov_b32_e32 v100, 0
	v_mov_b32_e32 v101, 0
	v_mov_b32_e32 v102, 0
	v_mov_b32_e32 v103, 0
	v_mov_b32_e32 v104, 0
	v_mov_b32_e32 v105, 0
	v_mov_b32_e32 v106, 0
	v_mov_b32_e32 v107, 0
	v_mov_b32_e32 v108, 0
	v_mov_b32_e32 v109, 0
	v_mov_b32_e32 v110, 0
	v_mov_b32_e32 v111, 0
	v_mov_b32_e32 v112, 0
	v_mov_b32_e32 v113, 0
	v_mov_b32_e32 v114, 0
	v_mov_b32_e32 v115, 0
	v_mov_b32_e32 v116, 0
	v_mov_b32_e32 v117, 0
	v_mov_b32_e32 v118, 0
	v_mov_b32_e32 v119, 0
	v_mov_b32_e32 v120, 0
	v_mov_b32_e32 v121, 0
	v_mov_b32_e32 v122, 0
	v_mov_b32_e32 v123, 0
	v_mov_b32_e32 v124, 0
	v_mov_b32_e32 v125, 0
	v_mov_b32_e32 v126, 0
	v_mov_b32_e32 v127, 0
	s_nop 0
	s_nop 0
	s_nop 0
	s_nop 0
	s_nop 0
	s_nop 0
	s_nop 0
	s_nop 0
	s_nop 0
	s_nop 0
	s_nop 0
	s_nop 0
	s_waitcnt vmcnt(2)
	s_barrier
	global_load_lds_dwordx4 v[6:7], off
	v_lshl_add_u64 v[4:5], v[4:5], 0, s[8:9]
	s_add_i32 m0, s21, 0x1a000
	s_add_i32 s76, s21, 0x8000
	s_add_i32 s77, s21, 0xa000
	global_load_lds_dwordx4 v[4:5], off
	v_lshl_add_u64 v[0:1], v[0:1], 0, s[8:9]
	s_mov_b32 m0, s76
	s_add_u32 s12, s24, 0x40080
	global_load_lds_dwordx4 v[0:1], off
	v_lshl_add_u64 v[0:1], v[2:3], 0, s[8:9]
	s_mov_b32 m0, s77
	s_addc_u32 s13, s25, 0
	global_load_lds_dwordx4 v[0:1], off
	s_add_i32 m0, s21, 0x1c000
	v_lshl_add_u64 v[0:1], s[12:13], 0, v[132:133]
	global_load_lds_dwordx4 v[0:1], off
	v_lshl_add_u64 v[0:1], s[12:13], 0, v[128:129]
	s_add_i32 m0, s21, 0x1e000
	s_cmpk_lt_u32 s1, 0x100
	global_load_lds_dwordx4 v[0:1], off
	v_lshrrev_b32_e32 v1, 1, v9
	v_and_b32_e32 v1, 24, v1
	v_and_b32_e32 v0, 15, v9
	v_lshlrev_b32_e32 v2, 1, v1
	v_lshl_or_b32 v148, s10, 6, v0
	v_lshl_or_b32 v0, v0, 6, v2
	v_lshlrev_b32_e32 v2, 2, v9
	v_and_b32_e32 v2, 32, v2
	v_bitop3_b32 v3, v0, s11, v2 bitop3:0xde
	v_bitop3_b32 v149, v0, s15, v2 bitop3:0xde
	v_lshlrev_b32_e32 v0, 14, v13
	v_and_b32_e32 v0, 0xffff8000, v0
	v_or_b32_e32 v150, s14, v1
	v_lshl_add_u32 v0, v12, 11, v0
	v_and_b32_e32 v1, 1, v13
	v_lshl_or_b32 v0, v1, 6, v0
	v_lshl_add_u32 v136, v14, 1, v0
	v_lshlrev_b32_e32 v0, 14, v8
	v_and_b32_e32 v0, 0xffff8000, v0
	s_waitcnt vmcnt(6)
	v_lshl_add_u32 v0, v10, 11, v0
	v_and_b32_e32 v1, 1, v8
	s_cselect_b64 s[10:11], -1, 0
	v_lshl_or_b32 v0, v1, 6, v0
	s_add_i32 s79, 0, 0x10000
	s_add_i32 s84, 0, 0x14000
	s_sext_i32_i8 s3, s0
	s_ashr_i32 s78, s28, 31
	v_mov_b32_e32 v137, v133
	v_lshl_add_u32 v138, v11, 1, v0
	v_mov_b32_e32 v139, v133
	v_mov_b64_e32 v[140:141], 0x280
	v_mov_b64_e32 v[142:143], 0x27f
	v_add_u32_e32 v151, s79, v149
	v_add_u32_e32 v152, s84, v149
	v_add_u32_e32 v153, 0, v3
	v_mov_b32_e32 v154, 0x358637bd
	s_movk_i32 s85, 0x1400
	v_mov_b32_e32 v155, 0x3e38aa3b
	s_barrier
	s_branch .LBB0_172

.LBB0_174:
	s_ashr_i32 s15, s14, 31
	s_lshl_b64 s[16:17], s[14:15], 19
	s_add_u32 s16, s82, s16
	s_addc_u32 s17, s83, s17
	s_and_b64 s[18:19], s[0:1], exec
	s_cselect_b32 s15, s17, s23
	s_cselect_b32 s86, s16, s22
	s_ashr_i32 s13, s12, 31
	s_lshl_b64 s[18:19], s[12:13], 19
	s_add_u32 s18, s33, s18
	s_addc_u32 s19, s38, s19
	s_and_b64 s[26:27], s[0:1], exec
	s_cselect_b32 s13, s19, s25
	s_cselect_b32 s87, s18, s24
	s_add_u32 s22, s22, 0x40080
	s_addc_u32 s23, s23, 0
	s_add_u32 s88, s24, 0x100
	v_mov_b32_e32 v0, 0
	s_addc_u32 s89, s25, 0
	s_mov_b32 s90, -2
	v_mov_b32_e32 v1, v0
	v_mov_b32_e32 v2, v0
	v_mov_b32_e32 v3, v0
	v_mov_b32_e32 v4, v0
	v_mov_b32_e32 v5, v0
	v_mov_b32_e32 v6, v0
	v_mov_b32_e32 v7, v0
	s_nop 0
	v_mov_b32_e32 v8, v0
	v_mov_b32_e32 v9, v0
	v_mov_b32_e32 v10, v0
	v_mov_b32_e32 v11, v0
	v_mov_b32_e32 v12, v0
	v_mov_b32_e32 v13, v0
	v_mov_b32_e32 v14, v0
	v_mov_b32_e32 v15, v0
	v_mov_b32_e32 v16, v0
	v_mov_b32_e32 v17, v0
	v_mov_b32_e32 v18, v0
	v_mov_b32_e32 v19, v0
	v_mov_b32_e32 v20, v0
	v_mov_b32_e32 v21, v0
	v_mov_b32_e32 v22, v0
	v_mov_b32_e32 v23, v0
	v_mov_b32_e32 v24, v0
	v_mov_b32_e32 v25, v0
	v_mov_b32_e32 v26, v0
	v_mov_b32_e32 v27, v0
	v_mov_b32_e32 v28, v0
	v_mov_b32_e32 v29, v0
	v_mov_b32_e32 v30, v0
	v_mov_b32_e32 v31, v0
	s_cmp_eq_u32 s98, 1
	s_mov_b32 s98, 0
	s_cbranch_scc1 .Lzskip_0
	v_mov_b32_e32 v32, v0
	v_mov_b32_e32 v33, v0
	v_mov_b32_e32 v34, v0
	v_mov_b32_e32 v35, v0
	v_mov_b32_e32 v36, v0
	v_mov_b32_e32 v37, v0
	v_mov_b32_e32 v38, v0
	v_mov_b32_e32 v39, v0
	v_mov_b32_e32 v40, v0
	v_mov_b32_e32 v41, v0
	v_mov_b32_e32 v42, v0
	v_mov_b32_e32 v43, v0
	v_mov_b32_e32 v44, v0
	v_mov_b32_e32 v45, v0
	v_mov_b32_e32 v46, v0
	v_mov_b32_e32 v47, v0
	v_mov_b32_e32 v48, v0
	v_mov_b32_e32 v49, v0
	v_mov_b32_e32 v50, v0
	v_mov_b32_e32 v51, v0
	v_mov_b32_e32 v52, v0
	v_mov_b32_e32 v53, v0
	v_mov_b32_e32 v54, v0
	v_mov_b32_e32 v55, v0
	v_mov_b32_e32 v56, v0
	v_mov_b32_e32 v57, v0
	v_mov_b32_e32 v58, v0
	v_mov_b32_e32 v59, v0
	v_mov_b32_e32 v60, v0
	v_mov_b32_e32 v61, v0
	v_mov_b32_e32 v62, v0
	v_mov_b32_e32 v63, v0
	v_mov_b32_e32 v64, v0
	v_mov_b32_e32 v65, v0
	v_mov_b32_e32 v66, v0
	v_mov_b32_e32 v67, v0
	v_mov_b32_e32 v68, v0
	v_mov_b32_e32 v69, v0
	v_mov_b32_e32 v70, v0
	v_mov_b32_e32 v71, v0
	v_mov_b32_e32 v72, v0
	v_mov_b32_e32 v73, v0
	v_mov_b32_e32 v74, v0
	v_mov_b32_e32 v75, v0
	v_mov_b32_e32 v76, v0
	v_mov_b32_e32 v77, v0
	v_mov_b32_e32 v78, v0
	v_mov_b32_e32 v79, v0
	v_mov_b32_e32 v80, v0
	v_mov_b32_e32 v81, v0
	v_mov_b32_e32 v82, v0
	v_mov_b32_e32 v83, v0
	v_mov_b32_e32 v84, v0
	v_mov_b32_e32 v85, v0
	v_mov_b32_e32 v86, v0
	v_mov_b32_e32 v87, v0
	v_mov_b32_e32 v88, v0
	v_mov_b32_e32 v89, v0
	v_mov_b32_e32 v90, v0
	v_mov_b32_e32 v91, v0
	v_mov_b32_e32 v92, v0
	v_mov_b32_e32 v93, v0
	v_mov_b32_e32 v94, v0
	v_mov_b32_e32 v95, v0
	v_mov_b32_e32 v96, v0
	v_mov_b32_e32 v97, v0
	v_mov_b32_e32 v98, v0
	v_mov_b32_e32 v99, v0
	v_mov_b32_e32 v100, v0
	v_mov_b32_e32 v101, v0
	v_mov_b32_e32 v102, v0
	v_mov_b32_e32 v103, v0
	v_mov_b32_e32 v104, v0
	v_mov_b32_e32 v105, v0
	v_mov_b32_e32 v106, v0
	v_mov_b32_e32 v107, v0
	v_mov_b32_e32 v108, v0
	v_mov_b32_e32 v109, v0
	v_mov_b32_e32 v110, v0
	v_mov_b32_e32 v111, v0
	v_mov_b32_e32 v112, v0
	v_mov_b32_e32 v113, v0
	v_mov_b32_e32 v114, v0
	v_mov_b32_e32 v115, v0
	v_mov_b32_e32 v116, v0
	v_mov_b32_e32 v117, v0
	v_mov_b32_e32 v118, v0
	v_mov_b32_e32 v119, v0
	v_mov_b32_e32 v120, v0
	v_mov_b32_e32 v121, v0
	v_mov_b32_e32 v122, v0
	v_mov_b32_e32 v123, v0
	v_mov_b32_e32 v124, v0
	v_mov_b32_e32 v125, v0
	v_mov_b32_e32 v126, v0
	v_mov_b32_e32 v127, v0
.Lzskip_0:
.LBB0_175:
	ds_read_b128 v[144:147], v151
	ds_read_b128 v[156:159], v151 offset:1024
	ds_read_b128 v[160:163], v151 offset:2048
	ds_read_b128 v[164:167], v151 offset:3072
	ds_read_b128 v[168:171], v152
	ds_read_b128 v[172:175], v152 offset:1024
	ds_read_b128 v[176:179], v152 offset:2048
	ds_read_b128 v[180:183], v152 offset:3072
	s_add_u32 s24, s22, 0xfffc0080
	s_addc_u32 s25, s23, -1
	s_cmp_eq_u32 s90, 12
	s_cselect_b32 s27, s15, s25
	s_cselect_b32 s26, s86, s24
	s_cselect_b32 s25, s13, s89
	s_cselect_b32 s24, s87, s88
	v_lshl_add_u64 v[204:205], s[22:23], 0, v[136:137]
	s_add_i32 m0, s21, 0xc000
	ds_read_b128 v[184:187], v153
	ds_read_b128 v[188:191], v153 offset:1024
	ds_read_b128 v[192:195], v153 offset:2048
	ds_read_b128 v[196:199], v153 offset:3072
	ds_read_b128 v[200:203], v153 offset:4096
	ds_read_b128 v[208:211], v153 offset:5120
	ds_read_b128 v[212:215], v153 offset:6144
	ds_read_b128 v[216:219], v153 offset:7168
	global_load_lds_dwordx4 v[204:205], off
	v_lshl_add_u64 v[204:205], s[22:23], 0, v[138:139]
	s_add_i32 m0, s21, 0xe000
	s_nop 0
	global_load_lds_dwordx4 v[204:205], off
	s_waitcnt vmcnt(8)
	s_waitcnt lgkmcnt(0)
	s_setprio 1
	s_barrier
	v_mfma_f32_16x16x32_bf16 v[124:127], v[144:147], v[184:187], v[124:127]
	v_mfma_f32_16x16x32_bf16 v[120:123], v[160:163], v[184:187], v[120:123]
	v_mfma_f32_16x16x32_bf16 v[116:119], v[144:147], v[192:195], v[116:119]
	v_mfma_f32_16x16x32_bf16 v[112:115], v[160:163], v[192:195], v[112:115]
	v_mfma_f32_16x16x32_bf16 v[104:107], v[144:147], v[200:203], v[104:107]
	v_mfma_f32_16x16x32_bf16 v[96:99], v[160:163], v[200:203], v[96:99]
	v_mfma_f32_16x16x32_bf16 v[76:79], v[144:147], v[212:215], v[76:79]
	v_mfma_f32_16x16x32_bf16 v[72:75], v[160:163], v[212:215], v[72:75]
	v_mfma_f32_16x16x32_bf16 v[124:127], v[156:159], v[188:191], v[124:127]
	v_mfma_f32_16x16x32_bf16 v[120:123], v[164:167], v[188:191], v[120:123]
	v_mfma_f32_16x16x32_bf16 v[116:119], v[156:159], v[196:199], v[116:119]
	v_mfma_f32_16x16x32_bf16 v[112:115], v[164:167], v[196:199], v[112:115]
	v_mfma_f32_16x16x32_bf16 v[104:107], v[156:159], v[208:211], v[104:107]
	v_mfma_f32_16x16x32_bf16 v[96:99], v[164:167], v[208:211], v[96:99]
	v_mfma_f32_16x16x32_bf16 v[76:79], v[156:159], v[216:219], v[76:79]
	v_mfma_f32_16x16x32_bf16 v[72:75], v[164:167], v[216:219], v[72:75]
	s_setprio 0
	s_setprio 1
	v_mfma_f32_16x16x32_bf16 v[108:111], v[168:171], v[184:187], v[108:111]
	v_mfma_f32_16x16x32_bf16 v[100:103], v[176:179], v[184:187], v[100:103]
	v_mfma_f32_16x16x32_bf16 v[92:95], v[168:171], v[192:195], v[92:95]
	v_mfma_f32_16x16x32_bf16 v[88:91], v[176:179], v[192:195], v[88:91]
	v_mfma_f32_16x16x32_bf16 v[84:87], v[168:171], v[200:203], v[84:87]
	v_mfma_f32_16x16x32_bf16 v[80:83], v[176:179], v[200:203], v[80:83]
	v_mfma_f32_16x16x32_bf16 v[68:71], v[168:171], v[212:215], v[68:71]
	v_mfma_f32_16x16x32_bf16 v[64:67], v[176:179], v[212:215], v[64:67]
	v_mfma_f32_16x16x32_bf16 v[108:111], v[172:175], v[188:191], v[108:111]
	v_mfma_f32_16x16x32_bf16 v[100:103], v[180:183], v[188:191], v[100:103]
	v_mfma_f32_16x16x32_bf16 v[92:95], v[172:175], v[196:199], v[92:95]
	v_mfma_f32_16x16x32_bf16 v[88:91], v[180:183], v[196:199], v[88:91]
	v_mfma_f32_16x16x32_bf16 v[84:87], v[172:175], v[208:211], v[84:87]
	v_mfma_f32_16x16x32_bf16 v[80:83], v[180:183], v[208:211], v[80:83]
	v_mfma_f32_16x16x32_bf16 v[68:71], v[172:175], v[216:219], v[68:71]
	v_mfma_f32_16x16x32_bf16 v[64:67], v[180:183], v[216:219], v[64:67]
	s_barrier
	s_setprio 0
	s_add_i32 s91, s79, s30
	v_lshl_add_u64 v[204:205], s[24:25], 0, v[132:133]
	s_mov_b32 m0, s91
	ds_read_b128 v[184:187], v153 offset:16384
	ds_read_b128 v[188:191], v153 offset:17408
	ds_read_b128 v[192:195], v153 offset:18432
	ds_read_b128 v[196:199], v153 offset:19456
	ds_read_b128 v[200:203], v153 offset:20480
	ds_read_b128 v[208:211], v153 offset:21504
	ds_read_b128 v[212:215], v153 offset:22528
	ds_read_b128 v[216:219], v153 offset:23552
	global_load_lds_dwordx4 v[204:205], off
	s_add_i32 m0, s91, 0x2000
	s_add_u32 s92, s24, 0x40000
	v_lshl_add_u64 v[220:221], s[24:25], 0, v[128:129]
	s_addc_u32 s93, s25, 0
	s_add_i32 s91, s84, s30
	global_load_lds_dwordx4 v[220:221], off
	v_lshl_add_u64 v[222:223], s[92:93], 0, v[132:133]
	s_mov_b32 m0, s91
	v_lshl_add_u64 v[224:225], s[26:27], 0, v[130:131]
	global_load_lds_dwordx4 v[222:223], off
	v_lshl_add_u64 v[222:223], s[92:93], 0, v[128:129]
	s_add_i32 m0, s91, 0x2000
	s_nop 0
	global_load_lds_dwordx4 v[222:223], off
	v_lshl_add_u64 v[222:223], s[26:27], 0, v[134:135]
	s_mov_b32 m0, s21
	s_nop 0
	global_load_lds_dwordx4 v[222:223], off
	s_mov_b32 m0, s35
	s_nop 0
	global_load_lds_dwordx4 v[224:225], off
	s_waitcnt vmcnt(8)
	s_waitcnt lgkmcnt(0)
	s_setprio 1
	s_barrier
	v_mfma_f32_16x16x32_bf16 v[60:63], v[144:147], v[184:187], v[60:63]
	v_mfma_f32_16x16x32_bf16 v[56:59], v[160:163], v[184:187], v[56:59]
	v_mfma_f32_16x16x32_bf16 v[44:47], v[144:147], v[192:195], v[44:47]
	v_mfma_f32_16x16x32_bf16 v[40:43], v[160:163], v[192:195], v[40:43]
	v_mfma_f32_16x16x32_bf16 v[28:31], v[144:147], v[200:203], v[28:31]
	v_mfma_f32_16x16x32_bf16 v[24:27], v[160:163], v[200:203], v[24:27]
	v_mfma_f32_16x16x32_bf16 v[12:15], v[144:147], v[212:215], v[12:15]
	v_mfma_f32_16x16x32_bf16 v[8:11], v[160:163], v[212:215], v[8:11]
	v_mfma_f32_16x16x32_bf16 v[60:63], v[156:159], v[188:191], v[60:63]
	v_mfma_f32_16x16x32_bf16 v[56:59], v[164:167], v[188:191], v[56:59]
	v_mfma_f32_16x16x32_bf16 v[44:47], v[156:159], v[196:199], v[44:47]
	v_mfma_f32_16x16x32_bf16 v[40:43], v[164:167], v[196:199], v[40:43]
	v_mfma_f32_16x16x32_bf16 v[28:31], v[156:159], v[208:211], v[28:31]
	v_mfma_f32_16x16x32_bf16 v[24:27], v[164:167], v[208:211], v[24:27]
	v_mfma_f32_16x16x32_bf16 v[12:15], v[156:159], v[216:219], v[12:15]
	v_mfma_f32_16x16x32_bf16 v[8:11], v[164:167], v[216:219], v[8:11]
	s_setprio 0
	s_setprio 1
	v_mfma_f32_16x16x32_bf16 v[52:55], v[168:171], v[184:187], v[52:55]
	v_mfma_f32_16x16x32_bf16 v[48:51], v[176:179], v[184:187], v[48:51]
	v_mfma_f32_16x16x32_bf16 v[36:39], v[168:171], v[192:195], v[36:39]
	v_mfma_f32_16x16x32_bf16 v[32:35], v[176:179], v[192:195], v[32:35]
	v_mfma_f32_16x16x32_bf16 v[20:23], v[168:171], v[200:203], v[20:23]
	v_mfma_f32_16x16x32_bf16 v[16:19], v[176:179], v[200:203], v[16:19]
	v_mfma_f32_16x16x32_bf16 v[4:7], v[168:171], v[212:215], v[4:7]
	v_mfma_f32_16x16x32_bf16 v[0:3], v[176:179], v[212:215], v[0:3]
	v_mfma_f32_16x16x32_bf16 v[52:55], v[172:175], v[188:191], v[52:55]
	v_mfma_f32_16x16x32_bf16 v[48:51], v[180:183], v[188:191], v[48:51]
	v_mfma_f32_16x16x32_bf16 v[36:39], v[172:175], v[196:199], v[36:39]
	v_mfma_f32_16x16x32_bf16 v[32:35], v[180:183], v[196:199], v[32:35]
	v_mfma_f32_16x16x32_bf16 v[20:23], v[172:175], v[208:211], v[20:23]
	v_mfma_f32_16x16x32_bf16 v[16:19], v[180:183], v[208:211], v[16:19]
	v_mfma_f32_16x16x32_bf16 v[4:7], v[172:175], v[216:219], v[4:7]
	v_mfma_f32_16x16x32_bf16 v[0:3], v[180:183], v[216:219], v[0:3]
	s_barrier
	s_setprio 0
	s_add_i32 s91, 0, 0x18000
	s_add_i32 s92, 0, 0x1c000
	v_add_u32_e32 v164, s91, v149
	v_add_u32_e32 v180, s92, v149
	ds_read_b128 v[144:147], v164
	ds_read_b128 v[156:159], v164 offset:1024
	ds_read_b128 v[160:163], v164 offset:2048
	ds_read_b128 v[164:167], v164 offset:3072
	ds_read_b128 v[168:171], v180
	ds_read_b128 v[172:175], v180 offset:1024
	ds_read_b128 v[176:179], v180 offset:2048
	ds_read_b128 v[180:183], v180 offset:3072
	s_add_u32 s26, s26, 0x40000
	s_addc_u32 s27, s27, 0
	s_mov_b32 m0, s36
	v_lshl_add_u64 v[226:227], s[26:27], 0, v[134:135]
	ds_read_b128 v[184:187], v153 offset:32768
	ds_read_b128 v[188:191], v153 offset:33792
	ds_read_b128 v[192:195], v153 offset:34816
	ds_read_b128 v[196:199], v153 offset:35840
	ds_read_b128 v[200:203], v153 offset:36864
	ds_read_b128 v[208:211], v153 offset:37888
	ds_read_b128 v[212:215], v153 offset:38912
	ds_read_b128 v[216:219], v153 offset:39936
	global_load_lds_dwordx4 v[226:227], off
	v_lshl_add_u64 v[226:227], s[26:27], 0, v[130:131]
	s_mov_b32 m0, s37
	s_nop 0
	global_load_lds_dwordx4 v[226:227], off
	s_waitcnt vmcnt(8)
	s_waitcnt lgkmcnt(0)
	s_setprio 1
	s_barrier
	v_mfma_f32_16x16x32_bf16 v[124:127], v[144:147], v[184:187], v[124:127]
	v_mfma_f32_16x16x32_bf16 v[120:123], v[160:163], v[184:187], v[120:123]
	v_mfma_f32_16x16x32_bf16 v[116:119], v[144:147], v[192:195], v[116:119]
	v_mfma_f32_16x16x32_bf16 v[112:115], v[160:163], v[192:195], v[112:115]
	v_mfma_f32_16x16x32_bf16 v[104:107], v[144:147], v[200:203], v[104:107]
	v_mfma_f32_16x16x32_bf16 v[96:99], v[160:163], v[200:203], v[96:99]
	v_mfma_f32_16x16x32_bf16 v[76:79], v[144:147], v[212:215], v[76:79]
	v_mfma_f32_16x16x32_bf16 v[72:75], v[160:163], v[212:215], v[72:75]
	v_mfma_f32_16x16x32_bf16 v[124:127], v[156:159], v[188:191], v[124:127]
	v_mfma_f32_16x16x32_bf16 v[120:123], v[164:167], v[188:191], v[120:123]
	v_mfma_f32_16x16x32_bf16 v[116:119], v[156:159], v[196:199], v[116:119]
	v_mfma_f32_16x16x32_bf16 v[112:115], v[164:167], v[196:199], v[112:115]
	v_mfma_f32_16x16x32_bf16 v[104:107], v[156:159], v[208:211], v[104:107]
	v_mfma_f32_16x16x32_bf16 v[96:99], v[164:167], v[208:211], v[96:99]
	v_mfma_f32_16x16x32_bf16 v[76:79], v[156:159], v[216:219], v[76:79]
	v_mfma_f32_16x16x32_bf16 v[72:75], v[164:167], v[216:219], v[72:75]
	s_setprio 0
	s_setprio 1
	v_mfma_f32_16x16x32_bf16 v[108:111], v[168:171], v[184:187], v[108:111]
	v_mfma_f32_16x16x32_bf16 v[100:103], v[176:179], v[184:187], v[100:103]
	v_mfma_f32_16x16x32_bf16 v[92:95], v[168:171], v[192:195], v[92:95]
	v_mfma_f32_16x16x32_bf16 v[88:91], v[176:179], v[192:195], v[88:91]
	v_mfma_f32_16x16x32_bf16 v[84:87], v[168:171], v[200:203], v[84:87]
	v_mfma_f32_16x16x32_bf16 v[80:83], v[176:179], v[200:203], v[80:83]
	v_mfma_f32_16x16x32_bf16 v[68:71], v[168:171], v[212:215], v[68:71]
	v_mfma_f32_16x16x32_bf16 v[64:67], v[176:179], v[212:215], v[64:67]
	v_mfma_f32_16x16x32_bf16 v[108:111], v[172:175], v[188:191], v[108:111]
	v_mfma_f32_16x16x32_bf16 v[100:103], v[180:183], v[188:191], v[100:103]
	v_mfma_f32_16x16x32_bf16 v[92:95], v[172:175], v[196:199], v[92:95]
	v_mfma_f32_16x16x32_bf16 v[88:91], v[180:183], v[196:199], v[88:91]
	v_mfma_f32_16x16x32_bf16 v[84:87], v[172:175], v[208:211], v[84:87]
	v_mfma_f32_16x16x32_bf16 v[80:83], v[180:183], v[208:211], v[80:83]
	v_mfma_f32_16x16x32_bf16 v[68:71], v[172:175], v[216:219], v[68:71]
	v_mfma_f32_16x16x32_bf16 v[64:67], v[180:183], v[216:219], v[64:67]
	s_barrier
	s_setprio 0
	s_add_i32 s26, s91, s30
	v_lshl_add_u64 v[204:205], v[204:205], 0, s[8:9]
	s_mov_b32 m0, s26
	ds_read_b128 v[184:187], v153 offset:49152
	ds_read_b128 v[188:191], v153 offset:50176
	ds_read_b128 v[192:195], v153 offset:51200
	ds_read_b128 v[196:199], v153 offset:52224
	ds_read_b128 v[200:203], v153 offset:53248
	ds_read_b128 v[208:211], v153 offset:54272
	ds_read_b128 v[212:215], v153 offset:55296
	ds_read_b128 v[216:219], v153 offset:56320
	global_load_lds_dwordx4 v[204:205], off
	s_add_i32 m0, s26, 0x2000
	s_add_u32 s24, s24, 0x40080
	v_lshl_add_u64 v[204:205], v[220:221], 0, s[8:9]
	s_addc_u32 s25, s25, 0
	s_add_i32 s26, s92, s30
	global_load_lds_dwordx4 v[204:205], off
	v_lshl_add_u64 v[204:205], s[24:25], 0, v[132:133]
	s_mov_b32 m0, s26
	s_nop 0
	global_load_lds_dwordx4 v[204:205], off
	v_lshl_add_u64 v[204:205], s[24:25], 0, v[128:129]
	s_add_i32 m0, s26, 0x2000
	s_nop 0
	global_load_lds_dwordx4 v[204:205], off
	v_lshl_add_u64 v[204:205], v[222:223], 0, s[8:9]
	s_mov_b32 m0, s76
	s_nop 0
	global_load_lds_dwordx4 v[204:205], off
	v_lshl_add_u64 v[204:205], v[224:225], 0, s[8:9]
	s_mov_b32 m0, s77
	s_nop 0
	global_load_lds_dwordx4 v[204:205], off
	s_waitcnt vmcnt(8)
	s_waitcnt lgkmcnt(0)
	s_setprio 1
	s_barrier
	v_mfma_f32_16x16x32_bf16 v[60:63], v[144:147], v[184:187], v[60:63]
	v_mfma_f32_16x16x32_bf16 v[56:59], v[160:163], v[184:187], v[56:59]
	v_mfma_f32_16x16x32_bf16 v[44:47], v[144:147], v[192:195], v[44:47]
	v_mfma_f32_16x16x32_bf16 v[40:43], v[160:163], v[192:195], v[40:43]
	v_mfma_f32_16x16x32_bf16 v[28:31], v[144:147], v[200:203], v[28:31]
	v_mfma_f32_16x16x32_bf16 v[24:27], v[160:163], v[200:203], v[24:27]
	v_mfma_f32_16x16x32_bf16 v[12:15], v[144:147], v[212:215], v[12:15]
	v_mfma_f32_16x16x32_bf16 v[8:11], v[160:163], v[212:215], v[8:11]
	v_mfma_f32_16x16x32_bf16 v[60:63], v[156:159], v[188:191], v[60:63]
	v_mfma_f32_16x16x32_bf16 v[56:59], v[164:167], v[188:191], v[56:59]
	v_mfma_f32_16x16x32_bf16 v[44:47], v[156:159], v[196:199], v[44:47]
	v_mfma_f32_16x16x32_bf16 v[40:43], v[164:167], v[196:199], v[40:43]
	v_mfma_f32_16x16x32_bf16 v[28:31], v[156:159], v[208:211], v[28:31]
	v_mfma_f32_16x16x32_bf16 v[24:27], v[164:167], v[208:211], v[24:27]
	v_mfma_f32_16x16x32_bf16 v[12:15], v[156:159], v[216:219], v[12:15]
	v_mfma_f32_16x16x32_bf16 v[8:11], v[164:167], v[216:219], v[8:11]
	s_setprio 0
	s_setprio 1
	v_mfma_f32_16x16x32_bf16 v[52:55], v[168:171], v[184:187], v[52:55]
	v_mfma_f32_16x16x32_bf16 v[48:51], v[176:179], v[184:187], v[48:51]
	v_mfma_f32_16x16x32_bf16 v[36:39], v[168:171], v[192:195], v[36:39]
	v_mfma_f32_16x16x32_bf16 v[32:35], v[176:179], v[192:195], v[32:35]
	v_mfma_f32_16x16x32_bf16 v[20:23], v[168:171], v[200:203], v[20:23]
	v_mfma_f32_16x16x32_bf16 v[16:19], v[176:179], v[200:203], v[16:19]
	v_mfma_f32_16x16x32_bf16 v[4:7], v[168:171], v[212:215], v[4:7]
	v_mfma_f32_16x16x32_bf16 v[0:3], v[176:179], v[212:215], v[0:3]
	v_mfma_f32_16x16x32_bf16 v[52:55], v[172:175], v[188:191], v[52:55]
	v_mfma_f32_16x16x32_bf16 v[48:51], v[180:183], v[188:191], v[48:51]
	v_mfma_f32_16x16x32_bf16 v[36:39], v[172:175], v[196:199], v[36:39]
	v_mfma_f32_16x16x32_bf16 v[32:35], v[180:183], v[196:199], v[32:35]
	v_mfma_f32_16x16x32_bf16 v[20:23], v[172:175], v[208:211], v[20:23]
	v_mfma_f32_16x16x32_bf16 v[16:19], v[180:183], v[208:211], v[16:19]
	v_mfma_f32_16x16x32_bf16 v[4:7], v[172:175], v[216:219], v[4:7]
	v_mfma_f32_16x16x32_bf16 v[0:3], v[180:183], v[216:219], v[0:3]
	s_barrier
	s_setprio 0
	s_add_i32 s90, s90, 2
	s_add_u32 s22, s22, 0x100
	s_addc_u32 s23, s23, 0
	s_add_u32 s88, s88, 0x100
	s_addc_u32 s89, s89, 0
	s_cmp_gt_u32 s90, 13
	s_cbranch_scc0 .LBB0_175
	s_and_b64 vcc, exec, s[10:11]
	s_cbranch_vccz .LBB0_178
	s_barrier

.LBB0_189:
	s_lshl_b32 s3, s3, 5
	s_mov_b64 s[8:9], 0x80
	s_and_b32 s14, s3, 0x60
	s_add_i32 m0, s21, 0x18000
	v_lshl_add_u64 v[6:7], v[6:7], 0, s[8:9]
	s_lshl_b32 s11, s1, 13
	s_lshl_b32 s15, s14, 7
	s_mov_b32 s98, 1
	v_mov_b32_e32 v32, 0
	v_mov_b32_e32 v33, 0
	v_mov_b32_e32 v34, 0
	v_mov_b32_e32 v35, 0
	v_mov_b32_e32 v36, 0
	v_mov_b32_e32 v37, 0
	v_mov_b32_e32 v38, 0
	v_mov_b32_e32 v39, 0
	v_mov_b32_e32 v40, 0
	v_mov_b32_e32 v41, 0
	v_mov_b32_e32 v42, 0
	v_mov_b32_e32 v43, 0
	v_mov_b32_e32 v44, 0
	v_mov_b32_e32 v45, 0
	v_mov_b32_e32 v46, 0
	v_mov_b32_e32 v47, 0
	v_mov_b32_e32 v48, 0
	v_mov_b32_e32 v49, 0
	v_mov_b32_e32 v50, 0
	v_mov_b32_e32 v51, 0
	v_mov_b32_e32 v52, 0
	v_mov_b32_e32 v53, 0
	v_mov_b32_e32 v54, 0
	v_mov_b32_e32 v55, 0
	v_mov_b32_e32 v56, 0
	v_mov_b32_e32 v57, 0
	v_mov_b32_e32 v58, 0
	v_mov_b32_e32 v59, 0
	v_mov_b32_e32 v60, 0
	v_mov_b32_e32 v61, 0
	v_mov_b32_e32 v62, 0
	v_mov_b32_e32 v63, 0
	v_mov_b32_e32 v64, 0
	v_mov_b32_e32 v65, 0
	v_mov_b32_e32 v66, 0
	v_mov_b32_e32 v67, 0
	v_mov_b32_e32 v68, 0
	v_mov_b32_e32 v69, 0
	v_mov_b32_e32 v70, 0
	v_mov_b32_e32 v71, 0
	v_mov_b32_e32 v72, 0
	v_mov_b32_e32 v73, 0
	v_mov_b32_e32 v74, 0
	v_mov_b32_e32 v75, 0
	v_mov_b32_e32 v76, 0
	v_mov_b32_e32 v77, 0
	v_mov_b32_e32 v78, 0
	v_mov_b32_e32 v79, 0
	v_mov_b32_e32 v80, 0
	v_mov_b32_e32 v81, 0
	v_mov_b32_e32 v82, 0
	v_mov_b32_e32 v83, 0
	v_mov_b32_e32 v84, 0
	v_mov_b32_e32 v85, 0
	v_mov_b32_e32 v86, 0
	v_mov_b32_e32 v87, 0
	v_mov_b32_e32 v88, 0
	v_mov_b32_e32 v89, 0
	v_mov_b32_e32 v90, 0
	v_mov_b32_e32 v91, 0
	v_mov_b32_e32 v92, 0
	v_mov_b32_e32 v93, 0
	v_mov_b32_e32 v94, 0
	v_mov_b32_e32 v95, 0
	v_mov_b32_e32 v96, 0
	v_mov_b32_e32 v97, 0
	v_mov_b32_e32 v98, 0
	v_mov_b32_e32 v99, 0
	v_mov_b32_e32 v100, 0
	v_mov_b32_e32 v101, 0
	v_mov_b32_e32 v102, 0
	v_mov_b32_e32 v103, 0
	v_mov_b32_e32 v104, 0
	v_mov_b32_e32 v105, 0
	v_mov_b32_e32 v106, 0
	v_mov_b32_e32 v107, 0
	v_mov_b32_e32 v108, 0
	v_mov_b32_e32 v109, 0
	v_mov_b32_e32 v110, 0
	v_mov_b32_e32 v111, 0
	v_mov_b32_e32 v112, 0
	v_mov_b32_e32 v113, 0
	v_mov_b32_e32 v114, 0
	v_mov_b32_e32 v115, 0
	v_mov_b32_e32 v116, 0
	v_mov_b32_e32 v117, 0
	v_mov_b32_e32 v118, 0
	v_mov_b32_e32 v119, 0
	v_mov_b32_e32 v120, 0
	v_mov_b32_e32 v121, 0
	v_mov_b32_e32 v122, 0
	v_mov_b32_e32 v123, 0
	v_mov_b32_e32 v124, 0
	v_mov_b32_e32 v125, 0
	v_mov_b32_e32 v126, 0
	v_mov_b32_e32 v127, 0
	s_nop 0
	s_nop 0
	s_nop 0
	s_nop 0
	s_nop 0
	s_nop 0
	s_nop 0
	s_nop 0
	s_nop 0
	s_nop 0
	s_nop 0
	s_nop 0
	s_waitcnt vmcnt(2)
	s_barrier
	global_load_lds_dwordx4 v[6:7], off
	v_lshl_add_u64 v[4:5], v[4:5], 0, s[8:9]
	s_add_i32 m0, s21, 0x1a000
	s_add_i32 s77, s21, 0x8000
	s_add_i32 s78, s21, 0xa000
	global_load_lds_dwordx4 v[4:5], off
	v_lshl_add_u64 v[0:1], v[0:1], 0, s[8:9]
	s_mov_b32 m0, s77
	s_add_u32 s12, s24, 0x40080
	global_load_lds_dwordx4 v[0:1], off
	v_lshl_add_u64 v[0:1], v[2:3], 0, s[8:9]
	s_mov_b32 m0, s78
	s_addc_u32 s13, s25, 0
	global_load_lds_dwordx4 v[0:1], off
	s_add_i32 m0, s21, 0x1c000
	v_lshl_add_u64 v[0:1], s[12:13], 0, v[130:131]
	global_load_lds_dwordx4 v[0:1], off
	v_lshl_add_u64 v[0:1], s[12:13], 0, v[134:135]
	s_add_i32 m0, s21, 0x1e000
	s_cmpk_lt_u32 s10, 0x100
	global_load_lds_dwordx4 v[0:1], off
	v_lshrrev_b32_e32 v1, 1, v8
	v_and_b32_e32 v1, 24, v1
	v_and_b32_e32 v0, 15, v8
	v_lshlrev_b32_e32 v2, 1, v1
	v_lshl_or_b32 v164, s1, 6, v0
	v_lshl_or_b32 v0, v0, 6, v2
	v_lshlrev_b32_e32 v2, 2, v8
	v_and_b32_e32 v2, 32, v2
	v_bitop3_b32 v3, v0, s11, v2 bitop3:0xde
	v_bitop3_b32 v165, v0, s15, v2 bitop3:0xde
	v_lshlrev_b32_e32 v0, 14, v9
	v_and_b32_e32 v0, 0xffff8000, v0
	v_or_b32_e32 v166, s14, v1
	v_lshl_add_u32 v0, v10, 11, v0
	v_and_b32_e32 v1, 1, v9
	v_lshl_or_b32 v0, v1, 6, v0
	v_lshl_add_u32 v136, v11, 1, v0
	v_lshlrev_b32_e32 v0, 14, v12
	v_and_b32_e32 v0, 0xffff8000, v0
	s_waitcnt vmcnt(6)
	v_lshl_add_u32 v0, v13, 11, v0
	v_and_b32_e32 v1, 1, v12
	s_cselect_b64 s[10:11], -1, 0
	v_lshl_or_b32 v0, v1, 6, v0
	s_add_i32 s84, 0, 0x10000
	s_add_i32 s85, 0, 0x14000
	s_sext_i32_i16 s3, s0
	s_ashr_i32 s79, s28, 31
	v_mov_b32_e32 v137, v131
	v_lshl_add_u32 v138, v14, 1, v0
	v_mov_b32_e32 v139, v131
	v_mov_b64_e32 v[140:141], 0x80
	v_mov_b64_e32 v[142:143], 0x7f
	v_add_u32_e32 v167, s84, v165
	v_add_u32_e32 v168, s85, v165
	v_add_u32_e32 v169, 0, v3
	v_mov_b32_e32 v170, 0x358637bd
	s_barrier
	s_branch .LBB0_192

.LBB0_198:
	s_ashr_i32 s15, s14, 31
	s_lshl_b64 s[16:17], s[14:15], 19
	s_add_u32 s16, s31, s16
	s_addc_u32 s17, s34, s17
	s_and_b64 s[18:19], s[0:1], exec
	s_cselect_b32 s15, s17, s23
	s_cselect_b32 s88, s16, s22
	s_ashr_i32 s13, s12, 31
	s_lshl_b64 s[18:19], s[12:13], 19
	s_add_u32 s18, s82, s18
	s_addc_u32 s19, s83, s19
	s_and_b64 s[26:27], s[0:1], exec
	s_cselect_b32 s13, s19, s25
	s_cselect_b32 s89, s18, s24
	s_add_u32 s22, s22, 0x40080
	s_addc_u32 s23, s23, 0
	s_add_u32 s90, s24, 0x100
	v_mov_b32_e32 v0, 0
	s_addc_u32 s91, s25, 0
	s_mov_b32 s92, -2
	v_mov_b32_e32 v1, v0
	v_mov_b32_e32 v2, v0
	v_mov_b32_e32 v3, v0
	v_mov_b32_e32 v4, v0
	v_mov_b32_e32 v5, v0
	v_mov_b32_e32 v6, v0
	v_mov_b32_e32 v7, v0
	s_nop 0
	v_mov_b32_e32 v8, v0
	v_mov_b32_e32 v9, v0
	v_mov_b32_e32 v10, v0
	v_mov_b32_e32 v11, v0
	v_mov_b32_e32 v12, v0
	v_mov_b32_e32 v13, v0
	v_mov_b32_e32 v14, v0
	v_mov_b32_e32 v15, v0
	v_mov_b32_e32 v16, v0
	v_mov_b32_e32 v17, v0
	v_mov_b32_e32 v18, v0
	v_mov_b32_e32 v19, v0
	v_mov_b32_e32 v20, v0
	v_mov_b32_e32 v21, v0
	v_mov_b32_e32 v22, v0
	v_mov_b32_e32 v23, v0
	v_mov_b32_e32 v24, v0
	v_mov_b32_e32 v25, v0
	v_mov_b32_e32 v26, v0
	v_mov_b32_e32 v27, v0
	v_mov_b32_e32 v28, v0
	v_mov_b32_e32 v29, v0
	v_mov_b32_e32 v30, v0
	v_mov_b32_e32 v31, v0
	s_cmp_eq_u32 s98, 1
	s_mov_b32 s98, 0
	s_cbranch_scc1 .Lzskip_1
	v_mov_b32_e32 v32, v0
	v_mov_b32_e32 v33, v0
	v_mov_b32_e32 v34, v0
	v_mov_b32_e32 v35, v0
	v_mov_b32_e32 v36, v0
	v_mov_b32_e32 v37, v0
	v_mov_b32_e32 v38, v0
	v_mov_b32_e32 v39, v0
	v_mov_b32_e32 v40, v0
	v_mov_b32_e32 v41, v0
	v_mov_b32_e32 v42, v0
	v_mov_b32_e32 v43, v0
	v_mov_b32_e32 v44, v0
	v_mov_b32_e32 v45, v0
	v_mov_b32_e32 v46, v0
	v_mov_b32_e32 v47, v0
	v_mov_b32_e32 v48, v0
	v_mov_b32_e32 v49, v0
	v_mov_b32_e32 v50, v0
	v_mov_b32_e32 v51, v0
	v_mov_b32_e32 v52, v0
	v_mov_b32_e32 v53, v0
	v_mov_b32_e32 v54, v0
	v_mov_b32_e32 v55, v0
	v_mov_b32_e32 v56, v0
	v_mov_b32_e32 v57, v0
	v_mov_b32_e32 v58, v0
	v_mov_b32_e32 v59, v0
	v_mov_b32_e32 v60, v0
	v_mov_b32_e32 v61, v0
	v_mov_b32_e32 v62, v0
	v_mov_b32_e32 v63, v0
	v_mov_b32_e32 v64, v0
	v_mov_b32_e32 v65, v0
	v_mov_b32_e32 v66, v0
	v_mov_b32_e32 v67, v0
	v_mov_b32_e32 v68, v0
	v_mov_b32_e32 v69, v0
	v_mov_b32_e32 v70, v0
	v_mov_b32_e32 v71, v0
	v_mov_b32_e32 v72, v0
	v_mov_b32_e32 v73, v0
	v_mov_b32_e32 v74, v0
	v_mov_b32_e32 v75, v0
	v_mov_b32_e32 v76, v0
	v_mov_b32_e32 v77, v0
	v_mov_b32_e32 v78, v0
	v_mov_b32_e32 v79, v0
	v_mov_b32_e32 v80, v0
	v_mov_b32_e32 v81, v0
	v_mov_b32_e32 v82, v0
	v_mov_b32_e32 v83, v0
	v_mov_b32_e32 v84, v0
	v_mov_b32_e32 v85, v0
	v_mov_b32_e32 v86, v0
	v_mov_b32_e32 v87, v0
	v_mov_b32_e32 v88, v0
	v_mov_b32_e32 v89, v0
	v_mov_b32_e32 v90, v0
	v_mov_b32_e32 v91, v0
	v_mov_b32_e32 v92, v0
	v_mov_b32_e32 v93, v0
	v_mov_b32_e32 v94, v0
	v_mov_b32_e32 v95, v0
	v_mov_b32_e32 v96, v0
	v_mov_b32_e32 v97, v0
	v_mov_b32_e32 v98, v0
	v_mov_b32_e32 v99, v0
	v_mov_b32_e32 v100, v0
	v_mov_b32_e32 v101, v0
	v_mov_b32_e32 v102, v0
	v_mov_b32_e32 v103, v0
	v_mov_b32_e32 v104, v0
	v_mov_b32_e32 v105, v0
	v_mov_b32_e32 v106, v0
	v_mov_b32_e32 v107, v0
	v_mov_b32_e32 v108, v0
	v_mov_b32_e32 v109, v0
	v_mov_b32_e32 v110, v0
	v_mov_b32_e32 v111, v0
	v_mov_b32_e32 v112, v0
	v_mov_b32_e32 v113, v0
	v_mov_b32_e32 v114, v0
	v_mov_b32_e32 v115, v0
	v_mov_b32_e32 v116, v0
	v_mov_b32_e32 v117, v0
	v_mov_b32_e32 v118, v0
	v_mov_b32_e32 v119, v0
	v_mov_b32_e32 v120, v0
	v_mov_b32_e32 v121, v0
	v_mov_b32_e32 v122, v0
	v_mov_b32_e32 v123, v0
	v_mov_b32_e32 v124, v0
	v_mov_b32_e32 v125, v0
	v_mov_b32_e32 v126, v0
	v_mov_b32_e32 v127, v0
.Lzskip_1:
.LBB0_199:
	ds_read_b128 v[144:147], v167
	ds_read_b128 v[148:151], v167 offset:1024
	ds_read_b128 v[152:155], v167 offset:2048
	ds_read_b128 v[156:159], v167 offset:3072
	ds_read_b128 v[160:163], v168
	ds_read_b128 v[172:175], v168 offset:1024
	ds_read_b128 v[176:179], v168 offset:2048
	ds_read_b128 v[180:183], v168 offset:3072
	s_add_u32 s24, s22, 0xfffc0080
	s_addc_u32 s25, s23, -1
	s_cmp_eq_u32 s92, 12
	s_cselect_b32 s27, s15, s25
	s_cselect_b32 s26, s88, s24
	s_cselect_b32 s25, s13, s91
	s_cselect_b32 s24, s89, s90
	v_lshl_add_u64 v[204:205], s[22:23], 0, v[136:137]
	s_add_i32 m0, s21, 0xc000
	ds_read_b128 v[184:187], v169
	ds_read_b128 v[188:191], v169 offset:1024
	ds_read_b128 v[192:195], v169 offset:2048
	ds_read_b128 v[196:199], v169 offset:3072
	ds_read_b128 v[200:203], v169 offset:4096
	ds_read_b128 v[208:211], v169 offset:5120
	ds_read_b128 v[212:215], v169 offset:6144
	ds_read_b128 v[216:219], v169 offset:7168
	global_load_lds_dwordx4 v[204:205], off
	v_lshl_add_u64 v[204:205], s[22:23], 0, v[138:139]
	s_add_i32 m0, s21, 0xe000
	s_nop 0
	global_load_lds_dwordx4 v[204:205], off
	s_waitcnt vmcnt(8)
	s_waitcnt lgkmcnt(0)
	s_setprio 1
	s_barrier
	v_mfma_f32_16x16x32_bf16 v[124:127], v[144:147], v[184:187], v[124:127]
	v_mfma_f32_16x16x32_bf16 v[120:123], v[152:155], v[184:187], v[120:123]
	v_mfma_f32_16x16x32_bf16 v[116:119], v[144:147], v[192:195], v[116:119]
	v_mfma_f32_16x16x32_bf16 v[112:115], v[152:155], v[192:195], v[112:115]
	v_mfma_f32_16x16x32_bf16 v[108:111], v[144:147], v[200:203], v[108:111]
	v_mfma_f32_16x16x32_bf16 v[88:91], v[152:155], v[200:203], v[88:91]
	v_mfma_f32_16x16x32_bf16 v[80:83], v[144:147], v[212:215], v[80:83]
	v_mfma_f32_16x16x32_bf16 v[72:75], v[152:155], v[212:215], v[72:75]
	v_mfma_f32_16x16x32_bf16 v[124:127], v[148:151], v[188:191], v[124:127]
	v_mfma_f32_16x16x32_bf16 v[120:123], v[156:159], v[188:191], v[120:123]
	v_mfma_f32_16x16x32_bf16 v[116:119], v[148:151], v[196:199], v[116:119]
	v_mfma_f32_16x16x32_bf16 v[112:115], v[156:159], v[196:199], v[112:115]
	v_mfma_f32_16x16x32_bf16 v[108:111], v[148:151], v[208:211], v[108:111]
	v_mfma_f32_16x16x32_bf16 v[88:91], v[156:159], v[208:211], v[88:91]
	v_mfma_f32_16x16x32_bf16 v[80:83], v[148:151], v[216:219], v[80:83]
	v_mfma_f32_16x16x32_bf16 v[72:75], v[156:159], v[216:219], v[72:75]
	s_setprio 0
	s_setprio 1
	v_mfma_f32_16x16x32_bf16 v[104:107], v[160:163], v[184:187], v[104:107]
	v_mfma_f32_16x16x32_bf16 v[100:103], v[176:179], v[184:187], v[100:103]
	v_mfma_f32_16x16x32_bf16 v[96:99], v[160:163], v[192:195], v[96:99]
	v_mfma_f32_16x16x32_bf16 v[92:95], v[176:179], v[192:195], v[92:95]
	v_mfma_f32_16x16x32_bf16 v[84:87], v[160:163], v[200:203], v[84:87]
	v_mfma_f32_16x16x32_bf16 v[76:79], v[176:179], v[200:203], v[76:79]
	v_mfma_f32_16x16x32_bf16 v[68:71], v[160:163], v[212:215], v[68:71]
	v_mfma_f32_16x16x32_bf16 v[64:67], v[176:179], v[212:215], v[64:67]
	v_mfma_f32_16x16x32_bf16 v[104:107], v[172:175], v[188:191], v[104:107]
	v_mfma_f32_16x16x32_bf16 v[100:103], v[180:183], v[188:191], v[100:103]
	v_mfma_f32_16x16x32_bf16 v[96:99], v[172:175], v[196:199], v[96:99]
	v_mfma_f32_16x16x32_bf16 v[92:95], v[180:183], v[196:199], v[92:95]
	v_mfma_f32_16x16x32_bf16 v[84:87], v[172:175], v[208:211], v[84:87]
	v_mfma_f32_16x16x32_bf16 v[76:79], v[180:183], v[208:211], v[76:79]
	v_mfma_f32_16x16x32_bf16 v[68:71], v[172:175], v[216:219], v[68:71]
	v_mfma_f32_16x16x32_bf16 v[64:67], v[180:183], v[216:219], v[64:67]
	s_barrier
	s_setprio 0
	s_add_i32 s93, s84, s35
	v_lshl_add_u64 v[204:205], s[24:25], 0, v[130:131]
	s_mov_b32 m0, s93
	ds_read_b128 v[184:187], v169 offset:16384
	ds_read_b128 v[188:191], v169 offset:17408
	ds_read_b128 v[192:195], v169 offset:18432
	ds_read_b128 v[196:199], v169 offset:19456
	ds_read_b128 v[200:203], v169 offset:20480
	ds_read_b128 v[208:211], v169 offset:21504
	ds_read_b128 v[212:215], v169 offset:22528
	ds_read_b128 v[216:219], v169 offset:23552
	global_load_lds_dwordx4 v[204:205], off
	s_add_i32 m0, s93, 0x2000
	s_add_u32 s94, s24, 0x40000
	v_lshl_add_u64 v[220:221], s[24:25], 0, v[134:135]
	s_addc_u32 s95, s25, 0
	s_add_i32 s93, s85, s35
	global_load_lds_dwordx4 v[220:221], off
	v_lshl_add_u64 v[222:223], s[94:95], 0, v[130:131]
	s_mov_b32 m0, s93
	v_lshl_add_u64 v[224:225], s[26:27], 0, v[132:133]
	global_load_lds_dwordx4 v[222:223], off
	v_lshl_add_u64 v[222:223], s[94:95], 0, v[134:135]
	s_add_i32 m0, s93, 0x2000
	s_nop 0
	global_load_lds_dwordx4 v[222:223], off
	v_lshl_add_u64 v[222:223], s[26:27], 0, v[128:129]
	s_mov_b32 m0, s21
	s_nop 0
	global_load_lds_dwordx4 v[222:223], off
	s_mov_b32 m0, s36
	s_nop 0
	global_load_lds_dwordx4 v[224:225], off
	s_waitcnt vmcnt(8)
	s_waitcnt lgkmcnt(0)
	s_setprio 1
	s_barrier
	v_mfma_f32_16x16x32_bf16 v[60:63], v[144:147], v[184:187], v[60:63]
	v_mfma_f32_16x16x32_bf16 v[56:59], v[152:155], v[184:187], v[56:59]
	v_mfma_f32_16x16x32_bf16 v[48:51], v[144:147], v[192:195], v[48:51]
	v_mfma_f32_16x16x32_bf16 v[40:43], v[152:155], v[192:195], v[40:43]
	v_mfma_f32_16x16x32_bf16 v[32:35], v[144:147], v[200:203], v[32:35]
	v_mfma_f32_16x16x32_bf16 v[24:27], v[152:155], v[200:203], v[24:27]
	v_mfma_f32_16x16x32_bf16 v[16:19], v[144:147], v[212:215], v[16:19]
	v_mfma_f32_16x16x32_bf16 v[8:11], v[152:155], v[212:215], v[8:11]
	v_mfma_f32_16x16x32_bf16 v[60:63], v[148:151], v[188:191], v[60:63]
	v_mfma_f32_16x16x32_bf16 v[56:59], v[156:159], v[188:191], v[56:59]
	v_mfma_f32_16x16x32_bf16 v[48:51], v[148:151], v[196:199], v[48:51]
	v_mfma_f32_16x16x32_bf16 v[40:43], v[156:159], v[196:199], v[40:43]
	v_mfma_f32_16x16x32_bf16 v[32:35], v[148:151], v[208:211], v[32:35]
	v_mfma_f32_16x16x32_bf16 v[24:27], v[156:159], v[208:211], v[24:27]
	v_mfma_f32_16x16x32_bf16 v[16:19], v[148:151], v[216:219], v[16:19]
	v_mfma_f32_16x16x32_bf16 v[8:11], v[156:159], v[216:219], v[8:11]
	s_setprio 0
	s_setprio 1
	v_mfma_f32_16x16x32_bf16 v[52:55], v[160:163], v[184:187], v[52:55]
	v_mfma_f32_16x16x32_bf16 v[44:47], v[176:179], v[184:187], v[44:47]
	v_mfma_f32_16x16x32_bf16 v[36:39], v[160:163], v[192:195], v[36:39]
	v_mfma_f32_16x16x32_bf16 v[28:31], v[176:179], v[192:195], v[28:31]
	v_mfma_f32_16x16x32_bf16 v[20:23], v[160:163], v[200:203], v[20:23]
	v_mfma_f32_16x16x32_bf16 v[12:15], v[176:179], v[200:203], v[12:15]
	v_mfma_f32_16x16x32_bf16 v[4:7], v[160:163], v[212:215], v[4:7]
	v_mfma_f32_16x16x32_bf16 v[0:3], v[176:179], v[212:215], v[0:3]
	v_mfma_f32_16x16x32_bf16 v[52:55], v[172:175], v[188:191], v[52:55]
	v_mfma_f32_16x16x32_bf16 v[44:47], v[180:183], v[188:191], v[44:47]
	v_mfma_f32_16x16x32_bf16 v[36:39], v[172:175], v[196:199], v[36:39]
	v_mfma_f32_16x16x32_bf16 v[28:31], v[180:183], v[196:199], v[28:31]
	v_mfma_f32_16x16x32_bf16 v[20:23], v[172:175], v[208:211], v[20:23]
	v_mfma_f32_16x16x32_bf16 v[12:15], v[180:183], v[208:211], v[12:15]
	v_mfma_f32_16x16x32_bf16 v[4:7], v[172:175], v[216:219], v[4:7]
	v_mfma_f32_16x16x32_bf16 v[0:3], v[180:183], v[216:219], v[0:3]
	s_barrier
	s_setprio 0
	s_add_i32 s93, 0, 0x18000
	s_add_i32 s94, 0, 0x1c000
	v_add_u32_e32 v156, s93, v165
	v_add_u32_e32 v171, s94, v165
	ds_read_b128 v[144:147], v156
	ds_read_b128 v[148:151], v156 offset:1024
	ds_read_b128 v[152:155], v156 offset:2048
	ds_read_b128 v[156:159], v156 offset:3072
	ds_read_b128 v[160:163], v171
	ds_read_b128 v[172:175], v171 offset:1024
	ds_read_b128 v[176:179], v171 offset:2048
	ds_read_b128 v[180:183], v171 offset:3072
	s_add_u32 s26, s26, 0x40000
	s_addc_u32 s27, s27, 0
	s_mov_b32 m0, s37
	v_lshl_add_u64 v[226:227], s[26:27], 0, v[128:129]
	ds_read_b128 v[184:187], v169 offset:32768
	ds_read_b128 v[188:191], v169 offset:33792
	ds_read_b128 v[192:195], v169 offset:34816
	ds_read_b128 v[196:199], v169 offset:35840
	ds_read_b128 v[200:203], v169 offset:36864
	ds_read_b128 v[208:211], v169 offset:37888
	ds_read_b128 v[212:215], v169 offset:38912
	ds_read_b128 v[216:219], v169 offset:39936
	global_load_lds_dwordx4 v[226:227], off
	v_lshl_add_u64 v[226:227], s[26:27], 0, v[132:133]
	s_mov_b32 m0, s39
	s_nop 0
	global_load_lds_dwordx4 v[226:227], off
	s_waitcnt vmcnt(8)
	s_waitcnt lgkmcnt(0)
	s_setprio 1
	s_barrier
	v_mfma_f32_16x16x32_bf16 v[124:127], v[144:147], v[184:187], v[124:127]
	v_mfma_f32_16x16x32_bf16 v[120:123], v[152:155], v[184:187], v[120:123]
	v_mfma_f32_16x16x32_bf16 v[116:119], v[144:147], v[192:195], v[116:119]
	v_mfma_f32_16x16x32_bf16 v[112:115], v[152:155], v[192:195], v[112:115]
	v_mfma_f32_16x16x32_bf16 v[108:111], v[144:147], v[200:203], v[108:111]
	v_mfma_f32_16x16x32_bf16 v[88:91], v[152:155], v[200:203], v[88:91]
	v_mfma_f32_16x16x32_bf16 v[80:83], v[144:147], v[212:215], v[80:83]
	v_mfma_f32_16x16x32_bf16 v[72:75], v[152:155], v[212:215], v[72:75]
	v_mfma_f32_16x16x32_bf16 v[124:127], v[148:151], v[188:191], v[124:127]
	v_mfma_f32_16x16x32_bf16 v[120:123], v[156:159], v[188:191], v[120:123]
	v_mfma_f32_16x16x32_bf16 v[116:119], v[148:151], v[196:199], v[116:119]
	v_mfma_f32_16x16x32_bf16 v[112:115], v[156:159], v[196:199], v[112:115]
	v_mfma_f32_16x16x32_bf16 v[108:111], v[148:151], v[208:211], v[108:111]
	v_mfma_f32_16x16x32_bf16 v[88:91], v[156:159], v[208:211], v[88:91]
	v_mfma_f32_16x16x32_bf16 v[80:83], v[148:151], v[216:219], v[80:83]
	v_mfma_f32_16x16x32_bf16 v[72:75], v[156:159], v[216:219], v[72:75]
	s_setprio 0
	s_setprio 1
	v_mfma_f32_16x16x32_bf16 v[104:107], v[160:163], v[184:187], v[104:107]
	v_mfma_f32_16x16x32_bf16 v[100:103], v[176:179], v[184:187], v[100:103]
	v_mfma_f32_16x16x32_bf16 v[96:99], v[160:163], v[192:195], v[96:99]
	v_mfma_f32_16x16x32_bf16 v[92:95], v[176:179], v[192:195], v[92:95]
	v_mfma_f32_16x16x32_bf16 v[84:87], v[160:163], v[200:203], v[84:87]
	v_mfma_f32_16x16x32_bf16 v[76:79], v[176:179], v[200:203], v[76:79]
	v_mfma_f32_16x16x32_bf16 v[68:71], v[160:163], v[212:215], v[68:71]
	v_mfma_f32_16x16x32_bf16 v[64:67], v[176:179], v[212:215], v[64:67]
	v_mfma_f32_16x16x32_bf16 v[104:107], v[172:175], v[188:191], v[104:107]
	v_mfma_f32_16x16x32_bf16 v[100:103], v[180:183], v[188:191], v[100:103]
	v_mfma_f32_16x16x32_bf16 v[96:99], v[172:175], v[196:199], v[96:99]
	v_mfma_f32_16x16x32_bf16 v[92:95], v[180:183], v[196:199], v[92:95]
	v_mfma_f32_16x16x32_bf16 v[84:87], v[172:175], v[208:211], v[84:87]
	v_mfma_f32_16x16x32_bf16 v[76:79], v[180:183], v[208:211], v[76:79]
	v_mfma_f32_16x16x32_bf16 v[68:71], v[172:175], v[216:219], v[68:71]
	v_mfma_f32_16x16x32_bf16 v[64:67], v[180:183], v[216:219], v[64:67]
	s_barrier
	s_setprio 0
	s_add_i32 s26, s93, s35
	v_lshl_add_u64 v[204:205], v[204:205], 0, s[8:9]
	s_mov_b32 m0, s26
	ds_read_b128 v[184:187], v169 offset:49152
	ds_read_b128 v[188:191], v169 offset:50176
	ds_read_b128 v[192:195], v169 offset:51200
	ds_read_b128 v[196:199], v169 offset:52224
	ds_read_b128 v[200:203], v169 offset:53248
	ds_read_b128 v[208:211], v169 offset:54272
	ds_read_b128 v[212:215], v169 offset:55296
	ds_read_b128 v[216:219], v169 offset:56320
	global_load_lds_dwordx4 v[204:205], off
	s_add_i32 m0, s26, 0x2000
	s_add_u32 s24, s24, 0x40080
	v_lshl_add_u64 v[204:205], v[220:221], 0, s[8:9]
	s_addc_u32 s25, s25, 0
	s_add_i32 s26, s94, s35
	global_load_lds_dwordx4 v[204:205], off
	v_lshl_add_u64 v[204:205], s[24:25], 0, v[130:131]
	s_mov_b32 m0, s26
	s_nop 0
	global_load_lds_dwordx4 v[204:205], off
	v_lshl_add_u64 v[204:205], s[24:25], 0, v[134:135]
	s_add_i32 m0, s26, 0x2000
	s_nop 0
	global_load_lds_dwordx4 v[204:205], off
	v_lshl_add_u64 v[204:205], v[222:223], 0, s[8:9]
	s_mov_b32 m0, s77
	s_nop 0
	global_load_lds_dwordx4 v[204:205], off
	v_lshl_add_u64 v[204:205], v[224:225], 0, s[8:9]
	s_mov_b32 m0, s78
	s_nop 0
	global_load_lds_dwordx4 v[204:205], off
	s_waitcnt vmcnt(8)
	s_waitcnt lgkmcnt(0)
	s_setprio 1
	s_barrier
	v_mfma_f32_16x16x32_bf16 v[60:63], v[144:147], v[184:187], v[60:63]
	v_mfma_f32_16x16x32_bf16 v[56:59], v[152:155], v[184:187], v[56:59]
	v_mfma_f32_16x16x32_bf16 v[48:51], v[144:147], v[192:195], v[48:51]
	v_mfma_f32_16x16x32_bf16 v[40:43], v[152:155], v[192:195], v[40:43]
	v_mfma_f32_16x16x32_bf16 v[32:35], v[144:147], v[200:203], v[32:35]
	v_mfma_f32_16x16x32_bf16 v[24:27], v[152:155], v[200:203], v[24:27]
	v_mfma_f32_16x16x32_bf16 v[16:19], v[144:147], v[212:215], v[16:19]
	v_mfma_f32_16x16x32_bf16 v[8:11], v[152:155], v[212:215], v[8:11]
	v_mfma_f32_16x16x32_bf16 v[60:63], v[148:151], v[188:191], v[60:63]
	v_mfma_f32_16x16x32_bf16 v[56:59], v[156:159], v[188:191], v[56:59]
	v_mfma_f32_16x16x32_bf16 v[48:51], v[148:151], v[196:199], v[48:51]
	v_mfma_f32_16x16x32_bf16 v[40:43], v[156:159], v[196:199], v[40:43]
	v_mfma_f32_16x16x32_bf16 v[32:35], v[148:151], v[208:211], v[32:35]
	v_mfma_f32_16x16x32_bf16 v[24:27], v[156:159], v[208:211], v[24:27]
	v_mfma_f32_16x16x32_bf16 v[16:19], v[148:151], v[216:219], v[16:19]
	v_mfma_f32_16x16x32_bf16 v[8:11], v[156:159], v[216:219], v[8:11]
	s_setprio 0
	s_setprio 1
	v_mfma_f32_16x16x32_bf16 v[52:55], v[160:163], v[184:187], v[52:55]
	v_mfma_f32_16x16x32_bf16 v[44:47], v[176:179], v[184:187], v[44:47]
	v_mfma_f32_16x16x32_bf16 v[36:39], v[160:163], v[192:195], v[36:39]
	v_mfma_f32_16x16x32_bf16 v[28:31], v[176:179], v[192:195], v[28:31]
	v_mfma_f32_16x16x32_bf16 v[20:23], v[160:163], v[200:203], v[20:23]
	v_mfma_f32_16x16x32_bf16 v[12:15], v[176:179], v[200:203], v[12:15]
	v_mfma_f32_16x16x32_bf16 v[4:7], v[160:163], v[212:215], v[4:7]
	v_mfma_f32_16x16x32_bf16 v[0:3], v[176:179], v[212:215], v[0:3]
	v_mfma_f32_16x16x32_bf16 v[52:55], v[172:175], v[188:191], v[52:55]
	v_mfma_f32_16x16x32_bf16 v[44:47], v[180:183], v[188:191], v[44:47]
	v_mfma_f32_16x16x32_bf16 v[36:39], v[172:175], v[196:199], v[36:39]
	v_mfma_f32_16x16x32_bf16 v[28:31], v[180:183], v[196:199], v[28:31]
	v_mfma_f32_16x16x32_bf16 v[20:23], v[172:175], v[208:211], v[20:23]
	v_mfma_f32_16x16x32_bf16 v[12:15], v[180:183], v[208:211], v[12:15]
	v_mfma_f32_16x16x32_bf16 v[4:7], v[172:175], v[216:219], v[4:7]
	v_mfma_f32_16x16x32_bf16 v[0:3], v[180:183], v[216:219], v[0:3]
	s_barrier
	s_setprio 0
	s_add_i32 s92, s92, 2
	s_add_u32 s22, s22, 0x100
	s_addc_u32 s23, s23, 0
	s_add_u32 s90, s90, 0x100
	s_addc_u32 s91, s91, 0
	s_cmp_gt_u32 s92, 13
	s_cbranch_scc0 .LBB0_199
	s_and_b64 vcc, exec, s[10:11]
	s_cbranch_vccz .LBB0_202
	s_barrier

.LBB0_512:
	s_lshl_b32 s1, s1, 5
	s_mov_b64 s[10:11], 0x80
	s_and_b32 s14, s1, 0x60
	s_add_i32 m0, s25, 0x18000
	v_lshl_add_u64 v[6:7], v[6:7], 0, s[10:11]
	s_lshl_b32 s12, s0, 13
	s_lshl_b32 s1, s14, 7
	s_mov_b32 s98, 1
	v_mov_b32_e32 v32, 0
	v_mov_b32_e32 v33, 0
	v_mov_b32_e32 v34, 0
	v_mov_b32_e32 v35, 0
	v_mov_b32_e32 v36, 0
	v_mov_b32_e32 v37, 0
	v_mov_b32_e32 v38, 0
	v_mov_b32_e32 v39, 0
	v_mov_b32_e32 v40, 0
	v_mov_b32_e32 v41, 0
	v_mov_b32_e32 v42, 0
	v_mov_b32_e32 v43, 0
	v_mov_b32_e32 v44, 0
	v_mov_b32_e32 v45, 0
	v_mov_b32_e32 v46, 0
	v_mov_b32_e32 v47, 0
	v_mov_b32_e32 v48, 0
	v_mov_b32_e32 v49, 0
	v_mov_b32_e32 v50, 0
	v_mov_b32_e32 v51, 0
	v_mov_b32_e32 v52, 0
	v_mov_b32_e32 v53, 0
	v_mov_b32_e32 v54, 0
	v_mov_b32_e32 v55, 0
	v_mov_b32_e32 v56, 0
	v_mov_b32_e32 v57, 0
	v_mov_b32_e32 v58, 0
	v_mov_b32_e32 v59, 0
	v_mov_b32_e32 v60, 0
	v_mov_b32_e32 v61, 0
	v_mov_b32_e32 v62, 0
	v_mov_b32_e32 v63, 0
	v_mov_b32_e32 v64, 0
	v_mov_b32_e32 v65, 0
	v_mov_b32_e32 v66, 0
	v_mov_b32_e32 v67, 0
	v_mov_b32_e32 v68, 0
	v_mov_b32_e32 v69, 0
	v_mov_b32_e32 v70, 0
	v_mov_b32_e32 v71, 0
	v_mov_b32_e32 v72, 0
	v_mov_b32_e32 v73, 0
	v_mov_b32_e32 v74, 0
	v_mov_b32_e32 v75, 0
	v_mov_b32_e32 v76, 0
	v_mov_b32_e32 v77, 0
	v_mov_b32_e32 v78, 0
	v_mov_b32_e32 v79, 0
	v_mov_b32_e32 v80, 0
	v_mov_b32_e32 v81, 0
	v_mov_b32_e32 v82, 0
	v_mov_b32_e32 v83, 0
	v_mov_b32_e32 v84, 0
	v_mov_b32_e32 v85, 0
	v_mov_b32_e32 v86, 0
	v_mov_b32_e32 v87, 0
	v_mov_b32_e32 v88, 0
	v_mov_b32_e32 v89, 0
	v_mov_b32_e32 v90, 0
	v_mov_b32_e32 v91, 0
	v_mov_b32_e32 v92, 0
	v_mov_b32_e32 v93, 0
	v_mov_b32_e32 v94, 0
	v_mov_b32_e32 v95, 0
	v_mov_b32_e32 v96, 0
	v_mov_b32_e32 v97, 0
	v_mov_b32_e32 v98, 0
	v_mov_b32_e32 v99, 0
	v_mov_b32_e32 v100, 0
	v_mov_b32_e32 v101, 0
	v_mov_b32_e32 v102, 0
	v_mov_b32_e32 v103, 0
	v_mov_b32_e32 v104, 0
	v_mov_b32_e32 v105, 0
	v_mov_b32_e32 v106, 0
	v_mov_b32_e32 v107, 0
	v_mov_b32_e32 v108, 0
	v_mov_b32_e32 v109, 0
	v_mov_b32_e32 v110, 0
	v_mov_b32_e32 v111, 0
	v_mov_b32_e32 v112, 0
	v_mov_b32_e32 v113, 0
	v_mov_b32_e32 v114, 0
	v_mov_b32_e32 v115, 0
	v_mov_b32_e32 v116, 0
	v_mov_b32_e32 v117, 0
	v_mov_b32_e32 v118, 0
	v_mov_b32_e32 v119, 0
	v_mov_b32_e32 v120, 0
	v_mov_b32_e32 v121, 0
	v_mov_b32_e32 v122, 0
	v_mov_b32_e32 v123, 0
	v_mov_b32_e32 v124, 0
	v_mov_b32_e32 v125, 0
	v_mov_b32_e32 v126, 0
	v_mov_b32_e32 v127, 0
	s_nop 0
	s_nop 0
	s_nop 0
	s_nop 0
	s_nop 0
	s_nop 0
	s_nop 0
	s_nop 0
	s_nop 0
	s_nop 0
	s_nop 0
	s_nop 0
	s_waitcnt vmcnt(2)
	s_barrier
	global_load_lds_dwordx4 v[6:7], off
	v_lshl_add_u64 v[4:5], v[4:5], 0, s[10:11]
	s_add_i32 m0, s25, 0x1a000
	s_add_i32 s86, s25, 0x8000
	s_add_i32 s87, s25, 0xa000
	global_load_lds_dwordx4 v[4:5], off
	v_lshl_add_u64 v[0:1], v[0:1], 0, s[10:11]
	s_mov_b32 m0, s86
	s_add_u32 s4, s28, 0x40080
	global_load_lds_dwordx4 v[0:1], off
	v_lshl_add_u64 v[0:1], v[2:3], 0, s[10:11]
	s_mov_b32 m0, s87
	s_addc_u32 s5, s29, 0
	global_load_lds_dwordx4 v[0:1], off
	s_add_i32 m0, s25, 0x1c000
	v_lshl_add_u64 v[0:1], s[4:5], 0, v[176:177]
	global_load_lds_dwordx4 v[0:1], off
	v_lshl_add_u64 v[0:1], s[4:5], 0, v[178:179]
	s_add_i32 m0, s25, 0x1e000
	s_mov_b64 s[4:5], 0x40080
	global_load_lds_dwordx4 v[0:1], off
	v_bfe_u32 v0, v8, 4, 2
	v_and_b32_e32 v1, 15, v8
	v_lshlrev_b32_e32 v2, 4, v0
	v_lshl_or_b32 v200, s0, 6, v1
	v_lshl_or_b32 v1, v1, 6, v2
	v_lshlrev_b32_e32 v2, 2, v8
	v_and_b32_e32 v2, 32, v2
	v_bitop3_b32 v201, v1, s1, v2 bitop3:0xde
	v_cmp_eq_u32_e64 s[0:1], 0, v0
	v_lshl_or_b32 v202, v0, 2, s14
	v_lshlrev_b32_e32 v0, 13, v9
	v_and_b32_e32 v0, 0x7fffc000, v0
	v_lshl_add_u32 v0, v10, 10, v0
	v_or_b32_e32 v0, v0, v11
	v_bitop3_b32 v3, v1, s12, v2 bitop3:0xde
	v_add_lshl_u32 v0, v0, v12, 1
	v_mov_b32_e32 v1, v177
	v_lshl_add_u64 v[180:181], v[0:1], 0, s[4:5]
	v_lshlrev_b32_e32 v0, 13, v13
	v_and_b32_e32 v0, 0x7fffc000, v0
	v_lshl_add_u32 v0, v14, 10, v0
	s_waitcnt vmcnt(6)
	s_cmpk_lt_u32 s3, 0x100
	v_or_b32_e32 v0, v0, v15
	s_cselect_b64 s[12:13], -1, 0
	v_add_lshl_u32 v0, v0, v16, 1
	s_add_i32 s90, 0, 0x10000
	s_add_i32 s91, 0, 0x14000
	s_ashr_i32 s88, s37, 31
	s_ashr_i32 s89, s36, 31
	v_lshl_add_u64 v[182:183], v[0:1], 0, s[4:5]
	v_mov_b64_e32 v[184:185], 0x100
	v_mov_b64_e32 v[186:187], 0xff
	v_add_u32_e32 v203, s90, v201
	v_add_u32_e32 v204, s91, v201
	v_add_u32_e32 v205, 0, v3
	v_mbcnt_hi_u32_b32 v208, -1, v207
	s_barrier
	s_branch .LBB0_515

.LBB0_521:
	s_ashr_i32 s17, s16, 31
	s_lshl_b64 s[18:19], s[16:17], 19
	s_add_u32 s18, s84, s18
	s_addc_u32 s19, s85, s19
	s_and_b64 s[20:21], s[4:5], exec
	s_cselect_b32 s3, s19, s27
	s_cselect_b32 s17, s18, s26
	s_ashr_i32 s15, s14, 31
	s_lshl_b64 s[20:21], s[14:15], 19
	s_add_u32 s20, s39, s20
	s_addc_u32 s21, s50, s21
	s_and_b64 s[30:31], s[4:5], exec
	s_cselect_b32 s15, s21, s29
	s_cselect_b32 s23, s20, s28
	s_add_u32 s92, s28, 0x100
	v_mov_b32_e32 v0, 0
	s_addc_u32 s93, s29, 0
	s_mov_b32 s94, -2
	s_waitcnt lgkmcnt(0)
	v_mov_b32_e32 v1, v0
	v_mov_b32_e32 v2, v0
	v_mov_b32_e32 v3, v0
	v_mov_b32_e32 v4, v0
	v_mov_b32_e32 v5, v0
	v_mov_b32_e32 v6, v0
	v_mov_b32_e32 v7, v0
	s_nop 0
	v_mov_b32_e32 v8, v0
	v_mov_b32_e32 v9, v0
	v_mov_b32_e32 v10, v0
	v_mov_b32_e32 v11, v0
	v_mov_b32_e32 v12, v0
	v_mov_b32_e32 v13, v0
	v_mov_b32_e32 v14, v0
	v_mov_b32_e32 v15, v0
	v_mov_b32_e32 v16, v0
	v_mov_b32_e32 v17, v0
	v_mov_b32_e32 v18, v0
	v_mov_b32_e32 v19, v0
	v_mov_b32_e32 v20, v0
	v_mov_b32_e32 v21, v0
	v_mov_b32_e32 v22, v0
	v_mov_b32_e32 v23, v0
	v_mov_b32_e32 v24, v0
	v_mov_b32_e32 v25, v0
	v_mov_b32_e32 v26, v0
	v_mov_b32_e32 v27, v0
	v_mov_b32_e32 v28, v0
	v_mov_b32_e32 v29, v0
	v_mov_b32_e32 v30, v0
	v_mov_b32_e32 v31, v0
	s_cmp_eq_u32 s98, 1
	s_mov_b32 s98, 0
	s_cbranch_scc1 .Lzskip_2
	v_mov_b32_e32 v32, v0
	v_mov_b32_e32 v33, v0
	v_mov_b32_e32 v34, v0
	v_mov_b32_e32 v35, v0
	v_mov_b32_e32 v36, v0
	v_mov_b32_e32 v37, v0
	v_mov_b32_e32 v38, v0
	v_mov_b32_e32 v39, v0
	v_mov_b32_e32 v40, v0
	v_mov_b32_e32 v41, v0
	v_mov_b32_e32 v42, v0
	v_mov_b32_e32 v43, v0
	v_mov_b32_e32 v44, v0
	v_mov_b32_e32 v45, v0
	v_mov_b32_e32 v46, v0
	v_mov_b32_e32 v47, v0
	v_mov_b32_e32 v48, v0
	v_mov_b32_e32 v49, v0
	v_mov_b32_e32 v50, v0
	v_mov_b32_e32 v51, v0
	v_mov_b32_e32 v52, v0
	v_mov_b32_e32 v53, v0
	v_mov_b32_e32 v54, v0
	v_mov_b32_e32 v55, v0
	v_mov_b32_e32 v56, v0
	v_mov_b32_e32 v57, v0
	v_mov_b32_e32 v58, v0
	v_mov_b32_e32 v59, v0
	v_mov_b32_e32 v60, v0
	v_mov_b32_e32 v61, v0
	v_mov_b32_e32 v62, v0
	v_mov_b32_e32 v63, v0
	v_mov_b32_e32 v64, v0
	v_mov_b32_e32 v65, v0
	v_mov_b32_e32 v66, v0
	v_mov_b32_e32 v67, v0
	v_mov_b32_e32 v68, v0
	v_mov_b32_e32 v69, v0
	v_mov_b32_e32 v70, v0
	v_mov_b32_e32 v71, v0
	v_mov_b32_e32 v72, v0
	v_mov_b32_e32 v73, v0
	v_mov_b32_e32 v74, v0
	v_mov_b32_e32 v75, v0
	v_mov_b32_e32 v76, v0
	v_mov_b32_e32 v77, v0
	v_mov_b32_e32 v78, v0
	v_mov_b32_e32 v79, v0
	v_mov_b32_e32 v80, v0
	v_mov_b32_e32 v81, v0
	v_mov_b32_e32 v82, v0
	v_mov_b32_e32 v83, v0
	v_mov_b32_e32 v84, v0
	v_mov_b32_e32 v85, v0
	v_mov_b32_e32 v86, v0
	v_mov_b32_e32 v87, v0
	v_mov_b32_e32 v88, v0
	v_mov_b32_e32 v89, v0
	v_mov_b32_e32 v90, v0
	v_mov_b32_e32 v91, v0
	v_mov_b32_e32 v92, v0
	v_mov_b32_e32 v93, v0
	v_mov_b32_e32 v94, v0
	v_mov_b32_e32 v95, v0
	v_mov_b32_e32 v96, v0
	v_mov_b32_e32 v97, v0
	v_mov_b32_e32 v98, v0
	v_mov_b32_e32 v99, v0
	v_mov_b32_e32 v100, v0
	v_mov_b32_e32 v101, v0
	v_mov_b32_e32 v102, v0
	v_mov_b32_e32 v103, v0
	v_mov_b32_e32 v104, v0
	v_mov_b32_e32 v105, v0
	v_mov_b32_e32 v106, v0
	v_mov_b32_e32 v107, v0
	v_mov_b32_e32 v108, v0
	v_mov_b32_e32 v109, v0
	v_mov_b32_e32 v110, v0
	v_mov_b32_e32 v111, v0
	v_mov_b32_e32 v112, v0
	v_mov_b32_e32 v113, v0
	v_mov_b32_e32 v114, v0
	v_mov_b32_e32 v115, v0
	v_mov_b32_e32 v116, v0
	v_mov_b32_e32 v117, v0
	v_mov_b32_e32 v118, v0
	v_mov_b32_e32 v119, v0
	v_mov_b32_e32 v120, v0
	v_mov_b32_e32 v121, v0
	v_mov_b32_e32 v122, v0
	v_mov_b32_e32 v123, v0
	v_mov_b32_e32 v124, v0
	v_mov_b32_e32 v125, v0
	v_mov_b32_e32 v126, v0
	v_mov_b32_e32 v127, v0
.Lzskip_2:
.LBB0_522:
	ds_read_b128 v[128:131], v203
	ds_read_b128 v[132:135], v203 offset:1024
	ds_read_b128 v[136:139], v203 offset:2048
	ds_read_b128 v[140:143], v203 offset:3072
	ds_read_b128 v[144:147], v204
	ds_read_b128 v[148:151], v204 offset:1024
	ds_read_b128 v[152:155], v204 offset:2048
	ds_read_b128 v[156:159], v204 offset:3072
	s_add_u32 s28, s26, 0x100
	s_addc_u32 s29, s27, 0
	s_cmp_eq_u32 s94, 12
	s_cselect_b32 s35, s3, s29
	s_cselect_b32 s34, s17, s28
	s_cselect_b32 s31, s15, s93
	s_cselect_b32 s30, s23, s92
	v_lshl_add_u64 v[214:215], s[26:27], 0, v[180:181]
	s_add_i32 m0, s25, 0xc000
	ds_read_b128 v[160:163], v205
	ds_read_b128 v[164:167], v205 offset:1024
	ds_read_b128 v[168:171], v205 offset:2048
	ds_read_b128 v[172:175], v205 offset:3072
	ds_read_b128 v[188:191], v205 offset:4096
	ds_read_b128 v[192:195], v205 offset:5120
	ds_read_b128 v[196:199], v205 offset:6144
	ds_read_b128 v[210:213], v205 offset:7168
	global_load_lds_dwordx4 v[214:215], off
	v_lshl_add_u64 v[214:215], s[26:27], 0, v[182:183]
	s_add_i32 m0, s25, 0xe000
	s_nop 0
	global_load_lds_dwordx4 v[214:215], off
	s_waitcnt vmcnt(8)
	s_waitcnt lgkmcnt(0)
	s_setprio 1
	s_barrier
	v_mfma_f32_16x16x32_bf16 v[124:127], v[128:131], v[160:163], v[124:127]
	v_mfma_f32_16x16x32_bf16 v[120:123], v[136:139], v[160:163], v[120:123]
	v_mfma_f32_16x16x32_bf16 v[108:111], v[128:131], v[168:171], v[108:111]
	v_mfma_f32_16x16x32_bf16 v[104:107], v[136:139], v[168:171], v[104:107]
	v_mfma_f32_16x16x32_bf16 v[92:95], v[128:131], v[188:191], v[92:95]
	v_mfma_f32_16x16x32_bf16 v[88:91], v[136:139], v[188:191], v[88:91]
	v_mfma_f32_16x16x32_bf16 v[76:79], v[128:131], v[196:199], v[76:79]
	v_mfma_f32_16x16x32_bf16 v[72:75], v[136:139], v[196:199], v[72:75]
	v_mfma_f32_16x16x32_bf16 v[124:127], v[132:135], v[164:167], v[124:127]
	v_mfma_f32_16x16x32_bf16 v[120:123], v[140:143], v[164:167], v[120:123]
	v_mfma_f32_16x16x32_bf16 v[108:111], v[132:135], v[172:175], v[108:111]
	v_mfma_f32_16x16x32_bf16 v[104:107], v[140:143], v[172:175], v[104:107]
	v_mfma_f32_16x16x32_bf16 v[92:95], v[132:135], v[192:195], v[92:95]
	v_mfma_f32_16x16x32_bf16 v[88:91], v[140:143], v[192:195], v[88:91]
	v_mfma_f32_16x16x32_bf16 v[76:79], v[132:135], v[210:213], v[76:79]
	v_mfma_f32_16x16x32_bf16 v[72:75], v[140:143], v[210:213], v[72:75]
	s_setprio 0
	s_setprio 1
	v_mfma_f32_16x16x32_bf16 v[116:119], v[144:147], v[160:163], v[116:119]
	v_mfma_f32_16x16x32_bf16 v[112:115], v[152:155], v[160:163], v[112:115]
	v_mfma_f32_16x16x32_bf16 v[100:103], v[144:147], v[168:171], v[100:103]
	v_mfma_f32_16x16x32_bf16 v[96:99], v[152:155], v[168:171], v[96:99]
	v_mfma_f32_16x16x32_bf16 v[84:87], v[144:147], v[188:191], v[84:87]
	v_mfma_f32_16x16x32_bf16 v[80:83], v[152:155], v[188:191], v[80:83]
	v_mfma_f32_16x16x32_bf16 v[68:71], v[144:147], v[196:199], v[68:71]
	v_mfma_f32_16x16x32_bf16 v[64:67], v[152:155], v[196:199], v[64:67]
	v_mfma_f32_16x16x32_bf16 v[116:119], v[148:151], v[164:167], v[116:119]
	v_mfma_f32_16x16x32_bf16 v[112:115], v[156:159], v[164:167], v[112:115]
	v_mfma_f32_16x16x32_bf16 v[100:103], v[148:151], v[172:175], v[100:103]
	v_mfma_f32_16x16x32_bf16 v[96:99], v[156:159], v[172:175], v[96:99]
	v_mfma_f32_16x16x32_bf16 v[84:87], v[148:151], v[192:195], v[84:87]
	v_mfma_f32_16x16x32_bf16 v[80:83], v[156:159], v[192:195], v[80:83]
	v_mfma_f32_16x16x32_bf16 v[68:71], v[148:151], v[210:213], v[68:71]
	v_mfma_f32_16x16x32_bf16 v[64:67], v[156:159], v[210:213], v[64:67]
	s_barrier
	s_setprio 0
	s_add_i32 s26, s90, s51
	v_lshl_add_u64 v[214:215], s[30:31], 0, v[176:177]
	s_mov_b32 m0, s26
	ds_read_b128 v[160:163], v205 offset:16384
	ds_read_b128 v[164:167], v205 offset:17408
	ds_read_b128 v[168:171], v205 offset:18432
	ds_read_b128 v[172:175], v205 offset:19456
	ds_read_b128 v[188:191], v205 offset:20480
	ds_read_b128 v[192:195], v205 offset:21504
	ds_read_b128 v[196:199], v205 offset:22528
	ds_read_b128 v[210:213], v205 offset:23552
	global_load_lds_dwordx4 v[214:215], off
	s_add_i32 m0, s26, 0x2000
	s_add_u32 s26, s30, 0x40000
	v_lshl_add_u64 v[216:217], s[30:31], 0, v[178:179]
	s_addc_u32 s27, s31, 0
	s_add_i32 s95, s91, s51
	global_load_lds_dwordx4 v[216:217], off
	v_lshl_add_u64 v[218:219], s[26:27], 0, v[176:177]
	s_mov_b32 m0, s95
	v_lshl_add_u64 v[220:221], s[34:35], 0, v[178:179]
	global_load_lds_dwordx4 v[218:219], off
	v_lshl_add_u64 v[218:219], s[26:27], 0, v[178:179]
	s_add_i32 m0, s95, 0x2000
	s_nop 0
	global_load_lds_dwordx4 v[218:219], off
	v_lshl_add_u64 v[218:219], s[34:35], 0, v[176:177]
	s_mov_b32 m0, s25
	s_nop 0
	global_load_lds_dwordx4 v[218:219], off
	s_mov_b32 m0, s76
	s_nop 0
	global_load_lds_dwordx4 v[220:221], off
	s_waitcnt vmcnt(8)
	s_waitcnt lgkmcnt(0)
	s_setprio 1
	s_barrier
	v_mfma_f32_16x16x32_bf16 v[60:63], v[128:131], v[160:163], v[60:63]
	v_mfma_f32_16x16x32_bf16 v[56:59], v[136:139], v[160:163], v[56:59]
	v_mfma_f32_16x16x32_bf16 v[44:47], v[128:131], v[168:171], v[44:47]
	v_mfma_f32_16x16x32_bf16 v[40:43], v[136:139], v[168:171], v[40:43]
	v_mfma_f32_16x16x32_bf16 v[28:31], v[128:131], v[188:191], v[28:31]
	v_mfma_f32_16x16x32_bf16 v[24:27], v[136:139], v[188:191], v[24:27]
	v_mfma_f32_16x16x32_bf16 v[12:15], v[128:131], v[196:199], v[12:15]
	v_mfma_f32_16x16x32_bf16 v[8:11], v[136:139], v[196:199], v[8:11]
	v_mfma_f32_16x16x32_bf16 v[60:63], v[132:135], v[164:167], v[60:63]
	v_mfma_f32_16x16x32_bf16 v[56:59], v[140:143], v[164:167], v[56:59]
	v_mfma_f32_16x16x32_bf16 v[44:47], v[132:135], v[172:175], v[44:47]
	v_mfma_f32_16x16x32_bf16 v[40:43], v[140:143], v[172:175], v[40:43]
	v_mfma_f32_16x16x32_bf16 v[28:31], v[132:135], v[192:195], v[28:31]
	v_mfma_f32_16x16x32_bf16 v[24:27], v[140:143], v[192:195], v[24:27]
	v_mfma_f32_16x16x32_bf16 v[12:15], v[132:135], v[210:213], v[12:15]
	v_mfma_f32_16x16x32_bf16 v[8:11], v[140:143], v[210:213], v[8:11]
	s_setprio 0
	s_setprio 1
	v_mfma_f32_16x16x32_bf16 v[52:55], v[144:147], v[160:163], v[52:55]
	v_mfma_f32_16x16x32_bf16 v[48:51], v[152:155], v[160:163], v[48:51]
	v_mfma_f32_16x16x32_bf16 v[36:39], v[144:147], v[168:171], v[36:39]
	v_mfma_f32_16x16x32_bf16 v[32:35], v[152:155], v[168:171], v[32:35]
	v_mfma_f32_16x16x32_bf16 v[20:23], v[144:147], v[188:191], v[20:23]
	v_mfma_f32_16x16x32_bf16 v[16:19], v[152:155], v[188:191], v[16:19]
	v_mfma_f32_16x16x32_bf16 v[4:7], v[144:147], v[196:199], v[4:7]
	v_mfma_f32_16x16x32_bf16 v[0:3], v[152:155], v[196:199], v[0:3]
	v_mfma_f32_16x16x32_bf16 v[52:55], v[148:151], v[164:167], v[52:55]
	v_mfma_f32_16x16x32_bf16 v[48:51], v[156:159], v[164:167], v[48:51]
	v_mfma_f32_16x16x32_bf16 v[36:39], v[148:151], v[172:175], v[36:39]
	v_mfma_f32_16x16x32_bf16 v[32:35], v[156:159], v[172:175], v[32:35]
	v_mfma_f32_16x16x32_bf16 v[20:23], v[148:151], v[192:195], v[20:23]
	v_mfma_f32_16x16x32_bf16 v[16:19], v[156:159], v[192:195], v[16:19]
	v_mfma_f32_16x16x32_bf16 v[4:7], v[148:151], v[210:213], v[4:7]
	v_mfma_f32_16x16x32_bf16 v[0:3], v[156:159], v[210:213], v[0:3]
	s_barrier
	s_setprio 0
	s_add_i32 s95, 0, 0x18000
	s_add_i32 s96, 0, 0x1c000
	v_add_u32_e32 v140, s95, v201
	v_add_u32_e32 v156, s96, v201
	ds_read_b128 v[128:131], v140
	ds_read_b128 v[132:135], v140 offset:1024
	ds_read_b128 v[136:139], v140 offset:2048
	ds_read_b128 v[140:143], v140 offset:3072
	ds_read_b128 v[144:147], v156
	ds_read_b128 v[148:151], v156 offset:1024
	ds_read_b128 v[152:155], v156 offset:2048
	ds_read_b128 v[156:159], v156 offset:3072
	s_add_u32 s26, s34, 0x40000
	s_addc_u32 s27, s35, 0
	s_mov_b32 m0, s77
	v_lshl_add_u64 v[222:223], s[26:27], 0, v[176:177]
	ds_read_b128 v[160:163], v205 offset:32768
	ds_read_b128 v[164:167], v205 offset:33792
	ds_read_b128 v[168:171], v205 offset:34816
	ds_read_b128 v[172:175], v205 offset:35840
	ds_read_b128 v[188:191], v205 offset:36864
	ds_read_b128 v[192:195], v205 offset:37888
	ds_read_b128 v[196:199], v205 offset:38912
	ds_read_b128 v[210:213], v205 offset:39936
	global_load_lds_dwordx4 v[222:223], off
	v_lshl_add_u64 v[222:223], s[26:27], 0, v[178:179]
	s_mov_b32 m0, s78
	s_nop 0
	global_load_lds_dwordx4 v[222:223], off
	s_waitcnt vmcnt(8)
	s_waitcnt lgkmcnt(0)
	s_setprio 1
	s_barrier
	v_mfma_f32_16x16x32_bf16 v[124:127], v[128:131], v[160:163], v[124:127]
	v_mfma_f32_16x16x32_bf16 v[120:123], v[136:139], v[160:163], v[120:123]
	v_mfma_f32_16x16x32_bf16 v[108:111], v[128:131], v[168:171], v[108:111]
	v_mfma_f32_16x16x32_bf16 v[104:107], v[136:139], v[168:171], v[104:107]
	v_mfma_f32_16x16x32_bf16 v[92:95], v[128:131], v[188:191], v[92:95]
	v_mfma_f32_16x16x32_bf16 v[88:91], v[136:139], v[188:191], v[88:91]
	v_mfma_f32_16x16x32_bf16 v[76:79], v[128:131], v[196:199], v[76:79]
	v_mfma_f32_16x16x32_bf16 v[72:75], v[136:139], v[196:199], v[72:75]
	v_mfma_f32_16x16x32_bf16 v[124:127], v[132:135], v[164:167], v[124:127]
	v_mfma_f32_16x16x32_bf16 v[120:123], v[140:143], v[164:167], v[120:123]
	v_mfma_f32_16x16x32_bf16 v[108:111], v[132:135], v[172:175], v[108:111]
	v_mfma_f32_16x16x32_bf16 v[104:107], v[140:143], v[172:175], v[104:107]
	v_mfma_f32_16x16x32_bf16 v[92:95], v[132:135], v[192:195], v[92:95]
	v_mfma_f32_16x16x32_bf16 v[88:91], v[140:143], v[192:195], v[88:91]
	v_mfma_f32_16x16x32_bf16 v[76:79], v[132:135], v[210:213], v[76:79]
	v_mfma_f32_16x16x32_bf16 v[72:75], v[140:143], v[210:213], v[72:75]
	s_setprio 0
	s_setprio 1
	v_mfma_f32_16x16x32_bf16 v[116:119], v[144:147], v[160:163], v[116:119]
	v_mfma_f32_16x16x32_bf16 v[112:115], v[152:155], v[160:163], v[112:115]
	v_mfma_f32_16x16x32_bf16 v[100:103], v[144:147], v[168:171], v[100:103]
	v_mfma_f32_16x16x32_bf16 v[96:99], v[152:155], v[168:171], v[96:99]
	v_mfma_f32_16x16x32_bf16 v[84:87], v[144:147], v[188:191], v[84:87]
	v_mfma_f32_16x16x32_bf16 v[80:83], v[152:155], v[188:191], v[80:83]
	v_mfma_f32_16x16x32_bf16 v[68:71], v[144:147], v[196:199], v[68:71]
	v_mfma_f32_16x16x32_bf16 v[64:67], v[152:155], v[196:199], v[64:67]
	v_mfma_f32_16x16x32_bf16 v[116:119], v[148:151], v[164:167], v[116:119]
	v_mfma_f32_16x16x32_bf16 v[112:115], v[156:159], v[164:167], v[112:115]
	v_mfma_f32_16x16x32_bf16 v[100:103], v[148:151], v[172:175], v[100:103]
	v_mfma_f32_16x16x32_bf16 v[96:99], v[156:159], v[172:175], v[96:99]
	v_mfma_f32_16x16x32_bf16 v[84:87], v[148:151], v[192:195], v[84:87]
	v_mfma_f32_16x16x32_bf16 v[80:83], v[156:159], v[192:195], v[80:83]
	v_mfma_f32_16x16x32_bf16 v[68:71], v[148:151], v[210:213], v[68:71]
	v_mfma_f32_16x16x32_bf16 v[64:67], v[156:159], v[210:213], v[64:67]
	s_barrier
	s_setprio 0
	s_add_i32 s26, s95, s51
	v_lshl_add_u64 v[214:215], v[214:215], 0, s[10:11]
	s_mov_b32 m0, s26
	ds_read_b128 v[160:163], v205 offset:49152
	ds_read_b128 v[164:167], v205 offset:50176
	ds_read_b128 v[168:171], v205 offset:51200
	ds_read_b128 v[172:175], v205 offset:52224
	ds_read_b128 v[188:191], v205 offset:53248
	ds_read_b128 v[192:195], v205 offset:54272
	ds_read_b128 v[196:199], v205 offset:55296
	ds_read_b128 v[210:213], v205 offset:56320
	global_load_lds_dwordx4 v[214:215], off
	s_add_i32 m0, s26, 0x2000
	s_add_u32 s26, s30, 0x40080
	v_lshl_add_u64 v[214:215], v[216:217], 0, s[10:11]
	s_addc_u32 s27, s31, 0
	s_add_i32 s30, s96, s51
	global_load_lds_dwordx4 v[214:215], off
	v_lshl_add_u64 v[214:215], s[26:27], 0, v[176:177]
	s_mov_b32 m0, s30
	s_nop 0
	global_load_lds_dwordx4 v[214:215], off
	v_lshl_add_u64 v[214:215], s[26:27], 0, v[178:179]
	s_add_i32 m0, s30, 0x2000
	s_nop 0
	global_load_lds_dwordx4 v[214:215], off
	v_lshl_add_u64 v[214:215], v[218:219], 0, s[10:11]
	s_mov_b32 m0, s86
	s_nop 0
	global_load_lds_dwordx4 v[214:215], off
	v_lshl_add_u64 v[214:215], v[220:221], 0, s[10:11]
	s_mov_b32 m0, s87
	s_nop 0
	global_load_lds_dwordx4 v[214:215], off
	s_waitcnt vmcnt(8)
	s_waitcnt lgkmcnt(0)
	s_setprio 1
	s_barrier
	v_mfma_f32_16x16x32_bf16 v[60:63], v[128:131], v[160:163], v[60:63]
	v_mfma_f32_16x16x32_bf16 v[56:59], v[136:139], v[160:163], v[56:59]
	v_mfma_f32_16x16x32_bf16 v[44:47], v[128:131], v[168:171], v[44:47]
	v_mfma_f32_16x16x32_bf16 v[40:43], v[136:139], v[168:171], v[40:43]
	v_mfma_f32_16x16x32_bf16 v[28:31], v[128:131], v[188:191], v[28:31]
	v_mfma_f32_16x16x32_bf16 v[24:27], v[136:139], v[188:191], v[24:27]
	v_mfma_f32_16x16x32_bf16 v[12:15], v[128:131], v[196:199], v[12:15]
	v_mfma_f32_16x16x32_bf16 v[8:11], v[136:139], v[196:199], v[8:11]
	v_mfma_f32_16x16x32_bf16 v[60:63], v[132:135], v[164:167], v[60:63]
	v_mfma_f32_16x16x32_bf16 v[56:59], v[140:143], v[164:167], v[56:59]
	v_mfma_f32_16x16x32_bf16 v[44:47], v[132:135], v[172:175], v[44:47]
	v_mfma_f32_16x16x32_bf16 v[40:43], v[140:143], v[172:175], v[40:43]
	v_mfma_f32_16x16x32_bf16 v[28:31], v[132:135], v[192:195], v[28:31]
	v_mfma_f32_16x16x32_bf16 v[24:27], v[140:143], v[192:195], v[24:27]
	v_mfma_f32_16x16x32_bf16 v[12:15], v[132:135], v[210:213], v[12:15]
	v_mfma_f32_16x16x32_bf16 v[8:11], v[140:143], v[210:213], v[8:11]
	s_setprio 0
	s_setprio 1
	v_mfma_f32_16x16x32_bf16 v[52:55], v[144:147], v[160:163], v[52:55]
	v_mfma_f32_16x16x32_bf16 v[48:51], v[152:155], v[160:163], v[48:51]
	v_mfma_f32_16x16x32_bf16 v[36:39], v[144:147], v[168:171], v[36:39]
	v_mfma_f32_16x16x32_bf16 v[32:35], v[152:155], v[168:171], v[32:35]
	v_mfma_f32_16x16x32_bf16 v[20:23], v[144:147], v[188:191], v[20:23]
	v_mfma_f32_16x16x32_bf16 v[16:19], v[152:155], v[188:191], v[16:19]
	v_mfma_f32_16x16x32_bf16 v[4:7], v[144:147], v[196:199], v[4:7]
	v_mfma_f32_16x16x32_bf16 v[0:3], v[152:155], v[196:199], v[0:3]
	v_mfma_f32_16x16x32_bf16 v[52:55], v[148:151], v[164:167], v[52:55]
	v_mfma_f32_16x16x32_bf16 v[48:51], v[156:159], v[164:167], v[48:51]
	v_mfma_f32_16x16x32_bf16 v[36:39], v[148:151], v[172:175], v[36:39]
	v_mfma_f32_16x16x32_bf16 v[32:35], v[156:159], v[172:175], v[32:35]
	v_mfma_f32_16x16x32_bf16 v[20:23], v[148:151], v[192:195], v[20:23]
	v_mfma_f32_16x16x32_bf16 v[16:19], v[156:159], v[192:195], v[16:19]
	v_mfma_f32_16x16x32_bf16 v[4:7], v[148:151], v[210:213], v[4:7]
	v_mfma_f32_16x16x32_bf16 v[0:3], v[156:159], v[210:213], v[0:3]
	s_barrier
	s_setprio 0
	s_add_i32 s94, s94, 2
	s_add_u32 s92, s92, 0x100
	s_addc_u32 s93, s93, 0
	s_cmp_gt_u32 s94, 13
	s_mov_b64 s[26:27], s[28:29]
	s_cbranch_scc0 .LBB0_522
	s_and_b64 vcc, exec, s[12:13]
	s_cbranch_vccz .LBB0_525
	s_barrier

.LBB0_684:
	s_lshl_b32 s3, s3, 5
	s_mov_b64 s[8:9], 0x80
	s_and_b32 s14, s3, 0x60
	s_add_i32 m0, s23, 0x18000
	v_lshl_add_u64 v[6:7], v[6:7], 0, s[8:9]
	s_lshl_b32 s11, s1, 13
	s_lshl_b32 s15, s14, 7
	s_mov_b32 s98, 1
	v_mov_b32_e32 v32, 0
	v_mov_b32_e32 v33, 0
	v_mov_b32_e32 v34, 0
	v_mov_b32_e32 v35, 0
	v_mov_b32_e32 v36, 0
	v_mov_b32_e32 v37, 0
	v_mov_b32_e32 v38, 0
	v_mov_b32_e32 v39, 0
	v_mov_b32_e32 v40, 0
	v_mov_b32_e32 v41, 0
	v_mov_b32_e32 v42, 0
	v_mov_b32_e32 v43, 0
	v_mov_b32_e32 v44, 0
	v_mov_b32_e32 v45, 0
	v_mov_b32_e32 v46, 0
	v_mov_b32_e32 v47, 0
	v_mov_b32_e32 v48, 0
	v_mov_b32_e32 v49, 0
	v_mov_b32_e32 v50, 0
	v_mov_b32_e32 v51, 0
	v_mov_b32_e32 v52, 0
	v_mov_b32_e32 v53, 0
	v_mov_b32_e32 v54, 0
	v_mov_b32_e32 v55, 0
	v_mov_b32_e32 v56, 0
	v_mov_b32_e32 v57, 0
	v_mov_b32_e32 v58, 0
	v_mov_b32_e32 v59, 0
	v_mov_b32_e32 v60, 0
	v_mov_b32_e32 v61, 0
	v_mov_b32_e32 v62, 0
	v_mov_b32_e32 v63, 0
	v_mov_b32_e32 v64, 0
	v_mov_b32_e32 v65, 0
	v_mov_b32_e32 v66, 0
	v_mov_b32_e32 v67, 0
	v_mov_b32_e32 v68, 0
	v_mov_b32_e32 v69, 0
	v_mov_b32_e32 v70, 0
	v_mov_b32_e32 v71, 0
	v_mov_b32_e32 v72, 0
	v_mov_b32_e32 v73, 0
	v_mov_b32_e32 v74, 0
	v_mov_b32_e32 v75, 0
	v_mov_b32_e32 v76, 0
	v_mov_b32_e32 v77, 0
	v_mov_b32_e32 v78, 0
	v_mov_b32_e32 v79, 0
	v_mov_b32_e32 v80, 0
	v_mov_b32_e32 v81, 0
	v_mov_b32_e32 v82, 0
	v_mov_b32_e32 v83, 0
	v_mov_b32_e32 v84, 0
	v_mov_b32_e32 v85, 0
	v_mov_b32_e32 v86, 0
	v_mov_b32_e32 v87, 0
	v_mov_b32_e32 v88, 0
	v_mov_b32_e32 v89, 0
	v_mov_b32_e32 v90, 0
	v_mov_b32_e32 v91, 0
	v_mov_b32_e32 v92, 0
	v_mov_b32_e32 v93, 0
	v_mov_b32_e32 v94, 0
	v_mov_b32_e32 v95, 0
	v_mov_b32_e32 v96, 0
	v_mov_b32_e32 v97, 0
	v_mov_b32_e32 v98, 0
	v_mov_b32_e32 v99, 0
	v_mov_b32_e32 v100, 0
	v_mov_b32_e32 v101, 0
	v_mov_b32_e32 v102, 0
	v_mov_b32_e32 v103, 0
	v_mov_b32_e32 v104, 0
	v_mov_b32_e32 v105, 0
	v_mov_b32_e32 v106, 0
	v_mov_b32_e32 v107, 0
	v_mov_b32_e32 v108, 0
	v_mov_b32_e32 v109, 0
	v_mov_b32_e32 v110, 0
	v_mov_b32_e32 v111, 0
	v_mov_b32_e32 v112, 0
	v_mov_b32_e32 v113, 0
	v_mov_b32_e32 v114, 0
	v_mov_b32_e32 v115, 0
	v_mov_b32_e32 v116, 0
	v_mov_b32_e32 v117, 0
	v_mov_b32_e32 v118, 0
	v_mov_b32_e32 v119, 0
	v_mov_b32_e32 v120, 0
	v_mov_b32_e32 v121, 0
	v_mov_b32_e32 v122, 0
	v_mov_b32_e32 v123, 0
	v_mov_b32_e32 v124, 0
	v_mov_b32_e32 v125, 0
	v_mov_b32_e32 v126, 0
	v_mov_b32_e32 v127, 0
	s_nop 0
	s_nop 0
	s_nop 0
	s_nop 0
	s_nop 0
	s_nop 0
	s_nop 0
	s_nop 0
	s_nop 0
	s_nop 0
	s_nop 0
	s_nop 0
	s_waitcnt vmcnt(2)
	s_barrier
	global_load_lds_dwordx4 v[6:7], off
	v_lshl_add_u64 v[4:5], v[4:5], 0, s[8:9]
	s_add_i32 m0, s23, 0x1a000
	s_add_i32 s51, s23, 0x8000
	s_add_i32 s76, s23, 0xa000
	global_load_lds_dwordx4 v[4:5], off
	v_lshl_add_u64 v[0:1], v[0:1], 0, s[8:9]
	s_mov_b32 m0, s51
	s_add_u32 s12, s26, 0x40080
	global_load_lds_dwordx4 v[0:1], off
	v_lshl_add_u64 v[0:1], v[2:3], 0, s[8:9]
	s_mov_b32 m0, s76
	s_addc_u32 s13, s27, 0
	global_load_lds_dwordx4 v[0:1], off
	s_add_i32 m0, s23, 0x1c000
	v_lshl_add_u64 v[0:1], s[12:13], 0, v[130:131]
	global_load_lds_dwordx4 v[0:1], off
	v_lshl_add_u64 v[0:1], s[12:13], 0, v[134:135]
	s_add_i32 m0, s23, 0x1e000
	s_cmpk_lt_u32 s10, 0x100
	global_load_lds_dwordx4 v[0:1], off
	v_lshrrev_b32_e32 v1, 1, v8
	v_and_b32_e32 v1, 24, v1
	v_and_b32_e32 v0, 15, v8
	v_lshlrev_b32_e32 v2, 1, v1
	v_lshl_or_b32 v152, s1, 6, v0
	v_lshl_or_b32 v0, v0, 6, v2
	v_lshlrev_b32_e32 v2, 2, v8
	v_and_b32_e32 v2, 32, v2
	v_bitop3_b32 v3, v0, s11, v2 bitop3:0xde
	v_bitop3_b32 v153, v0, s15, v2 bitop3:0xde
	v_lshlrev_b32_e32 v0, 14, v9
	v_and_b32_e32 v0, 0xffff8000, v0
	v_or_b32_e32 v154, s14, v1
	v_lshl_add_u32 v0, v10, 11, v0
	v_and_b32_e32 v1, 1, v9
	v_lshl_or_b32 v0, v1, 6, v0
	v_lshl_add_u32 v136, v11, 1, v0
	v_lshlrev_b32_e32 v0, 14, v12
	v_and_b32_e32 v0, 0xffff8000, v0
	s_waitcnt vmcnt(6)
	v_lshl_add_u32 v0, v13, 11, v0
	v_and_b32_e32 v1, 1, v12
	s_cselect_b64 s[10:11], -1, 0
	v_lshl_or_b32 v0, v1, 6, v0
	s_add_i32 s78, 0, 0x10000
	s_add_i32 s79, 0, 0x14000
	s_sext_i32_i8 s3, s0
	s_ashr_i32 s77, s31, 31
	v_mov_b32_e32 v137, v131
	v_lshl_add_u32 v138, v14, 1, v0
	v_mov_b32_e32 v139, v131
	v_mov_b64_e32 v[140:141], 0x400
	v_mov_b64_e32 v[142:143], 0x3ff
	v_add_u32_e32 v155, s78, v153
	v_add_u32_e32 v156, s79, v153
	v_add_u32_e32 v157, 0, v3
	v_mov_b32_e32 v158, 0x358637bd
	s_mov_b64 s[12:13], 0x160000
	s_mov_b32 s86, 0x160000
	s_barrier
	s_branch .LBB0_687

.LBB0_693:
	s_ashr_i32 s17, s16, 31
	s_lshl_b64 s[18:19], s[16:17], 19
	s_add_u32 s18, s82, s18
	s_addc_u32 s19, s83, s19
	s_and_b64 s[20:21], s[0:1], exec
	s_cselect_b32 s17, s19, s25
	s_cselect_b32 s87, s18, s24
	s_ashr_i32 s15, s14, 31
	s_lshl_b64 s[20:21], s[14:15], 19
	s_add_u32 s20, s35, s20
	s_addc_u32 s21, s36, s21
	s_and_b64 s[28:29], s[0:1], exec
	s_cselect_b32 s15, s21, s27
	s_cselect_b32 s88, s20, s26
	s_add_u32 s24, s24, 0x40080
	s_addc_u32 s25, s25, 0
	s_add_u32 s89, s26, 0x100
	v_mov_b32_e32 v0, 0
	s_addc_u32 s90, s27, 0
	s_mov_b32 s91, -2
	v_mov_b32_e32 v1, v0
	v_mov_b32_e32 v2, v0
	v_mov_b32_e32 v3, v0
	v_mov_b32_e32 v4, v0
	v_mov_b32_e32 v5, v0
	v_mov_b32_e32 v6, v0
	v_mov_b32_e32 v7, v0
	s_nop 0
	v_mov_b32_e32 v8, v0
	v_mov_b32_e32 v9, v0
	v_mov_b32_e32 v10, v0
	v_mov_b32_e32 v11, v0
	v_mov_b32_e32 v12, v0
	v_mov_b32_e32 v13, v0
	v_mov_b32_e32 v14, v0
	v_mov_b32_e32 v15, v0
	v_mov_b32_e32 v16, v0
	v_mov_b32_e32 v17, v0
	v_mov_b32_e32 v18, v0
	v_mov_b32_e32 v19, v0
	v_mov_b32_e32 v20, v0
	v_mov_b32_e32 v21, v0
	v_mov_b32_e32 v22, v0
	v_mov_b32_e32 v23, v0
	v_mov_b32_e32 v24, v0
	v_mov_b32_e32 v25, v0
	v_mov_b32_e32 v26, v0
	v_mov_b32_e32 v27, v0
	v_mov_b32_e32 v28, v0
	v_mov_b32_e32 v29, v0
	v_mov_b32_e32 v30, v0
	v_mov_b32_e32 v31, v0
	s_cmp_eq_u32 s98, 1
	s_mov_b32 s98, 0
	s_cbranch_scc1 .Lzskip_3
	v_mov_b32_e32 v32, v0
	v_mov_b32_e32 v33, v0
	v_mov_b32_e32 v34, v0
	v_mov_b32_e32 v35, v0
	v_mov_b32_e32 v36, v0
	v_mov_b32_e32 v37, v0
	v_mov_b32_e32 v38, v0
	v_mov_b32_e32 v39, v0
	v_mov_b32_e32 v40, v0
	v_mov_b32_e32 v41, v0
	v_mov_b32_e32 v42, v0
	v_mov_b32_e32 v43, v0
	v_mov_b32_e32 v44, v0
	v_mov_b32_e32 v45, v0
	v_mov_b32_e32 v46, v0
	v_mov_b32_e32 v47, v0
	v_mov_b32_e32 v48, v0
	v_mov_b32_e32 v49, v0
	v_mov_b32_e32 v50, v0
	v_mov_b32_e32 v51, v0
	v_mov_b32_e32 v52, v0
	v_mov_b32_e32 v53, v0
	v_mov_b32_e32 v54, v0
	v_mov_b32_e32 v55, v0
	v_mov_b32_e32 v56, v0
	v_mov_b32_e32 v57, v0
	v_mov_b32_e32 v58, v0
	v_mov_b32_e32 v59, v0
	v_mov_b32_e32 v60, v0
	v_mov_b32_e32 v61, v0
	v_mov_b32_e32 v62, v0
	v_mov_b32_e32 v63, v0
	v_mov_b32_e32 v64, v0
	v_mov_b32_e32 v65, v0
	v_mov_b32_e32 v66, v0
	v_mov_b32_e32 v67, v0
	v_mov_b32_e32 v68, v0
	v_mov_b32_e32 v69, v0
	v_mov_b32_e32 v70, v0
	v_mov_b32_e32 v71, v0
	v_mov_b32_e32 v72, v0
	v_mov_b32_e32 v73, v0
	v_mov_b32_e32 v74, v0
	v_mov_b32_e32 v75, v0
	v_mov_b32_e32 v76, v0
	v_mov_b32_e32 v77, v0
	v_mov_b32_e32 v78, v0
	v_mov_b32_e32 v79, v0
	v_mov_b32_e32 v80, v0
	v_mov_b32_e32 v81, v0
	v_mov_b32_e32 v82, v0
	v_mov_b32_e32 v83, v0
	v_mov_b32_e32 v84, v0
	v_mov_b32_e32 v85, v0
	v_mov_b32_e32 v86, v0
	v_mov_b32_e32 v87, v0
	v_mov_b32_e32 v88, v0
	v_mov_b32_e32 v89, v0
	v_mov_b32_e32 v90, v0
	v_mov_b32_e32 v91, v0
	v_mov_b32_e32 v92, v0
	v_mov_b32_e32 v93, v0
	v_mov_b32_e32 v94, v0
	v_mov_b32_e32 v95, v0
	v_mov_b32_e32 v96, v0
	v_mov_b32_e32 v97, v0
	v_mov_b32_e32 v98, v0
	v_mov_b32_e32 v99, v0
	v_mov_b32_e32 v100, v0
	v_mov_b32_e32 v101, v0
	v_mov_b32_e32 v102, v0
	v_mov_b32_e32 v103, v0
	v_mov_b32_e32 v104, v0
	v_mov_b32_e32 v105, v0
	v_mov_b32_e32 v106, v0
	v_mov_b32_e32 v107, v0
	v_mov_b32_e32 v108, v0
	v_mov_b32_e32 v109, v0
	v_mov_b32_e32 v110, v0
	v_mov_b32_e32 v111, v0
	v_mov_b32_e32 v112, v0
	v_mov_b32_e32 v113, v0
	v_mov_b32_e32 v114, v0
	v_mov_b32_e32 v115, v0
	v_mov_b32_e32 v116, v0
	v_mov_b32_e32 v117, v0
	v_mov_b32_e32 v118, v0
	v_mov_b32_e32 v119, v0
	v_mov_b32_e32 v120, v0
	v_mov_b32_e32 v121, v0
	v_mov_b32_e32 v122, v0
	v_mov_b32_e32 v123, v0
	v_mov_b32_e32 v124, v0
	v_mov_b32_e32 v125, v0
	v_mov_b32_e32 v126, v0
	v_mov_b32_e32 v127, v0
.Lzskip_3:
.LBB0_694:
	ds_read_b128 v[144:147], v155
	ds_read_b128 v[148:151], v155 offset:1024
	ds_read_b128 v[160:163], v155 offset:2048
	ds_read_b128 v[164:167], v155 offset:3072
	ds_read_b128 v[168:171], v156
	ds_read_b128 v[172:175], v156 offset:1024
	ds_read_b128 v[176:179], v156 offset:2048
	ds_read_b128 v[180:183], v156 offset:3072
	s_add_u32 s26, s24, 0xfffc0080
	s_addc_u32 s27, s25, -1
	s_cmp_eq_u32 s91, 12
	s_cselect_b32 s29, s17, s27
	s_cselect_b32 s28, s87, s26
	s_cselect_b32 s27, s15, s90
	s_cselect_b32 s26, s88, s89
	v_lshl_add_u64 v[204:205], s[24:25], 0, v[136:137]
	s_add_i32 m0, s23, 0xc000
	ds_read_b128 v[184:187], v157
	ds_read_b128 v[188:191], v157 offset:1024
	ds_read_b128 v[192:195], v157 offset:2048
	ds_read_b128 v[196:199], v157 offset:3072
	ds_read_b128 v[200:203], v157 offset:4096
	ds_read_b128 v[208:211], v157 offset:5120
	ds_read_b128 v[212:215], v157 offset:6144
	ds_read_b128 v[216:219], v157 offset:7168
	global_load_lds_dwordx4 v[204:205], off
	v_lshl_add_u64 v[204:205], s[24:25], 0, v[138:139]
	s_add_i32 m0, s23, 0xe000
	s_nop 0
	global_load_lds_dwordx4 v[204:205], off
	s_waitcnt vmcnt(8)
	s_waitcnt lgkmcnt(0)
	s_setprio 1
	s_barrier
	v_mfma_f32_16x16x32_bf16 v[124:127], v[144:147], v[184:187], v[124:127]
	v_mfma_f32_16x16x32_bf16 v[120:123], v[160:163], v[184:187], v[120:123]
	v_mfma_f32_16x16x32_bf16 v[116:119], v[144:147], v[192:195], v[116:119]
	v_mfma_f32_16x16x32_bf16 v[104:107], v[160:163], v[192:195], v[104:107]
	v_mfma_f32_16x16x32_bf16 v[92:95], v[144:147], v[200:203], v[92:95]
	v_mfma_f32_16x16x32_bf16 v[88:91], v[160:163], v[200:203], v[88:91]
	v_mfma_f32_16x16x32_bf16 v[76:79], v[144:147], v[212:215], v[76:79]
	v_mfma_f32_16x16x32_bf16 v[72:75], v[160:163], v[212:215], v[72:75]
	v_mfma_f32_16x16x32_bf16 v[124:127], v[148:151], v[188:191], v[124:127]
	v_mfma_f32_16x16x32_bf16 v[120:123], v[164:167], v[188:191], v[120:123]
	v_mfma_f32_16x16x32_bf16 v[116:119], v[148:151], v[196:199], v[116:119]
	v_mfma_f32_16x16x32_bf16 v[104:107], v[164:167], v[196:199], v[104:107]
	v_mfma_f32_16x16x32_bf16 v[92:95], v[148:151], v[208:211], v[92:95]
	v_mfma_f32_16x16x32_bf16 v[88:91], v[164:167], v[208:211], v[88:91]
	v_mfma_f32_16x16x32_bf16 v[76:79], v[148:151], v[216:219], v[76:79]
	v_mfma_f32_16x16x32_bf16 v[72:75], v[164:167], v[216:219], v[72:75]
	s_setprio 0
	s_setprio 1
	v_mfma_f32_16x16x32_bf16 v[112:115], v[168:171], v[184:187], v[112:115]
	v_mfma_f32_16x16x32_bf16 v[108:111], v[176:179], v[184:187], v[108:111]
	v_mfma_f32_16x16x32_bf16 v[100:103], v[168:171], v[192:195], v[100:103]
	v_mfma_f32_16x16x32_bf16 v[96:99], v[176:179], v[192:195], v[96:99]
	v_mfma_f32_16x16x32_bf16 v[84:87], v[168:171], v[200:203], v[84:87]
	v_mfma_f32_16x16x32_bf16 v[80:83], v[176:179], v[200:203], v[80:83]
	v_mfma_f32_16x16x32_bf16 v[68:71], v[168:171], v[212:215], v[68:71]
	v_mfma_f32_16x16x32_bf16 v[64:67], v[176:179], v[212:215], v[64:67]
	v_mfma_f32_16x16x32_bf16 v[112:115], v[172:175], v[188:191], v[112:115]
	v_mfma_f32_16x16x32_bf16 v[108:111], v[180:183], v[188:191], v[108:111]
	v_mfma_f32_16x16x32_bf16 v[100:103], v[172:175], v[196:199], v[100:103]
	v_mfma_f32_16x16x32_bf16 v[96:99], v[180:183], v[196:199], v[96:99]
	v_mfma_f32_16x16x32_bf16 v[84:87], v[172:175], v[208:211], v[84:87]
	v_mfma_f32_16x16x32_bf16 v[80:83], v[180:183], v[208:211], v[80:83]
	v_mfma_f32_16x16x32_bf16 v[68:71], v[172:175], v[216:219], v[68:71]
	v_mfma_f32_16x16x32_bf16 v[64:67], v[180:183], v[216:219], v[64:67]
	s_barrier
	s_setprio 0
	s_add_i32 s92, s78, s37
	v_lshl_add_u64 v[204:205], s[26:27], 0, v[130:131]
	s_mov_b32 m0, s92
	ds_read_b128 v[184:187], v157 offset:16384
	ds_read_b128 v[188:191], v157 offset:17408
	ds_read_b128 v[192:195], v157 offset:18432
	ds_read_b128 v[196:199], v157 offset:19456
	ds_read_b128 v[200:203], v157 offset:20480
	ds_read_b128 v[208:211], v157 offset:21504
	ds_read_b128 v[212:215], v157 offset:22528
	ds_read_b128 v[216:219], v157 offset:23552
	global_load_lds_dwordx4 v[204:205], off
	s_add_i32 m0, s92, 0x2000
	s_add_u32 s92, s26, 0x40000
	v_lshl_add_u64 v[220:221], s[26:27], 0, v[134:135]
	s_addc_u32 s93, s27, 0
	s_add_i32 s94, s79, s37
	global_load_lds_dwordx4 v[220:221], off
	v_lshl_add_u64 v[222:223], s[92:93], 0, v[130:131]
	s_mov_b32 m0, s94
	v_lshl_add_u64 v[224:225], s[28:29], 0, v[132:133]
	global_load_lds_dwordx4 v[222:223], off
	v_lshl_add_u64 v[222:223], s[92:93], 0, v[134:135]
	s_add_i32 m0, s94, 0x2000
	s_nop 0
	global_load_lds_dwordx4 v[222:223], off
	v_lshl_add_u64 v[222:223], s[28:29], 0, v[128:129]
	s_mov_b32 m0, s23
	s_nop 0
	global_load_lds_dwordx4 v[222:223], off
	s_mov_b32 m0, s39
	s_nop 0
	global_load_lds_dwordx4 v[224:225], off
	s_waitcnt vmcnt(8)
	s_waitcnt lgkmcnt(0)
	s_setprio 1
	s_barrier
	v_mfma_f32_16x16x32_bf16 v[60:63], v[144:147], v[184:187], v[60:63]
	v_mfma_f32_16x16x32_bf16 v[56:59], v[160:163], v[184:187], v[56:59]
	v_mfma_f32_16x16x32_bf16 v[44:47], v[144:147], v[192:195], v[44:47]
	v_mfma_f32_16x16x32_bf16 v[40:43], v[160:163], v[192:195], v[40:43]
	v_mfma_f32_16x16x32_bf16 v[28:31], v[144:147], v[200:203], v[28:31]
	v_mfma_f32_16x16x32_bf16 v[24:27], v[160:163], v[200:203], v[24:27]
	v_mfma_f32_16x16x32_bf16 v[12:15], v[144:147], v[212:215], v[12:15]
	v_mfma_f32_16x16x32_bf16 v[8:11], v[160:163], v[212:215], v[8:11]
	v_mfma_f32_16x16x32_bf16 v[60:63], v[148:151], v[188:191], v[60:63]
	v_mfma_f32_16x16x32_bf16 v[56:59], v[164:167], v[188:191], v[56:59]
	v_mfma_f32_16x16x32_bf16 v[44:47], v[148:151], v[196:199], v[44:47]
	v_mfma_f32_16x16x32_bf16 v[40:43], v[164:167], v[196:199], v[40:43]
	v_mfma_f32_16x16x32_bf16 v[28:31], v[148:151], v[208:211], v[28:31]
	v_mfma_f32_16x16x32_bf16 v[24:27], v[164:167], v[208:211], v[24:27]
	v_mfma_f32_16x16x32_bf16 v[12:15], v[148:151], v[216:219], v[12:15]
	v_mfma_f32_16x16x32_bf16 v[8:11], v[164:167], v[216:219], v[8:11]
	s_setprio 0
	s_setprio 1
	v_mfma_f32_16x16x32_bf16 v[52:55], v[168:171], v[184:187], v[52:55]
	v_mfma_f32_16x16x32_bf16 v[48:51], v[176:179], v[184:187], v[48:51]
	v_mfma_f32_16x16x32_bf16 v[36:39], v[168:171], v[192:195], v[36:39]
	v_mfma_f32_16x16x32_bf16 v[32:35], v[176:179], v[192:195], v[32:35]
	v_mfma_f32_16x16x32_bf16 v[20:23], v[168:171], v[200:203], v[20:23]
	v_mfma_f32_16x16x32_bf16 v[16:19], v[176:179], v[200:203], v[16:19]
	v_mfma_f32_16x16x32_bf16 v[4:7], v[168:171], v[212:215], v[4:7]
	v_mfma_f32_16x16x32_bf16 v[0:3], v[176:179], v[212:215], v[0:3]
	v_mfma_f32_16x16x32_bf16 v[52:55], v[172:175], v[188:191], v[52:55]
	v_mfma_f32_16x16x32_bf16 v[48:51], v[180:183], v[188:191], v[48:51]
	v_mfma_f32_16x16x32_bf16 v[36:39], v[172:175], v[196:199], v[36:39]
	v_mfma_f32_16x16x32_bf16 v[32:35], v[180:183], v[196:199], v[32:35]
	v_mfma_f32_16x16x32_bf16 v[20:23], v[172:175], v[208:211], v[20:23]
	v_mfma_f32_16x16x32_bf16 v[16:19], v[180:183], v[208:211], v[16:19]
	v_mfma_f32_16x16x32_bf16 v[4:7], v[172:175], v[216:219], v[4:7]
	v_mfma_f32_16x16x32_bf16 v[0:3], v[180:183], v[216:219], v[0:3]
	s_barrier
	s_setprio 0
	s_add_i32 s92, 0, 0x18000
	v_add_u32_e32 v159, s92, v153
	s_add_i32 s93, 0, 0x1c000
	ds_read_b128 v[144:147], v159
	ds_read_b128 v[148:151], v159 offset:1024
	ds_read_b128 v[160:163], v159 offset:2048
	ds_read_b128 v[164:167], v159 offset:3072
	v_add_u32_e32 v159, s93, v153
	ds_read_b128 v[168:171], v159
	ds_read_b128 v[172:175], v159 offset:1024
	ds_read_b128 v[176:179], v159 offset:2048
	ds_read_b128 v[180:183], v159 offset:3072
	s_add_u32 s28, s28, 0x40000
	s_addc_u32 s29, s29, 0
	s_mov_b32 m0, s40
	v_lshl_add_u64 v[226:227], s[28:29], 0, v[128:129]
	ds_read_b128 v[184:187], v157 offset:32768
	ds_read_b128 v[188:191], v157 offset:33792
	ds_read_b128 v[192:195], v157 offset:34816
	ds_read_b128 v[196:199], v157 offset:35840
	ds_read_b128 v[200:203], v157 offset:36864
	ds_read_b128 v[208:211], v157 offset:37888
	ds_read_b128 v[212:215], v157 offset:38912
	ds_read_b128 v[216:219], v157 offset:39936
	global_load_lds_dwordx4 v[226:227], off
	v_lshl_add_u64 v[226:227], s[28:29], 0, v[132:133]
	s_mov_b32 m0, s41
	s_nop 0
	global_load_lds_dwordx4 v[226:227], off
	s_waitcnt vmcnt(8)
	s_waitcnt lgkmcnt(0)
	s_setprio 1
	s_barrier
	v_mfma_f32_16x16x32_bf16 v[124:127], v[144:147], v[184:187], v[124:127]
	v_mfma_f32_16x16x32_bf16 v[120:123], v[160:163], v[184:187], v[120:123]
	v_mfma_f32_16x16x32_bf16 v[116:119], v[144:147], v[192:195], v[116:119]
	v_mfma_f32_16x16x32_bf16 v[104:107], v[160:163], v[192:195], v[104:107]
	v_mfma_f32_16x16x32_bf16 v[92:95], v[144:147], v[200:203], v[92:95]
	v_mfma_f32_16x16x32_bf16 v[88:91], v[160:163], v[200:203], v[88:91]
	v_mfma_f32_16x16x32_bf16 v[76:79], v[144:147], v[212:215], v[76:79]
	v_mfma_f32_16x16x32_bf16 v[72:75], v[160:163], v[212:215], v[72:75]
	v_mfma_f32_16x16x32_bf16 v[124:127], v[148:151], v[188:191], v[124:127]
	v_mfma_f32_16x16x32_bf16 v[120:123], v[164:167], v[188:191], v[120:123]
	v_mfma_f32_16x16x32_bf16 v[116:119], v[148:151], v[196:199], v[116:119]
	v_mfma_f32_16x16x32_bf16 v[104:107], v[164:167], v[196:199], v[104:107]
	v_mfma_f32_16x16x32_bf16 v[92:95], v[148:151], v[208:211], v[92:95]
	v_mfma_f32_16x16x32_bf16 v[88:91], v[164:167], v[208:211], v[88:91]
	v_mfma_f32_16x16x32_bf16 v[76:79], v[148:151], v[216:219], v[76:79]
	v_mfma_f32_16x16x32_bf16 v[72:75], v[164:167], v[216:219], v[72:75]
	s_setprio 0
	s_setprio 1
	v_mfma_f32_16x16x32_bf16 v[112:115], v[168:171], v[184:187], v[112:115]
	v_mfma_f32_16x16x32_bf16 v[108:111], v[176:179], v[184:187], v[108:111]
	v_mfma_f32_16x16x32_bf16 v[100:103], v[168:171], v[192:195], v[100:103]
	v_mfma_f32_16x16x32_bf16 v[96:99], v[176:179], v[192:195], v[96:99]
	v_mfma_f32_16x16x32_bf16 v[84:87], v[168:171], v[200:203], v[84:87]
	v_mfma_f32_16x16x32_bf16 v[80:83], v[176:179], v[200:203], v[80:83]
	v_mfma_f32_16x16x32_bf16 v[68:71], v[168:171], v[212:215], v[68:71]
	v_mfma_f32_16x16x32_bf16 v[64:67], v[176:179], v[212:215], v[64:67]
	v_mfma_f32_16x16x32_bf16 v[112:115], v[172:175], v[188:191], v[112:115]
	v_mfma_f32_16x16x32_bf16 v[108:111], v[180:183], v[188:191], v[108:111]
	v_mfma_f32_16x16x32_bf16 v[100:103], v[172:175], v[196:199], v[100:103]
	v_mfma_f32_16x16x32_bf16 v[96:99], v[180:183], v[196:199], v[96:99]
	v_mfma_f32_16x16x32_bf16 v[84:87], v[172:175], v[208:211], v[84:87]
	v_mfma_f32_16x16x32_bf16 v[80:83], v[180:183], v[208:211], v[80:83]
	v_mfma_f32_16x16x32_bf16 v[68:71], v[172:175], v[216:219], v[68:71]
	v_mfma_f32_16x16x32_bf16 v[64:67], v[180:183], v[216:219], v[64:67]
	s_barrier
	s_setprio 0
	s_add_i32 s28, s92, s37
	v_lshl_add_u64 v[204:205], v[204:205], 0, s[8:9]
	s_mov_b32 m0, s28
	ds_read_b128 v[184:187], v157 offset:49152
	ds_read_b128 v[188:191], v157 offset:50176
	ds_read_b128 v[192:195], v157 offset:51200
	ds_read_b128 v[196:199], v157 offset:52224
	ds_read_b128 v[200:203], v157 offset:53248
	ds_read_b128 v[208:211], v157 offset:54272
	ds_read_b128 v[212:215], v157 offset:55296
	ds_read_b128 v[216:219], v157 offset:56320
	global_load_lds_dwordx4 v[204:205], off
	s_add_i32 m0, s28, 0x2000
	s_add_u32 s26, s26, 0x40080
	v_lshl_add_u64 v[204:205], v[220:221], 0, s[8:9]
	s_addc_u32 s27, s27, 0
	s_add_i32 s28, s93, s37
	global_load_lds_dwordx4 v[204:205], off
	v_lshl_add_u64 v[204:205], s[26:27], 0, v[130:131]
	s_mov_b32 m0, s28
	s_nop 0
	global_load_lds_dwordx4 v[204:205], off
	v_lshl_add_u64 v[204:205], s[26:27], 0, v[134:135]
	s_add_i32 m0, s28, 0x2000
	s_nop 0
	global_load_lds_dwordx4 v[204:205], off
	v_lshl_add_u64 v[204:205], v[222:223], 0, s[8:9]
	s_mov_b32 m0, s51
	s_nop 0
	global_load_lds_dwordx4 v[204:205], off
	v_lshl_add_u64 v[204:205], v[224:225], 0, s[8:9]
	s_mov_b32 m0, s76
	s_nop 0
	global_load_lds_dwordx4 v[204:205], off
	s_waitcnt vmcnt(8)
	s_waitcnt lgkmcnt(0)
	s_setprio 1
	s_barrier
	v_mfma_f32_16x16x32_bf16 v[60:63], v[144:147], v[184:187], v[60:63]
	v_mfma_f32_16x16x32_bf16 v[56:59], v[160:163], v[184:187], v[56:59]
	v_mfma_f32_16x16x32_bf16 v[44:47], v[144:147], v[192:195], v[44:47]
	v_mfma_f32_16x16x32_bf16 v[40:43], v[160:163], v[192:195], v[40:43]
	v_mfma_f32_16x16x32_bf16 v[28:31], v[144:147], v[200:203], v[28:31]
	v_mfma_f32_16x16x32_bf16 v[24:27], v[160:163], v[200:203], v[24:27]
	v_mfma_f32_16x16x32_bf16 v[12:15], v[144:147], v[212:215], v[12:15]
	v_mfma_f32_16x16x32_bf16 v[8:11], v[160:163], v[212:215], v[8:11]
	v_mfma_f32_16x16x32_bf16 v[60:63], v[148:151], v[188:191], v[60:63]
	v_mfma_f32_16x16x32_bf16 v[56:59], v[164:167], v[188:191], v[56:59]
	v_mfma_f32_16x16x32_bf16 v[44:47], v[148:151], v[196:199], v[44:47]
	v_mfma_f32_16x16x32_bf16 v[40:43], v[164:167], v[196:199], v[40:43]
	v_mfma_f32_16x16x32_bf16 v[28:31], v[148:151], v[208:211], v[28:31]
	v_mfma_f32_16x16x32_bf16 v[24:27], v[164:167], v[208:211], v[24:27]
	v_mfma_f32_16x16x32_bf16 v[12:15], v[148:151], v[216:219], v[12:15]
	v_mfma_f32_16x16x32_bf16 v[8:11], v[164:167], v[216:219], v[8:11]
	s_setprio 0
	s_setprio 1
	v_mfma_f32_16x16x32_bf16 v[52:55], v[168:171], v[184:187], v[52:55]
	v_mfma_f32_16x16x32_bf16 v[48:51], v[176:179], v[184:187], v[48:51]
	v_mfma_f32_16x16x32_bf16 v[36:39], v[168:171], v[192:195], v[36:39]
	v_mfma_f32_16x16x32_bf16 v[32:35], v[176:179], v[192:195], v[32:35]
	v_mfma_f32_16x16x32_bf16 v[20:23], v[168:171], v[200:203], v[20:23]
	v_mfma_f32_16x16x32_bf16 v[16:19], v[176:179], v[200:203], v[16:19]
	v_mfma_f32_16x16x32_bf16 v[4:7], v[168:171], v[212:215], v[4:7]
	v_mfma_f32_16x16x32_bf16 v[0:3], v[176:179], v[212:215], v[0:3]
	v_mfma_f32_16x16x32_bf16 v[52:55], v[172:175], v[188:191], v[52:55]
	v_mfma_f32_16x16x32_bf16 v[48:51], v[180:183], v[188:191], v[48:51]
	v_mfma_f32_16x16x32_bf16 v[36:39], v[172:175], v[196:199], v[36:39]
	v_mfma_f32_16x16x32_bf16 v[32:35], v[180:183], v[196:199], v[32:35]
	v_mfma_f32_16x16x32_bf16 v[20:23], v[172:175], v[208:211], v[20:23]
	v_mfma_f32_16x16x32_bf16 v[16:19], v[180:183], v[208:211], v[16:19]
	v_mfma_f32_16x16x32_bf16 v[4:7], v[172:175], v[216:219], v[4:7]
	v_mfma_f32_16x16x32_bf16 v[0:3], v[180:183], v[216:219], v[0:3]
	s_barrier
	s_setprio 0
	s_add_i32 s91, s91, 2
	s_add_u32 s24, s24, 0x100
	s_addc_u32 s25, s25, 0
	s_add_u32 s89, s89, 0x100
	s_addc_u32 s90, s90, 0
	s_cmp_gt_u32 s91, 13
	s_cbranch_scc0 .LBB0_694
	s_and_b64 vcc, exec, s[10:11]
	s_cbranch_vccz .LBB0_697
	s_barrier

.LBB0_842:
	s_lshl_b32 s1, s1, 5
	s_mov_b64 s[10:11], 0x80
	s_and_b32 s14, s1, 0x60
	s_add_i32 m0, s25, 0x18000
	v_lshl_add_u64 v[6:7], v[6:7], 0, s[10:11]
	s_lshl_b32 s12, s0, 13
	s_lshl_b32 s1, s14, 7
	s_mov_b32 s98, 1
	v_mov_b32_e32 v32, 0
	v_mov_b32_e32 v33, 0
	v_mov_b32_e32 v34, 0
	v_mov_b32_e32 v35, 0
	v_mov_b32_e32 v36, 0
	v_mov_b32_e32 v37, 0
	v_mov_b32_e32 v38, 0
	v_mov_b32_e32 v39, 0
	v_mov_b32_e32 v40, 0
	v_mov_b32_e32 v41, 0
	v_mov_b32_e32 v42, 0
	v_mov_b32_e32 v43, 0
	v_mov_b32_e32 v44, 0
	v_mov_b32_e32 v45, 0
	v_mov_b32_e32 v46, 0
	v_mov_b32_e32 v47, 0
	v_mov_b32_e32 v48, 0
	v_mov_b32_e32 v49, 0
	v_mov_b32_e32 v50, 0
	v_mov_b32_e32 v51, 0
	v_mov_b32_e32 v52, 0
	v_mov_b32_e32 v53, 0
	v_mov_b32_e32 v54, 0
	v_mov_b32_e32 v55, 0
	v_mov_b32_e32 v56, 0
	v_mov_b32_e32 v57, 0
	v_mov_b32_e32 v58, 0
	v_mov_b32_e32 v59, 0
	v_mov_b32_e32 v60, 0
	v_mov_b32_e32 v61, 0
	v_mov_b32_e32 v62, 0
	v_mov_b32_e32 v63, 0
	v_mov_b32_e32 v64, 0
	v_mov_b32_e32 v65, 0
	v_mov_b32_e32 v66, 0
	v_mov_b32_e32 v67, 0
	v_mov_b32_e32 v68, 0
	v_mov_b32_e32 v69, 0
	v_mov_b32_e32 v70, 0
	v_mov_b32_e32 v71, 0
	v_mov_b32_e32 v72, 0
	v_mov_b32_e32 v73, 0
	v_mov_b32_e32 v74, 0
	v_mov_b32_e32 v75, 0
	v_mov_b32_e32 v76, 0
	v_mov_b32_e32 v77, 0
	v_mov_b32_e32 v78, 0
	v_mov_b32_e32 v79, 0
	v_mov_b32_e32 v80, 0
	v_mov_b32_e32 v81, 0
	v_mov_b32_e32 v82, 0
	v_mov_b32_e32 v83, 0
	v_mov_b32_e32 v84, 0
	v_mov_b32_e32 v85, 0
	v_mov_b32_e32 v86, 0
	v_mov_b32_e32 v87, 0
	v_mov_b32_e32 v88, 0
	v_mov_b32_e32 v89, 0
	v_mov_b32_e32 v90, 0
	v_mov_b32_e32 v91, 0
	v_mov_b32_e32 v92, 0
	v_mov_b32_e32 v93, 0
	v_mov_b32_e32 v94, 0
	v_mov_b32_e32 v95, 0
	v_mov_b32_e32 v96, 0
	v_mov_b32_e32 v97, 0
	v_mov_b32_e32 v98, 0
	v_mov_b32_e32 v99, 0
	v_mov_b32_e32 v100, 0
	v_mov_b32_e32 v101, 0
	v_mov_b32_e32 v102, 0
	v_mov_b32_e32 v103, 0
	v_mov_b32_e32 v104, 0
	v_mov_b32_e32 v105, 0
	v_mov_b32_e32 v106, 0
	v_mov_b32_e32 v107, 0
	v_mov_b32_e32 v108, 0
	v_mov_b32_e32 v109, 0
	v_mov_b32_e32 v110, 0
	v_mov_b32_e32 v111, 0
	v_mov_b32_e32 v112, 0
	v_mov_b32_e32 v113, 0
	v_mov_b32_e32 v114, 0
	v_mov_b32_e32 v115, 0
	v_mov_b32_e32 v116, 0
	v_mov_b32_e32 v117, 0
	v_mov_b32_e32 v118, 0
	v_mov_b32_e32 v119, 0
	v_mov_b32_e32 v120, 0
	v_mov_b32_e32 v121, 0
	v_mov_b32_e32 v122, 0
	v_mov_b32_e32 v123, 0
	v_mov_b32_e32 v124, 0
	v_mov_b32_e32 v125, 0
	v_mov_b32_e32 v126, 0
	v_mov_b32_e32 v127, 0
	s_nop 0
	s_nop 0
	s_nop 0
	s_nop 0
	s_nop 0
	s_nop 0
	s_nop 0
	s_nop 0
	s_nop 0
	s_nop 0
	s_nop 0
	s_nop 0
	s_waitcnt vmcnt(2)
	s_barrier
	global_load_lds_dwordx4 v[6:7], off
	v_lshl_add_u64 v[4:5], v[4:5], 0, s[10:11]
	s_add_i32 m0, s25, 0x1a000
	s_add_i32 s78, s25, 0x8000
	s_add_i32 s79, s25, 0xa000
	global_load_lds_dwordx4 v[4:5], off
	v_lshl_add_u64 v[0:1], v[0:1], 0, s[10:11]
	s_mov_b32 m0, s78
	s_add_u32 s4, s28, 0x100080
	global_load_lds_dwordx4 v[0:1], off
	v_lshl_add_u64 v[0:1], v[2:3], 0, s[10:11]
	s_mov_b32 m0, s79
	s_addc_u32 s5, s29, 0
	global_load_lds_dwordx4 v[0:1], off
	s_add_i32 m0, s25, 0x1c000
	v_lshl_add_u64 v[0:1], s[4:5], 0, v[176:177]
	global_load_lds_dwordx4 v[0:1], off
	v_lshl_add_u64 v[0:1], s[4:5], 0, v[178:179]
	s_add_i32 m0, s25, 0x1e000
	s_mov_b64 s[4:5], 0x100080
	global_load_lds_dwordx4 v[0:1], off
	v_bfe_u32 v0, v8, 4, 2
	v_and_b32_e32 v1, 15, v8
	v_lshlrev_b32_e32 v2, 4, v0
	v_lshl_or_b32 v208, s0, 6, v1
	v_lshl_or_b32 v1, v1, 6, v2
	v_lshlrev_b32_e32 v2, 2, v8
	v_and_b32_e32 v2, 32, v2
	v_bitop3_b32 v209, v1, s1, v2 bitop3:0xde
	v_cmp_eq_u32_e64 s[0:1], 0, v0
	v_lshl_or_b32 v210, v0, 2, s14
	v_lshlrev_b32_e32 v0, 15, v9
	v_and_b32_e32 v0, 0x7fff0000, v0
	v_lshl_add_u32 v0, v10, 12, v0
	v_or_b32_e32 v0, v0, v11
	v_bitop3_b32 v3, v1, s12, v2 bitop3:0xde
	v_add_lshl_u32 v0, v0, v12, 1
	v_mov_b32_e32 v1, v177
	v_lshl_add_u64 v[180:181], v[0:1], 0, s[4:5]
	v_lshlrev_b32_e32 v0, 15, v13
	v_and_b32_e32 v0, 0x7fff0000, v0
	v_lshl_add_u32 v0, v14, 12, v0
	s_waitcnt vmcnt(6)
	s_cmpk_lt_u32 s3, 0x100
	v_or_b32_e32 v0, v0, v15
	s_cselect_b64 s[12:13], -1, 0
	v_add_lshl_u32 v0, v0, v16, 1
	s_add_i32 s88, 0, 0x10000
	s_add_i32 s89, 0, 0x14000
	s_ashr_i32 s86, s36, 31
	s_ashr_i32 s87, s37, 31
	v_lshl_add_u64 v[182:183], v[0:1], 0, s[4:5]
	v_mov_b64_e32 v[184:185], 0x100
	v_mov_b64_e32 v[186:187], 0xff
	v_add_u32_e32 v211, s88, v209
	v_add_u32_e32 v212, s89, v209
	v_add_u32_e32 v213, 0, v3
	v_mbcnt_hi_u32_b32 v214, -1, v207
	s_barrier
	s_branch .LBB0_845

.LBB0_851:
	s_ashr_i32 s17, s16, 31
	s_lshl_b64 s[18:19], s[16:17], 21
	s_add_u32 s18, s80, s18
	s_addc_u32 s19, s81, s19
	s_and_b64 s[20:21], s[4:5], exec
	s_cselect_b32 s3, s19, s27
	s_cselect_b32 s17, s18, s26
	s_ashr_i32 s15, s14, 31
	s_lshl_b64 s[20:21], s[14:15], 21
	s_add_u32 s20, s39, s20
	s_addc_u32 s21, s40, s21
	s_and_b64 s[30:31], s[4:5], exec
	s_cselect_b32 s15, s21, s29
	s_cselect_b32 s23, s20, s28
	s_add_u32 s90, s28, 0x100
	v_mov_b32_e32 v0, 0
	s_addc_u32 s91, s29, 0
	s_mov_b32 s92, -2
	s_waitcnt lgkmcnt(0)
	v_mov_b32_e32 v1, v0
	v_mov_b32_e32 v2, v0
	v_mov_b32_e32 v3, v0
	v_mov_b32_e32 v4, v0
	v_mov_b32_e32 v5, v0
	v_mov_b32_e32 v6, v0
	v_mov_b32_e32 v7, v0
	s_nop 0
	v_mov_b32_e32 v8, v0
	v_mov_b32_e32 v9, v0
	v_mov_b32_e32 v10, v0
	v_mov_b32_e32 v11, v0
	v_mov_b32_e32 v12, v0
	v_mov_b32_e32 v13, v0
	v_mov_b32_e32 v14, v0
	v_mov_b32_e32 v15, v0
	v_mov_b32_e32 v16, v0
	v_mov_b32_e32 v17, v0
	v_mov_b32_e32 v18, v0
	v_mov_b32_e32 v19, v0
	v_mov_b32_e32 v20, v0
	v_mov_b32_e32 v21, v0
	v_mov_b32_e32 v22, v0
	v_mov_b32_e32 v23, v0
	v_mov_b32_e32 v24, v0
	v_mov_b32_e32 v25, v0
	v_mov_b32_e32 v26, v0
	v_mov_b32_e32 v27, v0
	v_mov_b32_e32 v28, v0
	v_mov_b32_e32 v29, v0
	v_mov_b32_e32 v30, v0
	v_mov_b32_e32 v31, v0
	s_cmp_eq_u32 s98, 1
	s_mov_b32 s98, 0
	s_cbranch_scc1 .Lzskip_4
	v_mov_b32_e32 v32, v0
	v_mov_b32_e32 v33, v0
	v_mov_b32_e32 v34, v0
	v_mov_b32_e32 v35, v0
	v_mov_b32_e32 v36, v0
	v_mov_b32_e32 v37, v0
	v_mov_b32_e32 v38, v0
	v_mov_b32_e32 v39, v0
	v_mov_b32_e32 v40, v0
	v_mov_b32_e32 v41, v0
	v_mov_b32_e32 v42, v0
	v_mov_b32_e32 v43, v0
	v_mov_b32_e32 v44, v0
	v_mov_b32_e32 v45, v0
	v_mov_b32_e32 v46, v0
	v_mov_b32_e32 v47, v0
	v_mov_b32_e32 v48, v0
	v_mov_b32_e32 v49, v0
	v_mov_b32_e32 v50, v0
	v_mov_b32_e32 v51, v0
	v_mov_b32_e32 v52, v0
	v_mov_b32_e32 v53, v0
	v_mov_b32_e32 v54, v0
	v_mov_b32_e32 v55, v0
	v_mov_b32_e32 v56, v0
	v_mov_b32_e32 v57, v0
	v_mov_b32_e32 v58, v0
	v_mov_b32_e32 v59, v0
	v_mov_b32_e32 v60, v0
	v_mov_b32_e32 v61, v0
	v_mov_b32_e32 v62, v0
	v_mov_b32_e32 v63, v0
	v_mov_b32_e32 v64, v0
	v_mov_b32_e32 v65, v0
	v_mov_b32_e32 v66, v0
	v_mov_b32_e32 v67, v0
	v_mov_b32_e32 v68, v0
	v_mov_b32_e32 v69, v0
	v_mov_b32_e32 v70, v0
	v_mov_b32_e32 v71, v0
	v_mov_b32_e32 v72, v0
	v_mov_b32_e32 v73, v0
	v_mov_b32_e32 v74, v0
	v_mov_b32_e32 v75, v0
	v_mov_b32_e32 v76, v0
	v_mov_b32_e32 v77, v0
	v_mov_b32_e32 v78, v0
	v_mov_b32_e32 v79, v0
	v_mov_b32_e32 v80, v0
	v_mov_b32_e32 v81, v0
	v_mov_b32_e32 v82, v0
	v_mov_b32_e32 v83, v0
	v_mov_b32_e32 v84, v0
	v_mov_b32_e32 v85, v0
	v_mov_b32_e32 v86, v0
	v_mov_b32_e32 v87, v0
	v_mov_b32_e32 v88, v0
	v_mov_b32_e32 v89, v0
	v_mov_b32_e32 v90, v0
	v_mov_b32_e32 v91, v0
	v_mov_b32_e32 v92, v0
	v_mov_b32_e32 v93, v0
	v_mov_b32_e32 v94, v0
	v_mov_b32_e32 v95, v0
	v_mov_b32_e32 v96, v0
	v_mov_b32_e32 v97, v0
	v_mov_b32_e32 v98, v0
	v_mov_b32_e32 v99, v0
	v_mov_b32_e32 v100, v0
	v_mov_b32_e32 v101, v0
	v_mov_b32_e32 v102, v0
	v_mov_b32_e32 v103, v0
	v_mov_b32_e32 v104, v0
	v_mov_b32_e32 v105, v0
	v_mov_b32_e32 v106, v0
	v_mov_b32_e32 v107, v0
	v_mov_b32_e32 v108, v0
	v_mov_b32_e32 v109, v0
	v_mov_b32_e32 v110, v0
	v_mov_b32_e32 v111, v0
	v_mov_b32_e32 v112, v0
	v_mov_b32_e32 v113, v0
	v_mov_b32_e32 v114, v0
	v_mov_b32_e32 v115, v0
	v_mov_b32_e32 v116, v0
	v_mov_b32_e32 v117, v0
	v_mov_b32_e32 v118, v0
	v_mov_b32_e32 v119, v0
	v_mov_b32_e32 v120, v0
	v_mov_b32_e32 v121, v0
	v_mov_b32_e32 v122, v0
	v_mov_b32_e32 v123, v0
	v_mov_b32_e32 v124, v0
	v_mov_b32_e32 v125, v0
	v_mov_b32_e32 v126, v0
	v_mov_b32_e32 v127, v0
.Lzskip_4:
.LBB0_852:
	ds_read_b128 v[128:131], v211
	ds_read_b128 v[132:135], v211 offset:1024
	ds_read_b128 v[136:139], v211 offset:2048
	ds_read_b128 v[140:143], v211 offset:3072
	ds_read_b128 v[144:147], v212
	ds_read_b128 v[148:151], v212 offset:1024
	ds_read_b128 v[152:155], v212 offset:2048
	ds_read_b128 v[156:159], v212 offset:3072
	s_add_u32 s28, s26, 0x100
	s_addc_u32 s29, s27, 0
	s_cmp_eq_u32 s92, 60
	s_cselect_b32 s35, s3, s29
	s_cselect_b32 s34, s17, s28
	s_cselect_b32 s31, s15, s91
	s_cselect_b32 s30, s23, s90
	v_lshl_add_u64 v[204:205], s[26:27], 0, v[180:181]
	s_add_i32 m0, s25, 0xc000
	ds_read_b128 v[160:163], v213
	ds_read_b128 v[164:167], v213 offset:1024
	ds_read_b128 v[168:171], v213 offset:2048
	ds_read_b128 v[172:175], v213 offset:3072
	ds_read_b128 v[188:191], v213 offset:4096
	ds_read_b128 v[192:195], v213 offset:5120
	ds_read_b128 v[196:199], v213 offset:6144
	ds_read_b128 v[200:203], v213 offset:7168
	global_load_lds_dwordx4 v[204:205], off
	v_lshl_add_u64 v[204:205], s[26:27], 0, v[182:183]
	s_add_i32 m0, s25, 0xe000
	s_nop 0
	global_load_lds_dwordx4 v[204:205], off
	s_waitcnt vmcnt(8)
	s_waitcnt lgkmcnt(0)
	s_setprio 1
	s_barrier
	v_mfma_f32_16x16x32_bf16 v[124:127], v[128:131], v[160:163], v[124:127]
	v_mfma_f32_16x16x32_bf16 v[120:123], v[136:139], v[160:163], v[120:123]
	v_mfma_f32_16x16x32_bf16 v[108:111], v[128:131], v[168:171], v[108:111]
	v_mfma_f32_16x16x32_bf16 v[104:107], v[136:139], v[168:171], v[104:107]
	v_mfma_f32_16x16x32_bf16 v[92:95], v[128:131], v[188:191], v[92:95]
	v_mfma_f32_16x16x32_bf16 v[88:91], v[136:139], v[188:191], v[88:91]
	v_mfma_f32_16x16x32_bf16 v[76:79], v[128:131], v[196:199], v[76:79]
	v_mfma_f32_16x16x32_bf16 v[72:75], v[136:139], v[196:199], v[72:75]
	v_mfma_f32_16x16x32_bf16 v[124:127], v[132:135], v[164:167], v[124:127]
	v_mfma_f32_16x16x32_bf16 v[120:123], v[140:143], v[164:167], v[120:123]
	v_mfma_f32_16x16x32_bf16 v[108:111], v[132:135], v[172:175], v[108:111]
	v_mfma_f32_16x16x32_bf16 v[104:107], v[140:143], v[172:175], v[104:107]
	v_mfma_f32_16x16x32_bf16 v[92:95], v[132:135], v[192:195], v[92:95]
	v_mfma_f32_16x16x32_bf16 v[88:91], v[140:143], v[192:195], v[88:91]
	v_mfma_f32_16x16x32_bf16 v[76:79], v[132:135], v[200:203], v[76:79]
	v_mfma_f32_16x16x32_bf16 v[72:75], v[140:143], v[200:203], v[72:75]
	s_setprio 0
	s_setprio 1
	v_mfma_f32_16x16x32_bf16 v[116:119], v[144:147], v[160:163], v[116:119]
	v_mfma_f32_16x16x32_bf16 v[112:115], v[152:155], v[160:163], v[112:115]
	v_mfma_f32_16x16x32_bf16 v[100:103], v[144:147], v[168:171], v[100:103]
	v_mfma_f32_16x16x32_bf16 v[96:99], v[152:155], v[168:171], v[96:99]
	v_mfma_f32_16x16x32_bf16 v[84:87], v[144:147], v[188:191], v[84:87]
	v_mfma_f32_16x16x32_bf16 v[80:83], v[152:155], v[188:191], v[80:83]
	v_mfma_f32_16x16x32_bf16 v[68:71], v[144:147], v[196:199], v[68:71]
	v_mfma_f32_16x16x32_bf16 v[64:67], v[152:155], v[196:199], v[64:67]
	v_mfma_f32_16x16x32_bf16 v[116:119], v[148:151], v[164:167], v[116:119]
	v_mfma_f32_16x16x32_bf16 v[112:115], v[156:159], v[164:167], v[112:115]
	v_mfma_f32_16x16x32_bf16 v[100:103], v[148:151], v[172:175], v[100:103]
	v_mfma_f32_16x16x32_bf16 v[96:99], v[156:159], v[172:175], v[96:99]
	v_mfma_f32_16x16x32_bf16 v[84:87], v[148:151], v[192:195], v[84:87]
	v_mfma_f32_16x16x32_bf16 v[80:83], v[156:159], v[192:195], v[80:83]
	v_mfma_f32_16x16x32_bf16 v[68:71], v[148:151], v[200:203], v[68:71]
	v_mfma_f32_16x16x32_bf16 v[64:67], v[156:159], v[200:203], v[64:67]
	s_barrier
	s_setprio 0
	s_add_i32 s26, s88, s41
	v_lshl_add_u64 v[204:205], s[30:31], 0, v[176:177]
	s_mov_b32 m0, s26
	ds_read_b128 v[160:163], v213 offset:16384
	ds_read_b128 v[164:167], v213 offset:17408
	ds_read_b128 v[168:171], v213 offset:18432
	ds_read_b128 v[172:175], v213 offset:19456
	ds_read_b128 v[188:191], v213 offset:20480
	ds_read_b128 v[192:195], v213 offset:21504
	ds_read_b128 v[196:199], v213 offset:22528
	ds_read_b128 v[200:203], v213 offset:23552
	global_load_lds_dwordx4 v[204:205], off
	s_add_i32 m0, s26, 0x2000
	s_add_u32 s26, s30, 0x100000
	v_lshl_add_u64 v[216:217], s[30:31], 0, v[178:179]
	s_addc_u32 s27, s31, 0
	s_add_i32 s93, s89, s41
	global_load_lds_dwordx4 v[216:217], off
	v_lshl_add_u64 v[218:219], s[26:27], 0, v[176:177]
	s_mov_b32 m0, s93
	v_lshl_add_u64 v[220:221], s[34:35], 0, v[178:179]
	global_load_lds_dwordx4 v[218:219], off
	v_lshl_add_u64 v[218:219], s[26:27], 0, v[178:179]
	s_add_i32 m0, s93, 0x2000
	s_nop 0
	global_load_lds_dwordx4 v[218:219], off
	v_lshl_add_u64 v[218:219], s[34:35], 0, v[176:177]
	s_mov_b32 m0, s25
	s_nop 0
	global_load_lds_dwordx4 v[218:219], off
	s_mov_b32 m0, s50
	s_nop 0
	global_load_lds_dwordx4 v[220:221], off
	s_waitcnt vmcnt(8)
	s_waitcnt lgkmcnt(0)
	s_setprio 1
	s_barrier
	v_mfma_f32_16x16x32_bf16 v[60:63], v[128:131], v[160:163], v[60:63]
	v_mfma_f32_16x16x32_bf16 v[56:59], v[136:139], v[160:163], v[56:59]
	v_mfma_f32_16x16x32_bf16 v[44:47], v[128:131], v[168:171], v[44:47]
	v_mfma_f32_16x16x32_bf16 v[40:43], v[136:139], v[168:171], v[40:43]
	v_mfma_f32_16x16x32_bf16 v[28:31], v[128:131], v[188:191], v[28:31]
	v_mfma_f32_16x16x32_bf16 v[24:27], v[136:139], v[188:191], v[24:27]
	v_mfma_f32_16x16x32_bf16 v[12:15], v[128:131], v[196:199], v[12:15]
	v_mfma_f32_16x16x32_bf16 v[8:11], v[136:139], v[196:199], v[8:11]
	v_mfma_f32_16x16x32_bf16 v[60:63], v[132:135], v[164:167], v[60:63]
	v_mfma_f32_16x16x32_bf16 v[56:59], v[140:143], v[164:167], v[56:59]
	v_mfma_f32_16x16x32_bf16 v[44:47], v[132:135], v[172:175], v[44:47]
	v_mfma_f32_16x16x32_bf16 v[40:43], v[140:143], v[172:175], v[40:43]
	v_mfma_f32_16x16x32_bf16 v[28:31], v[132:135], v[192:195], v[28:31]
	v_mfma_f32_16x16x32_bf16 v[24:27], v[140:143], v[192:195], v[24:27]
	v_mfma_f32_16x16x32_bf16 v[12:15], v[132:135], v[200:203], v[12:15]
	v_mfma_f32_16x16x32_bf16 v[8:11], v[140:143], v[200:203], v[8:11]
	s_setprio 0
	s_setprio 1
	v_mfma_f32_16x16x32_bf16 v[52:55], v[144:147], v[160:163], v[52:55]
	v_mfma_f32_16x16x32_bf16 v[48:51], v[152:155], v[160:163], v[48:51]
	v_mfma_f32_16x16x32_bf16 v[36:39], v[144:147], v[168:171], v[36:39]
	v_mfma_f32_16x16x32_bf16 v[32:35], v[152:155], v[168:171], v[32:35]
	v_mfma_f32_16x16x32_bf16 v[20:23], v[144:147], v[188:191], v[20:23]
	v_mfma_f32_16x16x32_bf16 v[16:19], v[152:155], v[188:191], v[16:19]
	v_mfma_f32_16x16x32_bf16 v[4:7], v[144:147], v[196:199], v[4:7]
	v_mfma_f32_16x16x32_bf16 v[0:3], v[152:155], v[196:199], v[0:3]
	v_mfma_f32_16x16x32_bf16 v[52:55], v[148:151], v[164:167], v[52:55]
	v_mfma_f32_16x16x32_bf16 v[48:51], v[156:159], v[164:167], v[48:51]
	v_mfma_f32_16x16x32_bf16 v[36:39], v[148:151], v[172:175], v[36:39]
	v_mfma_f32_16x16x32_bf16 v[32:35], v[156:159], v[172:175], v[32:35]
	v_mfma_f32_16x16x32_bf16 v[20:23], v[148:151], v[192:195], v[20:23]
	v_mfma_f32_16x16x32_bf16 v[16:19], v[156:159], v[192:195], v[16:19]
	v_mfma_f32_16x16x32_bf16 v[4:7], v[148:151], v[200:203], v[4:7]
	v_mfma_f32_16x16x32_bf16 v[0:3], v[156:159], v[200:203], v[0:3]
	s_barrier
	s_setprio 0
	s_add_i32 s93, 0, 0x18000
	s_add_i32 s94, 0, 0x1c000
	v_add_u32_e32 v140, s93, v209
	v_add_u32_e32 v156, s94, v209
	ds_read_b128 v[128:131], v140
	ds_read_b128 v[132:135], v140 offset:1024
	ds_read_b128 v[136:139], v140 offset:2048
	ds_read_b128 v[140:143], v140 offset:3072
	ds_read_b128 v[144:147], v156
	ds_read_b128 v[148:151], v156 offset:1024
	ds_read_b128 v[152:155], v156 offset:2048
	ds_read_b128 v[156:159], v156 offset:3072
	s_add_u32 s26, s34, 0x100000
	s_addc_u32 s27, s35, 0
	s_mov_b32 m0, s51
	v_lshl_add_u64 v[222:223], s[26:27], 0, v[176:177]
	ds_read_b128 v[160:163], v213 offset:32768
	ds_read_b128 v[164:167], v213 offset:33792
	ds_read_b128 v[168:171], v213 offset:34816
	ds_read_b128 v[172:175], v213 offset:35840
	ds_read_b128 v[188:191], v213 offset:36864
	ds_read_b128 v[192:195], v213 offset:37888
	ds_read_b128 v[196:199], v213 offset:38912
	ds_read_b128 v[200:203], v213 offset:39936
	global_load_lds_dwordx4 v[222:223], off
	v_lshl_add_u64 v[222:223], s[26:27], 0, v[178:179]
	s_mov_b32 m0, s76
	s_nop 0
	global_load_lds_dwordx4 v[222:223], off
	s_waitcnt vmcnt(8)
	s_waitcnt lgkmcnt(0)
	s_setprio 1
	s_barrier
	v_mfma_f32_16x16x32_bf16 v[124:127], v[128:131], v[160:163], v[124:127]
	v_mfma_f32_16x16x32_bf16 v[120:123], v[136:139], v[160:163], v[120:123]
	v_mfma_f32_16x16x32_bf16 v[108:111], v[128:131], v[168:171], v[108:111]
	v_mfma_f32_16x16x32_bf16 v[104:107], v[136:139], v[168:171], v[104:107]
	v_mfma_f32_16x16x32_bf16 v[92:95], v[128:131], v[188:191], v[92:95]
	v_mfma_f32_16x16x32_bf16 v[88:91], v[136:139], v[188:191], v[88:91]
	v_mfma_f32_16x16x32_bf16 v[76:79], v[128:131], v[196:199], v[76:79]
	v_mfma_f32_16x16x32_bf16 v[72:75], v[136:139], v[196:199], v[72:75]
	v_mfma_f32_16x16x32_bf16 v[124:127], v[132:135], v[164:167], v[124:127]
	v_mfma_f32_16x16x32_bf16 v[120:123], v[140:143], v[164:167], v[120:123]
	v_mfma_f32_16x16x32_bf16 v[108:111], v[132:135], v[172:175], v[108:111]
	v_mfma_f32_16x16x32_bf16 v[104:107], v[140:143], v[172:175], v[104:107]
	v_mfma_f32_16x16x32_bf16 v[92:95], v[132:135], v[192:195], v[92:95]
	v_mfma_f32_16x16x32_bf16 v[88:91], v[140:143], v[192:195], v[88:91]
	v_mfma_f32_16x16x32_bf16 v[76:79], v[132:135], v[200:203], v[76:79]
	v_mfma_f32_16x16x32_bf16 v[72:75], v[140:143], v[200:203], v[72:75]
	s_setprio 0
	s_setprio 1
	v_mfma_f32_16x16x32_bf16 v[116:119], v[144:147], v[160:163], v[116:119]
	v_mfma_f32_16x16x32_bf16 v[112:115], v[152:155], v[160:163], v[112:115]
	v_mfma_f32_16x16x32_bf16 v[100:103], v[144:147], v[168:171], v[100:103]
	v_mfma_f32_16x16x32_bf16 v[96:99], v[152:155], v[168:171], v[96:99]
	v_mfma_f32_16x16x32_bf16 v[84:87], v[144:147], v[188:191], v[84:87]
	v_mfma_f32_16x16x32_bf16 v[80:83], v[152:155], v[188:191], v[80:83]
	v_mfma_f32_16x16x32_bf16 v[68:71], v[144:147], v[196:199], v[68:71]
	v_mfma_f32_16x16x32_bf16 v[64:67], v[152:155], v[196:199], v[64:67]
	v_mfma_f32_16x16x32_bf16 v[116:119], v[148:151], v[164:167], v[116:119]
	v_mfma_f32_16x16x32_bf16 v[112:115], v[156:159], v[164:167], v[112:115]
	v_mfma_f32_16x16x32_bf16 v[100:103], v[148:151], v[172:175], v[100:103]
	v_mfma_f32_16x16x32_bf16 v[96:99], v[156:159], v[172:175], v[96:99]
	v_mfma_f32_16x16x32_bf16 v[84:87], v[148:151], v[192:195], v[84:87]
	v_mfma_f32_16x16x32_bf16 v[80:83], v[156:159], v[192:195], v[80:83]
	v_mfma_f32_16x16x32_bf16 v[68:71], v[148:151], v[200:203], v[68:71]
	v_mfma_f32_16x16x32_bf16 v[64:67], v[156:159], v[200:203], v[64:67]
	s_barrier
	s_setprio 0
	s_add_i32 s26, s93, s41
	v_lshl_add_u64 v[204:205], v[204:205], 0, s[10:11]
	s_mov_b32 m0, s26
	ds_read_b128 v[160:163], v213 offset:49152
	ds_read_b128 v[164:167], v213 offset:50176
	ds_read_b128 v[168:171], v213 offset:51200
	ds_read_b128 v[172:175], v213 offset:52224
	ds_read_b128 v[188:191], v213 offset:53248
	ds_read_b128 v[192:195], v213 offset:54272
	ds_read_b128 v[196:199], v213 offset:55296
	ds_read_b128 v[200:203], v213 offset:56320
	global_load_lds_dwordx4 v[204:205], off
	s_add_i32 m0, s26, 0x2000
	s_add_u32 s26, s30, 0x100080
	v_lshl_add_u64 v[204:205], v[216:217], 0, s[10:11]
	s_addc_u32 s27, s31, 0
	s_add_i32 s30, s94, s41
	global_load_lds_dwordx4 v[204:205], off
	v_lshl_add_u64 v[204:205], s[26:27], 0, v[176:177]
	s_mov_b32 m0, s30
	s_nop 0
	global_load_lds_dwordx4 v[204:205], off
	v_lshl_add_u64 v[204:205], s[26:27], 0, v[178:179]
	s_add_i32 m0, s30, 0x2000
	s_nop 0
	global_load_lds_dwordx4 v[204:205], off
	v_lshl_add_u64 v[204:205], v[218:219], 0, s[10:11]
	s_mov_b32 m0, s78
	s_nop 0
	global_load_lds_dwordx4 v[204:205], off
	v_lshl_add_u64 v[204:205], v[220:221], 0, s[10:11]
	s_mov_b32 m0, s79
	s_nop 0
	global_load_lds_dwordx4 v[204:205], off
	s_waitcnt vmcnt(8)
	s_waitcnt lgkmcnt(0)
	s_setprio 1
	s_barrier
	v_mfma_f32_16x16x32_bf16 v[60:63], v[128:131], v[160:163], v[60:63]
	v_mfma_f32_16x16x32_bf16 v[56:59], v[136:139], v[160:163], v[56:59]
	v_mfma_f32_16x16x32_bf16 v[44:47], v[128:131], v[168:171], v[44:47]
	v_mfma_f32_16x16x32_bf16 v[40:43], v[136:139], v[168:171], v[40:43]
	v_mfma_f32_16x16x32_bf16 v[28:31], v[128:131], v[188:191], v[28:31]
	v_mfma_f32_16x16x32_bf16 v[24:27], v[136:139], v[188:191], v[24:27]
	v_mfma_f32_16x16x32_bf16 v[12:15], v[128:131], v[196:199], v[12:15]
	v_mfma_f32_16x16x32_bf16 v[8:11], v[136:139], v[196:199], v[8:11]
	v_mfma_f32_16x16x32_bf16 v[60:63], v[132:135], v[164:167], v[60:63]
	v_mfma_f32_16x16x32_bf16 v[56:59], v[140:143], v[164:167], v[56:59]
	v_mfma_f32_16x16x32_bf16 v[44:47], v[132:135], v[172:175], v[44:47]
	v_mfma_f32_16x16x32_bf16 v[40:43], v[140:143], v[172:175], v[40:43]
	v_mfma_f32_16x16x32_bf16 v[28:31], v[132:135], v[192:195], v[28:31]
	v_mfma_f32_16x16x32_bf16 v[24:27], v[140:143], v[192:195], v[24:27]
	v_mfma_f32_16x16x32_bf16 v[12:15], v[132:135], v[200:203], v[12:15]
	v_mfma_f32_16x16x32_bf16 v[8:11], v[140:143], v[200:203], v[8:11]
	s_setprio 0
	s_setprio 1
	v_mfma_f32_16x16x32_bf16 v[52:55], v[144:147], v[160:163], v[52:55]
	v_mfma_f32_16x16x32_bf16 v[48:51], v[152:155], v[160:163], v[48:51]
	v_mfma_f32_16x16x32_bf16 v[36:39], v[144:147], v[168:171], v[36:39]
	v_mfma_f32_16x16x32_bf16 v[32:35], v[152:155], v[168:171], v[32:35]
	v_mfma_f32_16x16x32_bf16 v[20:23], v[144:147], v[188:191], v[20:23]
	v_mfma_f32_16x16x32_bf16 v[16:19], v[152:155], v[188:191], v[16:19]
	v_mfma_f32_16x16x32_bf16 v[4:7], v[144:147], v[196:199], v[4:7]
	v_mfma_f32_16x16x32_bf16 v[0:3], v[152:155], v[196:199], v[0:3]
	v_mfma_f32_16x16x32_bf16 v[52:55], v[148:151], v[164:167], v[52:55]
	v_mfma_f32_16x16x32_bf16 v[48:51], v[156:159], v[164:167], v[48:51]
	v_mfma_f32_16x16x32_bf16 v[36:39], v[148:151], v[172:175], v[36:39]
	v_mfma_f32_16x16x32_bf16 v[32:35], v[156:159], v[172:175], v[32:35]
	v_mfma_f32_16x16x32_bf16 v[20:23], v[148:151], v[192:195], v[20:23]
	v_mfma_f32_16x16x32_bf16 v[16:19], v[156:159], v[192:195], v[16:19]
	v_mfma_f32_16x16x32_bf16 v[4:7], v[148:151], v[200:203], v[4:7]
	v_mfma_f32_16x16x32_bf16 v[0:3], v[156:159], v[200:203], v[0:3]
	s_barrier
	s_setprio 0
	s_add_i32 s92, s92, 2
	s_add_u32 s90, s90, 0x100
	s_addc_u32 s91, s91, 0
	s_cmp_gt_u32 s92, 61
	s_mov_b64 s[26:27], s[28:29]
	s_cbranch_scc0 .LBB0_852
	s_and_b64 vcc, exec, s[12:13]
	s_cbranch_vccz .LBB0_855
	s_barrier

.LBB0_1010:
	s_lshl_b32 s3, s3, 5
	s_mov_b64 s[8:9], 0x80
	s_and_b32 s14, s3, 0x60
	s_add_i32 m0, s21, 0x18000
	v_lshl_add_u64 v[6:7], v[6:7], 0, s[8:9]
	s_lshl_b32 s11, s10, 13
	s_lshl_b32 s15, s14, 7
	s_mov_b32 s98, 1
	v_mov_b32_e32 v32, 0
	v_mov_b32_e32 v33, 0
	v_mov_b32_e32 v34, 0
	v_mov_b32_e32 v35, 0
	v_mov_b32_e32 v36, 0
	v_mov_b32_e32 v37, 0
	v_mov_b32_e32 v38, 0
	v_mov_b32_e32 v39, 0
	v_mov_b32_e32 v40, 0
	v_mov_b32_e32 v41, 0
	v_mov_b32_e32 v42, 0
	v_mov_b32_e32 v43, 0
	v_mov_b32_e32 v44, 0
	v_mov_b32_e32 v45, 0
	v_mov_b32_e32 v46, 0
	v_mov_b32_e32 v47, 0
	v_mov_b32_e32 v48, 0
	v_mov_b32_e32 v49, 0
	v_mov_b32_e32 v50, 0
	v_mov_b32_e32 v51, 0
	v_mov_b32_e32 v52, 0
	v_mov_b32_e32 v53, 0
	v_mov_b32_e32 v54, 0
	v_mov_b32_e32 v55, 0
	v_mov_b32_e32 v56, 0
	v_mov_b32_e32 v57, 0
	v_mov_b32_e32 v58, 0
	v_mov_b32_e32 v59, 0
	v_mov_b32_e32 v60, 0
	v_mov_b32_e32 v61, 0
	v_mov_b32_e32 v62, 0
	v_mov_b32_e32 v63, 0
	v_mov_b32_e32 v64, 0
	v_mov_b32_e32 v65, 0
	v_mov_b32_e32 v66, 0
	v_mov_b32_e32 v67, 0
	v_mov_b32_e32 v68, 0
	v_mov_b32_e32 v69, 0
	v_mov_b32_e32 v70, 0
	v_mov_b32_e32 v71, 0
	v_mov_b32_e32 v72, 0
	v_mov_b32_e32 v73, 0
	v_mov_b32_e32 v74, 0
	v_mov_b32_e32 v75, 0
	v_mov_b32_e32 v76, 0
	v_mov_b32_e32 v77, 0
	v_mov_b32_e32 v78, 0
	v_mov_b32_e32 v79, 0
	v_mov_b32_e32 v80, 0
	v_mov_b32_e32 v81, 0
	v_mov_b32_e32 v82, 0
	v_mov_b32_e32 v83, 0
	v_mov_b32_e32 v84, 0
	v_mov_b32_e32 v85, 0
	v_mov_b32_e32 v86, 0
	v_mov_b32_e32 v87, 0
	v_mov_b32_e32 v88, 0
	v_mov_b32_e32 v89, 0
	v_mov_b32_e32 v90, 0
	v_mov_b32_e32 v91, 0
	v_mov_b32_e32 v92, 0
	v_mov_b32_e32 v93, 0
	v_mov_b32_e32 v94, 0
	v_mov_b32_e32 v95, 0
	v_mov_b32_e32 v96, 0
	v_mov_b32_e32 v97, 0
	v_mov_b32_e32 v98, 0
	v_mov_b32_e32 v99, 0
	v_mov_b32_e32 v100, 0
	v_mov_b32_e32 v101, 0
	v_mov_b32_e32 v102, 0
	v_mov_b32_e32 v103, 0
	v_mov_b32_e32 v104, 0
	v_mov_b32_e32 v105, 0
	v_mov_b32_e32 v106, 0
	v_mov_b32_e32 v107, 0
	v_mov_b32_e32 v108, 0
	v_mov_b32_e32 v109, 0
	v_mov_b32_e32 v110, 0
	v_mov_b32_e32 v111, 0
	v_mov_b32_e32 v112, 0
	v_mov_b32_e32 v113, 0
	v_mov_b32_e32 v114, 0
	v_mov_b32_e32 v115, 0
	v_mov_b32_e32 v116, 0
	v_mov_b32_e32 v117, 0
	v_mov_b32_e32 v118, 0
	v_mov_b32_e32 v119, 0
	v_mov_b32_e32 v120, 0
	v_mov_b32_e32 v121, 0
	v_mov_b32_e32 v122, 0
	v_mov_b32_e32 v123, 0
	v_mov_b32_e32 v124, 0
	v_mov_b32_e32 v125, 0
	v_mov_b32_e32 v126, 0
	v_mov_b32_e32 v127, 0
	s_nop 0
	s_nop 0
	s_nop 0
	s_nop 0
	s_nop 0
	s_nop 0
	s_nop 0
	s_nop 0
	s_nop 0
	s_nop 0
	s_nop 0
	s_nop 0
	s_waitcnt vmcnt(2)
	s_barrier
	global_load_lds_dwordx4 v[6:7], off
	v_lshl_add_u64 v[4:5], v[4:5], 0, s[8:9]
	s_add_i32 m0, s21, 0x1a000
	s_add_i32 s40, s21, 0x8000
	s_add_i32 s41, s21, 0xa000
	global_load_lds_dwordx4 v[4:5], off
	v_lshl_add_u64 v[0:1], v[0:1], 0, s[8:9]
	s_mov_b32 m0, s40
	s_add_u32 s12, s24, 0x40080
	global_load_lds_dwordx4 v[0:1], off
	v_lshl_add_u64 v[0:1], v[2:3], 0, s[8:9]
	s_mov_b32 m0, s41
	s_addc_u32 s13, s25, 0
	global_load_lds_dwordx4 v[0:1], off
	s_add_i32 m0, s21, 0x1c000
	v_lshl_add_u64 v[0:1], s[12:13], 0, v[132:133]
	global_load_lds_dwordx4 v[0:1], off
	v_lshl_add_u64 v[0:1], s[12:13], 0, v[128:129]
	s_add_i32 m0, s21, 0x1e000
	s_cmpk_lt_u32 s1, 0x100
	global_load_lds_dwordx4 v[0:1], off
	v_lshrrev_b32_e32 v1, 1, v9
	v_and_b32_e32 v1, 24, v1
	v_and_b32_e32 v0, 15, v9
	v_lshlrev_b32_e32 v2, 1, v1
	v_lshl_or_b32 v148, s10, 6, v0
	v_lshl_or_b32 v0, v0, 6, v2
	v_lshlrev_b32_e32 v2, 2, v9
	v_and_b32_e32 v2, 32, v2
	v_bitop3_b32 v3, v0, s11, v2 bitop3:0xde
	v_bitop3_b32 v149, v0, s15, v2 bitop3:0xde
	v_lshlrev_b32_e32 v0, 14, v13
	v_and_b32_e32 v0, 0xffff8000, v0
	v_or_b32_e32 v150, s14, v1
	v_lshl_add_u32 v0, v12, 11, v0
	v_and_b32_e32 v1, 1, v13
	v_lshl_or_b32 v0, v1, 6, v0
	v_lshl_add_u32 v136, v14, 1, v0
	v_lshlrev_b32_e32 v0, 14, v8
	v_and_b32_e32 v0, 0xffff8000, v0
	s_waitcnt vmcnt(6)
	v_lshl_add_u32 v0, v10, 11, v0
	v_and_b32_e32 v1, 1, v8
	s_cselect_b64 s[10:11], -1, 0
	v_lshl_or_b32 v0, v1, 6, v0
	s_add_i32 s43, 0, 0x10000
	s_add_i32 s44, 0, 0x14000
	s_sext_i32_i8 s3, s0
	s_ashr_i32 s42, s29, 31
	v_mov_b32_e32 v137, v133
	v_lshl_add_u32 v138, v11, 1, v0
	v_mov_b32_e32 v139, v133
	v_mov_b64_e32 v[140:141], 0x300
	v_mov_b64_e32 v[142:143], 0x2ff
	v_add_u32_e32 v151, s43, v149
	v_add_u32_e32 v152, s44, v149
	v_add_u32_e32 v153, 0, v3
	v_mov_b32_e32 v154, 0x358637bd
	s_movk_i32 s45, 0x1800
	v_mov_b32_e32 v155, 0x3e38aa3b
	s_barrier
	s_branch .LBB0_1013

.LBB0_1015:
	s_ashr_i32 s15, s14, 31
	s_lshl_b64 s[16:17], s[14:15], 19
	s_add_u32 s16, s82, s16
	s_addc_u32 s17, s83, s17
	s_and_b64 s[18:19], s[0:1], exec
	s_cselect_b32 s15, s17, s23
	s_cselect_b32 s48, s16, s22
	s_ashr_i32 s13, s12, 31
	s_lshl_b64 s[18:19], s[12:13], 19
	s_add_u32 s18, s30, s18
	s_addc_u32 s19, s31, s19
	s_and_b64 s[26:27], s[0:1], exec
	s_cselect_b32 s13, s19, s25
	s_cselect_b32 s49, s18, s24
	s_add_u32 s22, s22, 0x40080
	s_addc_u32 s23, s23, 0
	s_add_u32 s50, s24, 0x100
	v_mov_b32_e32 v0, 0
	s_addc_u32 s51, s25, 0
	s_mov_b32 s52, -2
	v_mov_b32_e32 v1, v0
	v_mov_b32_e32 v2, v0
	v_mov_b32_e32 v3, v0
	v_mov_b32_e32 v4, v0
	v_mov_b32_e32 v5, v0
	v_mov_b32_e32 v6, v0
	v_mov_b32_e32 v7, v0
	s_nop 0
	v_mov_b32_e32 v8, v0
	v_mov_b32_e32 v9, v0
	v_mov_b32_e32 v10, v0
	v_mov_b32_e32 v11, v0
	v_mov_b32_e32 v12, v0
	v_mov_b32_e32 v13, v0
	v_mov_b32_e32 v14, v0
	v_mov_b32_e32 v15, v0
	v_mov_b32_e32 v16, v0
	v_mov_b32_e32 v17, v0
	v_mov_b32_e32 v18, v0
	v_mov_b32_e32 v19, v0
	v_mov_b32_e32 v20, v0
	v_mov_b32_e32 v21, v0
	v_mov_b32_e32 v22, v0
	v_mov_b32_e32 v23, v0
	v_mov_b32_e32 v24, v0
	v_mov_b32_e32 v25, v0
	v_mov_b32_e32 v26, v0
	v_mov_b32_e32 v27, v0
	v_mov_b32_e32 v28, v0
	v_mov_b32_e32 v29, v0
	v_mov_b32_e32 v30, v0
	v_mov_b32_e32 v31, v0
	s_cmp_eq_u32 s98, 1
	s_mov_b32 s98, 0
	s_cbranch_scc1 .Lzskip_5
	v_mov_b32_e32 v32, v0
	v_mov_b32_e32 v33, v0
	v_mov_b32_e32 v34, v0
	v_mov_b32_e32 v35, v0
	v_mov_b32_e32 v36, v0
	v_mov_b32_e32 v37, v0
	v_mov_b32_e32 v38, v0
	v_mov_b32_e32 v39, v0
	v_mov_b32_e32 v40, v0
	v_mov_b32_e32 v41, v0
	v_mov_b32_e32 v42, v0
	v_mov_b32_e32 v43, v0
	v_mov_b32_e32 v44, v0
	v_mov_b32_e32 v45, v0
	v_mov_b32_e32 v46, v0
	v_mov_b32_e32 v47, v0
	v_mov_b32_e32 v48, v0
	v_mov_b32_e32 v49, v0
	v_mov_b32_e32 v50, v0
	v_mov_b32_e32 v51, v0
	v_mov_b32_e32 v52, v0
	v_mov_b32_e32 v53, v0
	v_mov_b32_e32 v54, v0
	v_mov_b32_e32 v55, v0
	v_mov_b32_e32 v56, v0
	v_mov_b32_e32 v57, v0
	v_mov_b32_e32 v58, v0
	v_mov_b32_e32 v59, v0
	v_mov_b32_e32 v60, v0
	v_mov_b32_e32 v61, v0
	v_mov_b32_e32 v62, v0
	v_mov_b32_e32 v63, v0
	v_mov_b32_e32 v64, v0
	v_mov_b32_e32 v65, v0
	v_mov_b32_e32 v66, v0
	v_mov_b32_e32 v67, v0
	v_mov_b32_e32 v68, v0
	v_mov_b32_e32 v69, v0
	v_mov_b32_e32 v70, v0
	v_mov_b32_e32 v71, v0
	v_mov_b32_e32 v72, v0
	v_mov_b32_e32 v73, v0
	v_mov_b32_e32 v74, v0
	v_mov_b32_e32 v75, v0
	v_mov_b32_e32 v76, v0
	v_mov_b32_e32 v77, v0
	v_mov_b32_e32 v78, v0
	v_mov_b32_e32 v79, v0
	v_mov_b32_e32 v80, v0
	v_mov_b32_e32 v81, v0
	v_mov_b32_e32 v82, v0
	v_mov_b32_e32 v83, v0
	v_mov_b32_e32 v84, v0
	v_mov_b32_e32 v85, v0
	v_mov_b32_e32 v86, v0
	v_mov_b32_e32 v87, v0
	v_mov_b32_e32 v88, v0
	v_mov_b32_e32 v89, v0
	v_mov_b32_e32 v90, v0
	v_mov_b32_e32 v91, v0
	v_mov_b32_e32 v92, v0
	v_mov_b32_e32 v93, v0
	v_mov_b32_e32 v94, v0
	v_mov_b32_e32 v95, v0
	v_mov_b32_e32 v96, v0
	v_mov_b32_e32 v97, v0
	v_mov_b32_e32 v98, v0
	v_mov_b32_e32 v99, v0
	v_mov_b32_e32 v100, v0
	v_mov_b32_e32 v101, v0
	v_mov_b32_e32 v102, v0
	v_mov_b32_e32 v103, v0
	v_mov_b32_e32 v104, v0
	v_mov_b32_e32 v105, v0
	v_mov_b32_e32 v106, v0
	v_mov_b32_e32 v107, v0
	v_mov_b32_e32 v108, v0
	v_mov_b32_e32 v109, v0
	v_mov_b32_e32 v110, v0
	v_mov_b32_e32 v111, v0
	v_mov_b32_e32 v112, v0
	v_mov_b32_e32 v113, v0
	v_mov_b32_e32 v114, v0
	v_mov_b32_e32 v115, v0
	v_mov_b32_e32 v116, v0
	v_mov_b32_e32 v117, v0
	v_mov_b32_e32 v118, v0
	v_mov_b32_e32 v119, v0
	v_mov_b32_e32 v120, v0
	v_mov_b32_e32 v121, v0
	v_mov_b32_e32 v122, v0
	v_mov_b32_e32 v123, v0
	v_mov_b32_e32 v124, v0
	v_mov_b32_e32 v125, v0
	v_mov_b32_e32 v126, v0
	v_mov_b32_e32 v127, v0
.Lzskip_5:
.LBB0_1016:
	ds_read_b128 v[144:147], v151
	ds_read_b128 v[156:159], v151 offset:1024
	ds_read_b128 v[160:163], v151 offset:2048
	ds_read_b128 v[164:167], v151 offset:3072
	ds_read_b128 v[168:171], v152
	ds_read_b128 v[172:175], v152 offset:1024
	ds_read_b128 v[176:179], v152 offset:2048
	ds_read_b128 v[180:183], v152 offset:3072
	s_add_u32 s24, s22, 0xfffc0080
	s_addc_u32 s25, s23, -1
	s_cmp_eq_u32 s52, 12
	s_cselect_b32 s27, s15, s25
	s_cselect_b32 s26, s48, s24
	s_cselect_b32 s25, s13, s51
	s_cselect_b32 s24, s49, s50
	v_lshl_add_u64 v[204:205], s[22:23], 0, v[136:137]
	s_add_i32 m0, s21, 0xc000
	ds_read_b128 v[184:187], v153
	ds_read_b128 v[188:191], v153 offset:1024
	ds_read_b128 v[192:195], v153 offset:2048
	ds_read_b128 v[196:199], v153 offset:3072
	ds_read_b128 v[200:203], v153 offset:4096
	ds_read_b128 v[208:211], v153 offset:5120
	ds_read_b128 v[212:215], v153 offset:6144
	ds_read_b128 v[216:219], v153 offset:7168
	global_load_lds_dwordx4 v[204:205], off
	v_lshl_add_u64 v[204:205], s[22:23], 0, v[138:139]
	s_add_i32 m0, s21, 0xe000
	s_nop 0
	global_load_lds_dwordx4 v[204:205], off
	s_waitcnt vmcnt(8)
	s_waitcnt lgkmcnt(0)
	s_setprio 1
	s_barrier
	v_mfma_f32_16x16x32_bf16 v[124:127], v[144:147], v[184:187], v[124:127]
	v_mfma_f32_16x16x32_bf16 v[120:123], v[160:163], v[184:187], v[120:123]
	v_mfma_f32_16x16x32_bf16 v[116:119], v[144:147], v[192:195], v[116:119]
	v_mfma_f32_16x16x32_bf16 v[112:115], v[160:163], v[192:195], v[112:115]
	v_mfma_f32_16x16x32_bf16 v[104:107], v[144:147], v[200:203], v[104:107]
	v_mfma_f32_16x16x32_bf16 v[96:99], v[160:163], v[200:203], v[96:99]
	v_mfma_f32_16x16x32_bf16 v[76:79], v[144:147], v[212:215], v[76:79]
	v_mfma_f32_16x16x32_bf16 v[72:75], v[160:163], v[212:215], v[72:75]
	v_mfma_f32_16x16x32_bf16 v[124:127], v[156:159], v[188:191], v[124:127]
	v_mfma_f32_16x16x32_bf16 v[120:123], v[164:167], v[188:191], v[120:123]
	v_mfma_f32_16x16x32_bf16 v[116:119], v[156:159], v[196:199], v[116:119]
	v_mfma_f32_16x16x32_bf16 v[112:115], v[164:167], v[196:199], v[112:115]
	v_mfma_f32_16x16x32_bf16 v[104:107], v[156:159], v[208:211], v[104:107]
	v_mfma_f32_16x16x32_bf16 v[96:99], v[164:167], v[208:211], v[96:99]
	v_mfma_f32_16x16x32_bf16 v[76:79], v[156:159], v[216:219], v[76:79]
	v_mfma_f32_16x16x32_bf16 v[72:75], v[164:167], v[216:219], v[72:75]
	s_setprio 0
	s_setprio 1
	v_mfma_f32_16x16x32_bf16 v[108:111], v[168:171], v[184:187], v[108:111]
	v_mfma_f32_16x16x32_bf16 v[100:103], v[176:179], v[184:187], v[100:103]
	v_mfma_f32_16x16x32_bf16 v[92:95], v[168:171], v[192:195], v[92:95]
	v_mfma_f32_16x16x32_bf16 v[88:91], v[176:179], v[192:195], v[88:91]
	v_mfma_f32_16x16x32_bf16 v[84:87], v[168:171], v[200:203], v[84:87]
	v_mfma_f32_16x16x32_bf16 v[80:83], v[176:179], v[200:203], v[80:83]
	v_mfma_f32_16x16x32_bf16 v[68:71], v[168:171], v[212:215], v[68:71]
	v_mfma_f32_16x16x32_bf16 v[64:67], v[176:179], v[212:215], v[64:67]
	v_mfma_f32_16x16x32_bf16 v[108:111], v[172:175], v[188:191], v[108:111]
	v_mfma_f32_16x16x32_bf16 v[100:103], v[180:183], v[188:191], v[100:103]
	v_mfma_f32_16x16x32_bf16 v[92:95], v[172:175], v[196:199], v[92:95]
	v_mfma_f32_16x16x32_bf16 v[88:91], v[180:183], v[196:199], v[88:91]
	v_mfma_f32_16x16x32_bf16 v[84:87], v[172:175], v[208:211], v[84:87]
	v_mfma_f32_16x16x32_bf16 v[80:83], v[180:183], v[208:211], v[80:83]
	v_mfma_f32_16x16x32_bf16 v[68:71], v[172:175], v[216:219], v[68:71]
	v_mfma_f32_16x16x32_bf16 v[64:67], v[180:183], v[216:219], v[64:67]
	s_barrier
	s_setprio 0
	s_add_i32 s53, s43, s33
	v_lshl_add_u64 v[204:205], s[24:25], 0, v[132:133]
	s_mov_b32 m0, s53
	ds_read_b128 v[184:187], v153 offset:16384
	ds_read_b128 v[188:191], v153 offset:17408
	ds_read_b128 v[192:195], v153 offset:18432
	ds_read_b128 v[196:199], v153 offset:19456
	ds_read_b128 v[200:203], v153 offset:20480
	ds_read_b128 v[208:211], v153 offset:21504
	ds_read_b128 v[212:215], v153 offset:22528
	ds_read_b128 v[216:219], v153 offset:23552
	global_load_lds_dwordx4 v[204:205], off
	s_add_i32 m0, s53, 0x2000
	s_add_u32 s54, s24, 0x40000
	v_lshl_add_u64 v[220:221], s[24:25], 0, v[128:129]
	s_addc_u32 s55, s25, 0
	s_add_i32 s53, s44, s33
	global_load_lds_dwordx4 v[220:221], off
	v_lshl_add_u64 v[222:223], s[54:55], 0, v[132:133]
	s_mov_b32 m0, s53
	v_lshl_add_u64 v[224:225], s[26:27], 0, v[130:131]
	global_load_lds_dwordx4 v[222:223], off
	v_lshl_add_u64 v[222:223], s[54:55], 0, v[128:129]
	s_add_i32 m0, s53, 0x2000
	s_nop 0
	global_load_lds_dwordx4 v[222:223], off
	v_lshl_add_u64 v[222:223], s[26:27], 0, v[134:135]
	s_mov_b32 m0, s21
	s_nop 0
	global_load_lds_dwordx4 v[222:223], off
	s_mov_b32 m0, s36
	s_nop 0
	global_load_lds_dwordx4 v[224:225], off
	s_waitcnt vmcnt(8)
	s_waitcnt lgkmcnt(0)
	s_setprio 1
	s_barrier
	v_mfma_f32_16x16x32_bf16 v[60:63], v[144:147], v[184:187], v[60:63]
	v_mfma_f32_16x16x32_bf16 v[56:59], v[160:163], v[184:187], v[56:59]
	v_mfma_f32_16x16x32_bf16 v[44:47], v[144:147], v[192:195], v[44:47]
	v_mfma_f32_16x16x32_bf16 v[40:43], v[160:163], v[192:195], v[40:43]
	v_mfma_f32_16x16x32_bf16 v[28:31], v[144:147], v[200:203], v[28:31]
	v_mfma_f32_16x16x32_bf16 v[24:27], v[160:163], v[200:203], v[24:27]
	v_mfma_f32_16x16x32_bf16 v[12:15], v[144:147], v[212:215], v[12:15]
	v_mfma_f32_16x16x32_bf16 v[8:11], v[160:163], v[212:215], v[8:11]
	v_mfma_f32_16x16x32_bf16 v[60:63], v[156:159], v[188:191], v[60:63]
	v_mfma_f32_16x16x32_bf16 v[56:59], v[164:167], v[188:191], v[56:59]
	v_mfma_f32_16x16x32_bf16 v[44:47], v[156:159], v[196:199], v[44:47]
	v_mfma_f32_16x16x32_bf16 v[40:43], v[164:167], v[196:199], v[40:43]
	v_mfma_f32_16x16x32_bf16 v[28:31], v[156:159], v[208:211], v[28:31]
	v_mfma_f32_16x16x32_bf16 v[24:27], v[164:167], v[208:211], v[24:27]
	v_mfma_f32_16x16x32_bf16 v[12:15], v[156:159], v[216:219], v[12:15]
	v_mfma_f32_16x16x32_bf16 v[8:11], v[164:167], v[216:219], v[8:11]
	s_setprio 0
	s_setprio 1
	v_mfma_f32_16x16x32_bf16 v[52:55], v[168:171], v[184:187], v[52:55]
	v_mfma_f32_16x16x32_bf16 v[48:51], v[176:179], v[184:187], v[48:51]
	v_mfma_f32_16x16x32_bf16 v[36:39], v[168:171], v[192:195], v[36:39]
	v_mfma_f32_16x16x32_bf16 v[32:35], v[176:179], v[192:195], v[32:35]
	v_mfma_f32_16x16x32_bf16 v[20:23], v[168:171], v[200:203], v[20:23]
	v_mfma_f32_16x16x32_bf16 v[16:19], v[176:179], v[200:203], v[16:19]
	v_mfma_f32_16x16x32_bf16 v[4:7], v[168:171], v[212:215], v[4:7]
	v_mfma_f32_16x16x32_bf16 v[0:3], v[176:179], v[212:215], v[0:3]
	v_mfma_f32_16x16x32_bf16 v[52:55], v[172:175], v[188:191], v[52:55]
	v_mfma_f32_16x16x32_bf16 v[48:51], v[180:183], v[188:191], v[48:51]
	v_mfma_f32_16x16x32_bf16 v[36:39], v[172:175], v[196:199], v[36:39]
	v_mfma_f32_16x16x32_bf16 v[32:35], v[180:183], v[196:199], v[32:35]
	v_mfma_f32_16x16x32_bf16 v[20:23], v[172:175], v[208:211], v[20:23]
	v_mfma_f32_16x16x32_bf16 v[16:19], v[180:183], v[208:211], v[16:19]
	v_mfma_f32_16x16x32_bf16 v[4:7], v[172:175], v[216:219], v[4:7]
	v_mfma_f32_16x16x32_bf16 v[0:3], v[180:183], v[216:219], v[0:3]
	s_barrier
	s_setprio 0
	s_add_i32 s53, 0, 0x18000
	s_add_i32 s54, 0, 0x1c000
	v_add_u32_e32 v164, s53, v149
	v_add_u32_e32 v180, s54, v149
	ds_read_b128 v[144:147], v164
	ds_read_b128 v[156:159], v164 offset:1024
	ds_read_b128 v[160:163], v164 offset:2048
	ds_read_b128 v[164:167], v164 offset:3072
	ds_read_b128 v[168:171], v180
	ds_read_b128 v[172:175], v180 offset:1024
	ds_read_b128 v[176:179], v180 offset:2048
	ds_read_b128 v[180:183], v180 offset:3072
	s_add_u32 s26, s26, 0x40000
	s_addc_u32 s27, s27, 0
	s_mov_b32 m0, s37
	v_lshl_add_u64 v[226:227], s[26:27], 0, v[134:135]
	ds_read_b128 v[184:187], v153 offset:32768
	ds_read_b128 v[188:191], v153 offset:33792
	ds_read_b128 v[192:195], v153 offset:34816
	ds_read_b128 v[196:199], v153 offset:35840
	ds_read_b128 v[200:203], v153 offset:36864
	ds_read_b128 v[208:211], v153 offset:37888
	ds_read_b128 v[212:215], v153 offset:38912
	ds_read_b128 v[216:219], v153 offset:39936
	global_load_lds_dwordx4 v[226:227], off
	v_lshl_add_u64 v[226:227], s[26:27], 0, v[130:131]
	s_mov_b32 m0, s38
	s_nop 0
	global_load_lds_dwordx4 v[226:227], off
	s_waitcnt vmcnt(8)
	s_waitcnt lgkmcnt(0)
	s_setprio 1
	s_barrier
	v_mfma_f32_16x16x32_bf16 v[124:127], v[144:147], v[184:187], v[124:127]
	v_mfma_f32_16x16x32_bf16 v[120:123], v[160:163], v[184:187], v[120:123]
	v_mfma_f32_16x16x32_bf16 v[116:119], v[144:147], v[192:195], v[116:119]
	v_mfma_f32_16x16x32_bf16 v[112:115], v[160:163], v[192:195], v[112:115]
	v_mfma_f32_16x16x32_bf16 v[104:107], v[144:147], v[200:203], v[104:107]
	v_mfma_f32_16x16x32_bf16 v[96:99], v[160:163], v[200:203], v[96:99]
	v_mfma_f32_16x16x32_bf16 v[76:79], v[144:147], v[212:215], v[76:79]
	v_mfma_f32_16x16x32_bf16 v[72:75], v[160:163], v[212:215], v[72:75]
	v_mfma_f32_16x16x32_bf16 v[124:127], v[156:159], v[188:191], v[124:127]
	v_mfma_f32_16x16x32_bf16 v[120:123], v[164:167], v[188:191], v[120:123]
	v_mfma_f32_16x16x32_bf16 v[116:119], v[156:159], v[196:199], v[116:119]
	v_mfma_f32_16x16x32_bf16 v[112:115], v[164:167], v[196:199], v[112:115]
	v_mfma_f32_16x16x32_bf16 v[104:107], v[156:159], v[208:211], v[104:107]
	v_mfma_f32_16x16x32_bf16 v[96:99], v[164:167], v[208:211], v[96:99]
	v_mfma_f32_16x16x32_bf16 v[76:79], v[156:159], v[216:219], v[76:79]
	v_mfma_f32_16x16x32_bf16 v[72:75], v[164:167], v[216:219], v[72:75]
	s_setprio 0
	s_setprio 1
	v_mfma_f32_16x16x32_bf16 v[108:111], v[168:171], v[184:187], v[108:111]
	v_mfma_f32_16x16x32_bf16 v[100:103], v[176:179], v[184:187], v[100:103]
	v_mfma_f32_16x16x32_bf16 v[92:95], v[168:171], v[192:195], v[92:95]
	v_mfma_f32_16x16x32_bf16 v[88:91], v[176:179], v[192:195], v[88:91]
	v_mfma_f32_16x16x32_bf16 v[84:87], v[168:171], v[200:203], v[84:87]
	v_mfma_f32_16x16x32_bf16 v[80:83], v[176:179], v[200:203], v[80:83]
	v_mfma_f32_16x16x32_bf16 v[68:71], v[168:171], v[212:215], v[68:71]
	v_mfma_f32_16x16x32_bf16 v[64:67], v[176:179], v[212:215], v[64:67]
	v_mfma_f32_16x16x32_bf16 v[108:111], v[172:175], v[188:191], v[108:111]
	v_mfma_f32_16x16x32_bf16 v[100:103], v[180:183], v[188:191], v[100:103]
	v_mfma_f32_16x16x32_bf16 v[92:95], v[172:175], v[196:199], v[92:95]
	v_mfma_f32_16x16x32_bf16 v[88:91], v[180:183], v[196:199], v[88:91]
	v_mfma_f32_16x16x32_bf16 v[84:87], v[172:175], v[208:211], v[84:87]
	v_mfma_f32_16x16x32_bf16 v[80:83], v[180:183], v[208:211], v[80:83]
	v_mfma_f32_16x16x32_bf16 v[68:71], v[172:175], v[216:219], v[68:71]
	v_mfma_f32_16x16x32_bf16 v[64:67], v[180:183], v[216:219], v[64:67]
	s_barrier
	s_setprio 0
	s_add_i32 s26, s53, s33
	v_lshl_add_u64 v[204:205], v[204:205], 0, s[8:9]
	s_mov_b32 m0, s26
	ds_read_b128 v[184:187], v153 offset:49152
	ds_read_b128 v[188:191], v153 offset:50176
	ds_read_b128 v[192:195], v153 offset:51200
	ds_read_b128 v[196:199], v153 offset:52224
	ds_read_b128 v[200:203], v153 offset:53248
	ds_read_b128 v[208:211], v153 offset:54272
	ds_read_b128 v[212:215], v153 offset:55296
	ds_read_b128 v[216:219], v153 offset:56320
	global_load_lds_dwordx4 v[204:205], off
	s_add_i32 m0, s26, 0x2000
	s_add_u32 s24, s24, 0x40080
	v_lshl_add_u64 v[204:205], v[220:221], 0, s[8:9]
	s_addc_u32 s25, s25, 0
	s_add_i32 s26, s54, s33
	global_load_lds_dwordx4 v[204:205], off
	v_lshl_add_u64 v[204:205], s[24:25], 0, v[132:133]
	s_mov_b32 m0, s26
	s_nop 0
	global_load_lds_dwordx4 v[204:205], off
	v_lshl_add_u64 v[204:205], s[24:25], 0, v[128:129]
	s_add_i32 m0, s26, 0x2000
	s_nop 0
	global_load_lds_dwordx4 v[204:205], off
	v_lshl_add_u64 v[204:205], v[222:223], 0, s[8:9]
	s_mov_b32 m0, s40
	s_nop 0
	global_load_lds_dwordx4 v[204:205], off
	v_lshl_add_u64 v[204:205], v[224:225], 0, s[8:9]
	s_mov_b32 m0, s41
	s_nop 0
	global_load_lds_dwordx4 v[204:205], off
	s_waitcnt vmcnt(8)
	s_waitcnt lgkmcnt(0)
	s_setprio 1
	s_barrier
	v_mfma_f32_16x16x32_bf16 v[60:63], v[144:147], v[184:187], v[60:63]
	v_mfma_f32_16x16x32_bf16 v[56:59], v[160:163], v[184:187], v[56:59]
	v_mfma_f32_16x16x32_bf16 v[44:47], v[144:147], v[192:195], v[44:47]
	v_mfma_f32_16x16x32_bf16 v[40:43], v[160:163], v[192:195], v[40:43]
	v_mfma_f32_16x16x32_bf16 v[28:31], v[144:147], v[200:203], v[28:31]
	v_mfma_f32_16x16x32_bf16 v[24:27], v[160:163], v[200:203], v[24:27]
	v_mfma_f32_16x16x32_bf16 v[12:15], v[144:147], v[212:215], v[12:15]
	v_mfma_f32_16x16x32_bf16 v[8:11], v[160:163], v[212:215], v[8:11]
	v_mfma_f32_16x16x32_bf16 v[60:63], v[156:159], v[188:191], v[60:63]
	v_mfma_f32_16x16x32_bf16 v[56:59], v[164:167], v[188:191], v[56:59]
	v_mfma_f32_16x16x32_bf16 v[44:47], v[156:159], v[196:199], v[44:47]
	v_mfma_f32_16x16x32_bf16 v[40:43], v[164:167], v[196:199], v[40:43]
	v_mfma_f32_16x16x32_bf16 v[28:31], v[156:159], v[208:211], v[28:31]
	v_mfma_f32_16x16x32_bf16 v[24:27], v[164:167], v[208:211], v[24:27]
	v_mfma_f32_16x16x32_bf16 v[12:15], v[156:159], v[216:219], v[12:15]
	v_mfma_f32_16x16x32_bf16 v[8:11], v[164:167], v[216:219], v[8:11]
	s_setprio 0
	s_setprio 1
	v_mfma_f32_16x16x32_bf16 v[52:55], v[168:171], v[184:187], v[52:55]
	v_mfma_f32_16x16x32_bf16 v[48:51], v[176:179], v[184:187], v[48:51]
	v_mfma_f32_16x16x32_bf16 v[36:39], v[168:171], v[192:195], v[36:39]
	v_mfma_f32_16x16x32_bf16 v[32:35], v[176:179], v[192:195], v[32:35]
	v_mfma_f32_16x16x32_bf16 v[20:23], v[168:171], v[200:203], v[20:23]
	v_mfma_f32_16x16x32_bf16 v[16:19], v[176:179], v[200:203], v[16:19]
	v_mfma_f32_16x16x32_bf16 v[4:7], v[168:171], v[212:215], v[4:7]
	v_mfma_f32_16x16x32_bf16 v[0:3], v[176:179], v[212:215], v[0:3]
	v_mfma_f32_16x16x32_bf16 v[52:55], v[172:175], v[188:191], v[52:55]
	v_mfma_f32_16x16x32_bf16 v[48:51], v[180:183], v[188:191], v[48:51]
	v_mfma_f32_16x16x32_bf16 v[36:39], v[172:175], v[196:199], v[36:39]
	v_mfma_f32_16x16x32_bf16 v[32:35], v[180:183], v[196:199], v[32:35]
	v_mfma_f32_16x16x32_bf16 v[20:23], v[172:175], v[208:211], v[20:23]
	v_mfma_f32_16x16x32_bf16 v[16:19], v[180:183], v[208:211], v[16:19]
	v_mfma_f32_16x16x32_bf16 v[4:7], v[172:175], v[216:219], v[4:7]
	v_mfma_f32_16x16x32_bf16 v[0:3], v[180:183], v[216:219], v[0:3]
	s_barrier
	s_setprio 0
	s_add_i32 s52, s52, 2
	s_add_u32 s22, s22, 0x100
	s_addc_u32 s23, s23, 0
	s_add_u32 s50, s50, 0x100
	s_addc_u32 s51, s51, 0
	s_cmp_gt_u32 s52, 13
	s_cbranch_scc0 .LBB0_1016
	s_and_b64 vcc, exec, s[10:11]
	s_cbranch_vccz .LBB0_1019
	s_barrier

.LBB0_1208:
	s_lshl_b32 s1, s1, 5
	s_mov_b64 s[10:11], 0x80
	s_and_b32 s14, s1, 0x60
	s_add_i32 m0, s25, 0x18000
	v_lshl_add_u64 v[6:7], v[6:7], 0, s[10:11]
	s_lshl_b32 s12, s0, 13
	s_lshl_b32 s1, s14, 7
	s_mov_b32 s98, 1
	v_mov_b32_e32 v32, 0
	v_mov_b32_e32 v33, 0
	v_mov_b32_e32 v34, 0
	v_mov_b32_e32 v35, 0
	v_mov_b32_e32 v36, 0
	v_mov_b32_e32 v37, 0
	v_mov_b32_e32 v38, 0
	v_mov_b32_e32 v39, 0
	v_mov_b32_e32 v40, 0
	v_mov_b32_e32 v41, 0
	v_mov_b32_e32 v42, 0
	v_mov_b32_e32 v43, 0
	v_mov_b32_e32 v44, 0
	v_mov_b32_e32 v45, 0
	v_mov_b32_e32 v46, 0
	v_mov_b32_e32 v47, 0
	v_mov_b32_e32 v48, 0
	v_mov_b32_e32 v49, 0
	v_mov_b32_e32 v50, 0
	v_mov_b32_e32 v51, 0
	v_mov_b32_e32 v52, 0
	v_mov_b32_e32 v53, 0
	v_mov_b32_e32 v54, 0
	v_mov_b32_e32 v55, 0
	v_mov_b32_e32 v56, 0
	v_mov_b32_e32 v57, 0
	v_mov_b32_e32 v58, 0
	v_mov_b32_e32 v59, 0
	v_mov_b32_e32 v60, 0
	v_mov_b32_e32 v61, 0
	v_mov_b32_e32 v62, 0
	v_mov_b32_e32 v63, 0
	v_mov_b32_e32 v64, 0
	v_mov_b32_e32 v65, 0
	v_mov_b32_e32 v66, 0
	v_mov_b32_e32 v67, 0
	v_mov_b32_e32 v68, 0
	v_mov_b32_e32 v69, 0
	v_mov_b32_e32 v70, 0
	v_mov_b32_e32 v71, 0
	v_mov_b32_e32 v72, 0
	v_mov_b32_e32 v73, 0
	v_mov_b32_e32 v74, 0
	v_mov_b32_e32 v75, 0
	v_mov_b32_e32 v76, 0
	v_mov_b32_e32 v77, 0
	v_mov_b32_e32 v78, 0
	v_mov_b32_e32 v79, 0
	v_mov_b32_e32 v80, 0
	v_mov_b32_e32 v81, 0
	v_mov_b32_e32 v82, 0
	v_mov_b32_e32 v83, 0
	v_mov_b32_e32 v84, 0
	v_mov_b32_e32 v85, 0
	v_mov_b32_e32 v86, 0
	v_mov_b32_e32 v87, 0
	v_mov_b32_e32 v88, 0
	v_mov_b32_e32 v89, 0
	v_mov_b32_e32 v90, 0
	v_mov_b32_e32 v91, 0
	v_mov_b32_e32 v92, 0
	v_mov_b32_e32 v93, 0
	v_mov_b32_e32 v94, 0
	v_mov_b32_e32 v95, 0
	v_mov_b32_e32 v96, 0
	v_mov_b32_e32 v97, 0
	v_mov_b32_e32 v98, 0
	v_mov_b32_e32 v99, 0
	v_mov_b32_e32 v100, 0
	v_mov_b32_e32 v101, 0
	v_mov_b32_e32 v102, 0
	v_mov_b32_e32 v103, 0
	v_mov_b32_e32 v104, 0
	v_mov_b32_e32 v105, 0
	v_mov_b32_e32 v106, 0
	v_mov_b32_e32 v107, 0
	v_mov_b32_e32 v108, 0
	v_mov_b32_e32 v109, 0
	v_mov_b32_e32 v110, 0
	v_mov_b32_e32 v111, 0
	v_mov_b32_e32 v112, 0
	v_mov_b32_e32 v113, 0
	v_mov_b32_e32 v114, 0
	v_mov_b32_e32 v115, 0
	v_mov_b32_e32 v116, 0
	v_mov_b32_e32 v117, 0
	v_mov_b32_e32 v118, 0
	v_mov_b32_e32 v119, 0
	v_mov_b32_e32 v120, 0
	v_mov_b32_e32 v121, 0
	v_mov_b32_e32 v122, 0
	v_mov_b32_e32 v123, 0
	v_mov_b32_e32 v124, 0
	v_mov_b32_e32 v125, 0
	v_mov_b32_e32 v126, 0
	v_mov_b32_e32 v127, 0
	s_nop 0
	s_nop 0
	s_nop 0
	s_nop 0
	s_nop 0
	s_nop 0
	s_nop 0
	s_nop 0
	s_nop 0
	s_nop 0
	s_nop 0
	s_nop 0
	s_waitcnt vmcnt(2)
	s_barrier
	global_load_lds_dwordx4 v[6:7], off
	v_lshl_add_u64 v[4:5], v[4:5], 0, s[10:11]
	s_add_i32 m0, s25, 0x1a000
	s_add_i32 s44, s25, 0x8000
	s_add_i32 s45, s25, 0xa000
	global_load_lds_dwordx4 v[4:5], off
	v_lshl_add_u64 v[0:1], v[0:1], 0, s[10:11]
	s_mov_b32 m0, s44
	s_add_u32 s4, s28, 0x40080
	global_load_lds_dwordx4 v[0:1], off
	v_lshl_add_u64 v[0:1], v[2:3], 0, s[10:11]
	s_mov_b32 m0, s45
	s_addc_u32 s5, s29, 0
	global_load_lds_dwordx4 v[0:1], off
	s_add_i32 m0, s25, 0x1c000
	v_lshl_add_u64 v[0:1], s[4:5], 0, v[176:177]
	global_load_lds_dwordx4 v[0:1], off
	v_lshl_add_u64 v[0:1], s[4:5], 0, v[178:179]
	s_add_i32 m0, s25, 0x1e000
	s_mov_b64 s[4:5], 0x40080
	global_load_lds_dwordx4 v[0:1], off
	v_bfe_u32 v0, v8, 4, 2
	v_and_b32_e32 v1, 15, v8
	v_lshlrev_b32_e32 v2, 4, v0
	v_lshl_or_b32 v209, s0, 6, v1
	v_lshl_or_b32 v1, v1, 6, v2
	v_lshlrev_b32_e32 v2, 2, v8
	v_and_b32_e32 v2, 32, v2
	v_bitop3_b32 v210, v1, s1, v2 bitop3:0xde
	v_cmp_eq_u32_e64 s[0:1], 0, v0
	v_lshl_or_b32 v211, v0, 2, s14
	v_lshlrev_b32_e32 v0, 13, v9
	v_and_b32_e32 v0, 0x7fffc000, v0
	v_lshl_add_u32 v0, v10, 10, v0
	v_or_b32_e32 v0, v0, v11
	v_bitop3_b32 v3, v1, s12, v2 bitop3:0xde
	v_add_lshl_u32 v0, v0, v12, 1
	v_mov_b32_e32 v1, v177
	v_lshl_add_u64 v[180:181], v[0:1], 0, s[4:5]
	v_lshlrev_b32_e32 v0, 13, v13
	v_and_b32_e32 v0, 0x7fffc000, v0
	v_lshl_add_u32 v0, v14, 10, v0
	s_waitcnt vmcnt(6)
	s_cmpk_lt_u32 s3, 0x100
	v_or_b32_e32 v0, v0, v15
	s_cselect_b64 s[12:13], -1, 0
	v_add_lshl_u32 v0, v0, v16, 1
	s_add_i32 s50, 0, 0x10000
	s_add_i32 s51, 0, 0x14000
	s_ashr_i32 s48, s36, 31
	s_ashr_i32 s49, s33, 31
	v_lshl_add_u64 v[182:183], v[0:1], 0, s[4:5]
	v_mov_b64_e32 v[184:185], 0x100
	v_mov_b64_e32 v[186:187], 0xff
	v_add_u32_e32 v212, s50, v210
	v_add_u32_e32 v213, s51, v210
	v_add_u32_e32 v214, 0, v3
	s_barrier
	s_branch .LBB0_1211

.LBB0_1217:
	s_ashr_i32 s17, s16, 31
	s_lshl_b64 s[18:19], s[16:17], 19
	s_add_u32 s18, s84, s18
	s_addc_u32 s19, s85, s19
	s_and_b64 s[20:21], s[4:5], exec
	s_cselect_b32 s3, s19, s27
	s_cselect_b32 s17, s18, s26
	s_ashr_i32 s15, s14, 31
	s_lshl_b64 s[20:21], s[14:15], 19
	s_add_u32 s20, s37, s20
	s_addc_u32 s21, s38, s21
	s_and_b64 s[30:31], s[4:5], exec
	s_cselect_b32 s15, s21, s29
	s_cselect_b32 s23, s20, s28
	s_add_u32 s52, s28, 0x100
	v_mov_b32_e32 v0, 0
	s_addc_u32 s53, s29, 0
	s_mov_b32 s54, -2
	s_waitcnt lgkmcnt(0)
	v_mov_b32_e32 v1, v0
	v_mov_b32_e32 v2, v0
	v_mov_b32_e32 v3, v0
	v_mov_b32_e32 v4, v0
	v_mov_b32_e32 v5, v0
	v_mov_b32_e32 v6, v0
	v_mov_b32_e32 v7, v0
	v_mov_b32_e32 v8, v0
	v_mov_b32_e32 v9, v0
	v_mov_b32_e32 v10, v0
	v_mov_b32_e32 v11, v0
	v_mov_b32_e32 v12, v0
	v_mov_b32_e32 v13, v0
	v_mov_b32_e32 v14, v0
	v_mov_b32_e32 v15, v0
	v_mov_b32_e32 v16, v0
	v_mov_b32_e32 v17, v0
	v_mov_b32_e32 v18, v0
	v_mov_b32_e32 v19, v0
	v_mov_b32_e32 v20, v0
	v_mov_b32_e32 v21, v0
	v_mov_b32_e32 v22, v0
	v_mov_b32_e32 v23, v0
	v_mov_b32_e32 v24, v0
	v_mov_b32_e32 v25, v0
	v_mov_b32_e32 v26, v0
	v_mov_b32_e32 v27, v0
	v_mov_b32_e32 v28, v0
	v_mov_b32_e32 v29, v0
	v_mov_b32_e32 v30, v0
	v_mov_b32_e32 v31, v0
	s_cmp_eq_u32 s98, 1
	s_mov_b32 s98, 0
	s_cbranch_scc1 .Lzskip_6
	v_mov_b32_e32 v32, v0
	v_mov_b32_e32 v33, v0
	v_mov_b32_e32 v34, v0
	v_mov_b32_e32 v35, v0
	v_mov_b32_e32 v36, v0
	v_mov_b32_e32 v37, v0
	v_mov_b32_e32 v38, v0
	v_mov_b32_e32 v39, v0
	v_mov_b32_e32 v40, v0
	v_mov_b32_e32 v41, v0
	v_mov_b32_e32 v42, v0
	v_mov_b32_e32 v43, v0
	v_mov_b32_e32 v44, v0
	v_mov_b32_e32 v45, v0
	v_mov_b32_e32 v46, v0
	v_mov_b32_e32 v47, v0
	v_mov_b32_e32 v48, v0
	v_mov_b32_e32 v49, v0
	v_mov_b32_e32 v50, v0
	v_mov_b32_e32 v51, v0
	v_mov_b32_e32 v52, v0
	v_mov_b32_e32 v53, v0
	v_mov_b32_e32 v54, v0
	v_mov_b32_e32 v55, v0
	v_mov_b32_e32 v56, v0
	v_mov_b32_e32 v57, v0
	v_mov_b32_e32 v58, v0
	v_mov_b32_e32 v59, v0
	v_mov_b32_e32 v60, v0
	v_mov_b32_e32 v61, v0
	v_mov_b32_e32 v62, v0
	v_mov_b32_e32 v63, v0
	v_mov_b32_e32 v64, v0
	v_mov_b32_e32 v65, v0
	v_mov_b32_e32 v66, v0
	v_mov_b32_e32 v67, v0
	v_mov_b32_e32 v68, v0
	v_mov_b32_e32 v69, v0
	v_mov_b32_e32 v70, v0
	v_mov_b32_e32 v71, v0
	v_mov_b32_e32 v72, v0
	v_mov_b32_e32 v73, v0
	v_mov_b32_e32 v74, v0
	v_mov_b32_e32 v75, v0
	v_mov_b32_e32 v76, v0
	v_mov_b32_e32 v77, v0
	v_mov_b32_e32 v78, v0
	v_mov_b32_e32 v79, v0
	v_mov_b32_e32 v80, v0
	v_mov_b32_e32 v81, v0
	v_mov_b32_e32 v82, v0
	v_mov_b32_e32 v83, v0
	v_mov_b32_e32 v84, v0
	v_mov_b32_e32 v85, v0
	v_mov_b32_e32 v86, v0
	v_mov_b32_e32 v87, v0
	v_mov_b32_e32 v88, v0
	v_mov_b32_e32 v89, v0
	v_mov_b32_e32 v90, v0
	v_mov_b32_e32 v91, v0
	v_mov_b32_e32 v92, v0
	v_mov_b32_e32 v93, v0
	v_mov_b32_e32 v94, v0
	v_mov_b32_e32 v95, v0
	v_mov_b32_e32 v96, v0
	v_mov_b32_e32 v97, v0
	v_mov_b32_e32 v98, v0
	v_mov_b32_e32 v99, v0
	v_mov_b32_e32 v100, v0
	v_mov_b32_e32 v101, v0
	v_mov_b32_e32 v102, v0
	v_mov_b32_e32 v103, v0
	v_mov_b32_e32 v104, v0
	v_mov_b32_e32 v105, v0
	v_mov_b32_e32 v106, v0
	v_mov_b32_e32 v107, v0
	v_mov_b32_e32 v108, v0
	v_mov_b32_e32 v109, v0
	v_mov_b32_e32 v110, v0
	v_mov_b32_e32 v111, v0
	v_mov_b32_e32 v112, v0
	v_mov_b32_e32 v113, v0
	v_mov_b32_e32 v114, v0
	v_mov_b32_e32 v115, v0
	v_mov_b32_e32 v116, v0
	v_mov_b32_e32 v117, v0
	v_mov_b32_e32 v118, v0
	v_mov_b32_e32 v119, v0
	v_mov_b32_e32 v120, v0
	v_mov_b32_e32 v121, v0
	v_mov_b32_e32 v122, v0
	v_mov_b32_e32 v123, v0
	v_mov_b32_e32 v124, v0
	v_mov_b32_e32 v125, v0
	v_mov_b32_e32 v126, v0
	v_mov_b32_e32 v127, v0
.Lzskip_6:
.LBB0_1218:
	ds_read_b128 v[128:131], v212
	ds_read_b128 v[132:135], v212 offset:1024
	ds_read_b128 v[136:139], v212 offset:2048
	ds_read_b128 v[140:143], v212 offset:3072
	ds_read_b128 v[144:147], v213
	ds_read_b128 v[148:151], v213 offset:1024
	ds_read_b128 v[152:155], v213 offset:2048
	ds_read_b128 v[156:159], v213 offset:3072
	s_add_u32 s28, s26, 0x100
	s_addc_u32 s29, s27, 0
	s_cmp_eq_u32 s54, 12
	s_cselect_b32 s35, s3, s29
	s_cselect_b32 s34, s17, s28
	s_cselect_b32 s31, s15, s53
	s_cselect_b32 s30, s23, s52
	v_lshl_add_u64 v[204:205], s[26:27], 0, v[180:181]
	s_add_i32 m0, s25, 0xc000
	ds_read_b128 v[160:163], v214
	ds_read_b128 v[164:167], v214 offset:1024
	ds_read_b128 v[168:171], v214 offset:2048
	ds_read_b128 v[172:175], v214 offset:3072
	ds_read_b128 v[188:191], v214 offset:4096
	ds_read_b128 v[192:195], v214 offset:5120
	ds_read_b128 v[196:199], v214 offset:6144
	ds_read_b128 v[200:203], v214 offset:7168
	global_load_lds_dwordx4 v[204:205], off
	v_lshl_add_u64 v[204:205], s[26:27], 0, v[182:183]
	s_add_i32 m0, s25, 0xe000
	s_nop 0
	global_load_lds_dwordx4 v[204:205], off
	s_waitcnt vmcnt(8)
	s_waitcnt lgkmcnt(0)
	s_setprio 1
	s_barrier
	v_mfma_f32_16x16x32_bf16 v[124:127], v[128:131], v[160:163], v[124:127]
	v_mfma_f32_16x16x32_bf16 v[120:123], v[136:139], v[160:163], v[120:123]
	v_mfma_f32_16x16x32_bf16 v[108:111], v[128:131], v[168:171], v[108:111]
	v_mfma_f32_16x16x32_bf16 v[104:107], v[136:139], v[168:171], v[104:107]
	v_mfma_f32_16x16x32_bf16 v[92:95], v[128:131], v[188:191], v[92:95]
	v_mfma_f32_16x16x32_bf16 v[88:91], v[136:139], v[188:191], v[88:91]
	v_mfma_f32_16x16x32_bf16 v[76:79], v[128:131], v[196:199], v[76:79]
	v_mfma_f32_16x16x32_bf16 v[72:75], v[136:139], v[196:199], v[72:75]
	v_mfma_f32_16x16x32_bf16 v[124:127], v[132:135], v[164:167], v[124:127]
	v_mfma_f32_16x16x32_bf16 v[120:123], v[140:143], v[164:167], v[120:123]
	v_mfma_f32_16x16x32_bf16 v[108:111], v[132:135], v[172:175], v[108:111]
	v_mfma_f32_16x16x32_bf16 v[104:107], v[140:143], v[172:175], v[104:107]
	v_mfma_f32_16x16x32_bf16 v[92:95], v[132:135], v[192:195], v[92:95]
	v_mfma_f32_16x16x32_bf16 v[88:91], v[140:143], v[192:195], v[88:91]
	v_mfma_f32_16x16x32_bf16 v[76:79], v[132:135], v[200:203], v[76:79]
	v_mfma_f32_16x16x32_bf16 v[72:75], v[140:143], v[200:203], v[72:75]
	s_setprio 0
	s_setprio 1
	v_mfma_f32_16x16x32_bf16 v[116:119], v[144:147], v[160:163], v[116:119]
	v_mfma_f32_16x16x32_bf16 v[112:115], v[152:155], v[160:163], v[112:115]
	v_mfma_f32_16x16x32_bf16 v[100:103], v[144:147], v[168:171], v[100:103]
	v_mfma_f32_16x16x32_bf16 v[96:99], v[152:155], v[168:171], v[96:99]
	v_mfma_f32_16x16x32_bf16 v[84:87], v[144:147], v[188:191], v[84:87]
	v_mfma_f32_16x16x32_bf16 v[80:83], v[152:155], v[188:191], v[80:83]
	v_mfma_f32_16x16x32_bf16 v[68:71], v[144:147], v[196:199], v[68:71]
	v_mfma_f32_16x16x32_bf16 v[64:67], v[152:155], v[196:199], v[64:67]
	v_mfma_f32_16x16x32_bf16 v[116:119], v[148:151], v[164:167], v[116:119]
	v_mfma_f32_16x16x32_bf16 v[112:115], v[156:159], v[164:167], v[112:115]
	v_mfma_f32_16x16x32_bf16 v[100:103], v[148:151], v[172:175], v[100:103]
	v_mfma_f32_16x16x32_bf16 v[96:99], v[156:159], v[172:175], v[96:99]
	v_mfma_f32_16x16x32_bf16 v[84:87], v[148:151], v[192:195], v[84:87]
	v_mfma_f32_16x16x32_bf16 v[80:83], v[156:159], v[192:195], v[80:83]
	v_mfma_f32_16x16x32_bf16 v[68:71], v[148:151], v[200:203], v[68:71]
	v_mfma_f32_16x16x32_bf16 v[64:67], v[156:159], v[200:203], v[64:67]
	s_barrier
	s_setprio 0
	s_add_i32 s26, s50, s39
	v_lshl_add_u64 v[204:205], s[30:31], 0, v[176:177]
	s_mov_b32 m0, s26
	ds_read_b128 v[160:163], v214 offset:16384
	ds_read_b128 v[164:167], v214 offset:17408
	ds_read_b128 v[168:171], v214 offset:18432
	ds_read_b128 v[172:175], v214 offset:19456
	ds_read_b128 v[188:191], v214 offset:20480
	ds_read_b128 v[192:195], v214 offset:21504
	ds_read_b128 v[196:199], v214 offset:22528
	ds_read_b128 v[200:203], v214 offset:23552
	global_load_lds_dwordx4 v[204:205], off
	s_add_i32 m0, s26, 0x2000
	s_add_u32 s26, s30, 0x40000
	v_lshl_add_u64 v[216:217], s[30:31], 0, v[178:179]
	s_addc_u32 s27, s31, 0
	s_add_i32 s55, s51, s39
	global_load_lds_dwordx4 v[216:217], off
	v_lshl_add_u64 v[218:219], s[26:27], 0, v[176:177]
	s_mov_b32 m0, s55
	v_lshl_add_u64 v[220:221], s[34:35], 0, v[178:179]
	global_load_lds_dwordx4 v[218:219], off
	v_lshl_add_u64 v[218:219], s[26:27], 0, v[178:179]
	s_add_i32 m0, s55, 0x2000
	s_nop 0
	global_load_lds_dwordx4 v[218:219], off
	v_lshl_add_u64 v[218:219], s[34:35], 0, v[176:177]
	s_mov_b32 m0, s25
	s_nop 0
	global_load_lds_dwordx4 v[218:219], off
	s_mov_b32 m0, s40
	s_nop 0
	global_load_lds_dwordx4 v[220:221], off
	s_waitcnt vmcnt(8)
	s_waitcnt lgkmcnt(0)
	s_setprio 1
	s_barrier
	v_mfma_f32_16x16x32_bf16 v[60:63], v[128:131], v[160:163], v[60:63]
	v_mfma_f32_16x16x32_bf16 v[56:59], v[136:139], v[160:163], v[56:59]
	v_mfma_f32_16x16x32_bf16 v[44:47], v[128:131], v[168:171], v[44:47]
	v_mfma_f32_16x16x32_bf16 v[40:43], v[136:139], v[168:171], v[40:43]
	v_mfma_f32_16x16x32_bf16 v[28:31], v[128:131], v[188:191], v[28:31]
	v_mfma_f32_16x16x32_bf16 v[24:27], v[136:139], v[188:191], v[24:27]
	v_mfma_f32_16x16x32_bf16 v[12:15], v[128:131], v[196:199], v[12:15]
	v_mfma_f32_16x16x32_bf16 v[8:11], v[136:139], v[196:199], v[8:11]
	v_mfma_f32_16x16x32_bf16 v[60:63], v[132:135], v[164:167], v[60:63]
	v_mfma_f32_16x16x32_bf16 v[56:59], v[140:143], v[164:167], v[56:59]
	v_mfma_f32_16x16x32_bf16 v[44:47], v[132:135], v[172:175], v[44:47]
	v_mfma_f32_16x16x32_bf16 v[40:43], v[140:143], v[172:175], v[40:43]
	v_mfma_f32_16x16x32_bf16 v[28:31], v[132:135], v[192:195], v[28:31]
	v_mfma_f32_16x16x32_bf16 v[24:27], v[140:143], v[192:195], v[24:27]
	v_mfma_f32_16x16x32_bf16 v[12:15], v[132:135], v[200:203], v[12:15]
	v_mfma_f32_16x16x32_bf16 v[8:11], v[140:143], v[200:203], v[8:11]
	s_setprio 0
	s_setprio 1
	v_mfma_f32_16x16x32_bf16 v[52:55], v[144:147], v[160:163], v[52:55]
	v_mfma_f32_16x16x32_bf16 v[48:51], v[152:155], v[160:163], v[48:51]
	v_mfma_f32_16x16x32_bf16 v[36:39], v[144:147], v[168:171], v[36:39]
	v_mfma_f32_16x16x32_bf16 v[32:35], v[152:155], v[168:171], v[32:35]
	v_mfma_f32_16x16x32_bf16 v[20:23], v[144:147], v[188:191], v[20:23]
	v_mfma_f32_16x16x32_bf16 v[16:19], v[152:155], v[188:191], v[16:19]
	v_mfma_f32_16x16x32_bf16 v[4:7], v[144:147], v[196:199], v[4:7]
	v_mfma_f32_16x16x32_bf16 v[0:3], v[152:155], v[196:199], v[0:3]
	v_mfma_f32_16x16x32_bf16 v[52:55], v[148:151], v[164:167], v[52:55]
	v_mfma_f32_16x16x32_bf16 v[48:51], v[156:159], v[164:167], v[48:51]
	v_mfma_f32_16x16x32_bf16 v[36:39], v[148:151], v[172:175], v[36:39]
	v_mfma_f32_16x16x32_bf16 v[32:35], v[156:159], v[172:175], v[32:35]
	v_mfma_f32_16x16x32_bf16 v[20:23], v[148:151], v[192:195], v[20:23]
	v_mfma_f32_16x16x32_bf16 v[16:19], v[156:159], v[192:195], v[16:19]
	v_mfma_f32_16x16x32_bf16 v[4:7], v[148:151], v[200:203], v[4:7]
	v_mfma_f32_16x16x32_bf16 v[0:3], v[156:159], v[200:203], v[0:3]
	s_barrier
	s_setprio 0
	s_add_i32 s55, 0, 0x18000
	s_add_i32 s56, 0, 0x1c000
	v_add_u32_e32 v140, s55, v210
	v_add_u32_e32 v156, s56, v210
	ds_read_b128 v[128:131], v140
	ds_read_b128 v[132:135], v140 offset:1024
	ds_read_b128 v[136:139], v140 offset:2048
	ds_read_b128 v[140:143], v140 offset:3072
	ds_read_b128 v[144:147], v156
	ds_read_b128 v[148:151], v156 offset:1024
	ds_read_b128 v[152:155], v156 offset:2048
	ds_read_b128 v[156:159], v156 offset:3072
	s_add_u32 s26, s34, 0x40000
	s_addc_u32 s27, s35, 0
	s_mov_b32 m0, s41
	v_lshl_add_u64 v[222:223], s[26:27], 0, v[176:177]
	ds_read_b128 v[160:163], v214 offset:32768
	ds_read_b128 v[164:167], v214 offset:33792
	ds_read_b128 v[168:171], v214 offset:34816
	ds_read_b128 v[172:175], v214 offset:35840
	ds_read_b128 v[188:191], v214 offset:36864
	ds_read_b128 v[192:195], v214 offset:37888
	ds_read_b128 v[196:199], v214 offset:38912
	ds_read_b128 v[200:203], v214 offset:39936
	global_load_lds_dwordx4 v[222:223], off
	v_lshl_add_u64 v[222:223], s[26:27], 0, v[178:179]
	s_mov_b32 m0, s42
	s_nop 0
	global_load_lds_dwordx4 v[222:223], off
	s_waitcnt vmcnt(8)
	s_waitcnt lgkmcnt(0)
	s_setprio 1
	s_barrier
	v_mfma_f32_16x16x32_bf16 v[124:127], v[128:131], v[160:163], v[124:127]
	v_mfma_f32_16x16x32_bf16 v[120:123], v[136:139], v[160:163], v[120:123]
	v_mfma_f32_16x16x32_bf16 v[108:111], v[128:131], v[168:171], v[108:111]
	v_mfma_f32_16x16x32_bf16 v[104:107], v[136:139], v[168:171], v[104:107]
	v_mfma_f32_16x16x32_bf16 v[92:95], v[128:131], v[188:191], v[92:95]
	v_mfma_f32_16x16x32_bf16 v[88:91], v[136:139], v[188:191], v[88:91]
	v_mfma_f32_16x16x32_bf16 v[76:79], v[128:131], v[196:199], v[76:79]
	v_mfma_f32_16x16x32_bf16 v[72:75], v[136:139], v[196:199], v[72:75]
	v_mfma_f32_16x16x32_bf16 v[124:127], v[132:135], v[164:167], v[124:127]
	v_mfma_f32_16x16x32_bf16 v[120:123], v[140:143], v[164:167], v[120:123]
	v_mfma_f32_16x16x32_bf16 v[108:111], v[132:135], v[172:175], v[108:111]
	v_mfma_f32_16x16x32_bf16 v[104:107], v[140:143], v[172:175], v[104:107]
	v_mfma_f32_16x16x32_bf16 v[92:95], v[132:135], v[192:195], v[92:95]
	v_mfma_f32_16x16x32_bf16 v[88:91], v[140:143], v[192:195], v[88:91]
	v_mfma_f32_16x16x32_bf16 v[76:79], v[132:135], v[200:203], v[76:79]
	v_mfma_f32_16x16x32_bf16 v[72:75], v[140:143], v[200:203], v[72:75]
	s_setprio 0
	s_setprio 1
	v_mfma_f32_16x16x32_bf16 v[116:119], v[144:147], v[160:163], v[116:119]
	v_mfma_f32_16x16x32_bf16 v[112:115], v[152:155], v[160:163], v[112:115]
	v_mfma_f32_16x16x32_bf16 v[100:103], v[144:147], v[168:171], v[100:103]
	v_mfma_f32_16x16x32_bf16 v[96:99], v[152:155], v[168:171], v[96:99]
	v_mfma_f32_16x16x32_bf16 v[84:87], v[144:147], v[188:191], v[84:87]
	v_mfma_f32_16x16x32_bf16 v[80:83], v[152:155], v[188:191], v[80:83]
	v_mfma_f32_16x16x32_bf16 v[68:71], v[144:147], v[196:199], v[68:71]
	v_mfma_f32_16x16x32_bf16 v[64:67], v[152:155], v[196:199], v[64:67]
	v_mfma_f32_16x16x32_bf16 v[116:119], v[148:151], v[164:167], v[116:119]
	v_mfma_f32_16x16x32_bf16 v[112:115], v[156:159], v[164:167], v[112:115]
	v_mfma_f32_16x16x32_bf16 v[100:103], v[148:151], v[172:175], v[100:103]
	v_mfma_f32_16x16x32_bf16 v[96:99], v[156:159], v[172:175], v[96:99]
	v_mfma_f32_16x16x32_bf16 v[84:87], v[148:151], v[192:195], v[84:87]
	v_mfma_f32_16x16x32_bf16 v[80:83], v[156:159], v[192:195], v[80:83]
	v_mfma_f32_16x16x32_bf16 v[68:71], v[148:151], v[200:203], v[68:71]
	v_mfma_f32_16x16x32_bf16 v[64:67], v[156:159], v[200:203], v[64:67]
	s_barrier
	s_setprio 0
	s_add_i32 s26, s55, s39
	v_lshl_add_u64 v[204:205], v[204:205], 0, s[10:11]
	s_mov_b32 m0, s26
	ds_read_b128 v[160:163], v214 offset:49152
	ds_read_b128 v[164:167], v214 offset:50176
	ds_read_b128 v[168:171], v214 offset:51200
	ds_read_b128 v[172:175], v214 offset:52224
	ds_read_b128 v[188:191], v214 offset:53248
	ds_read_b128 v[192:195], v214 offset:54272
	ds_read_b128 v[196:199], v214 offset:55296
	ds_read_b128 v[200:203], v214 offset:56320
	global_load_lds_dwordx4 v[204:205], off
	s_add_i32 m0, s26, 0x2000
	s_add_u32 s26, s30, 0x40080
	v_lshl_add_u64 v[204:205], v[216:217], 0, s[10:11]
	s_addc_u32 s27, s31, 0
	s_add_i32 s30, s56, s39
	global_load_lds_dwordx4 v[204:205], off
	v_lshl_add_u64 v[204:205], s[26:27], 0, v[176:177]
	s_mov_b32 m0, s30
	s_nop 0
	global_load_lds_dwordx4 v[204:205], off
	v_lshl_add_u64 v[204:205], s[26:27], 0, v[178:179]
	s_add_i32 m0, s30, 0x2000
	s_nop 0
	global_load_lds_dwordx4 v[204:205], off
	v_lshl_add_u64 v[204:205], v[218:219], 0, s[10:11]
	s_mov_b32 m0, s44
	s_nop 0
	global_load_lds_dwordx4 v[204:205], off
	v_lshl_add_u64 v[204:205], v[220:221], 0, s[10:11]
	s_mov_b32 m0, s45
	s_nop 0
	global_load_lds_dwordx4 v[204:205], off
	s_waitcnt vmcnt(8)
	s_waitcnt lgkmcnt(0)
	s_setprio 1
	s_barrier
	v_mfma_f32_16x16x32_bf16 v[60:63], v[128:131], v[160:163], v[60:63]
	v_mfma_f32_16x16x32_bf16 v[56:59], v[136:139], v[160:163], v[56:59]
	v_mfma_f32_16x16x32_bf16 v[44:47], v[128:131], v[168:171], v[44:47]
	v_mfma_f32_16x16x32_bf16 v[40:43], v[136:139], v[168:171], v[40:43]
	v_mfma_f32_16x16x32_bf16 v[28:31], v[128:131], v[188:191], v[28:31]
	v_mfma_f32_16x16x32_bf16 v[24:27], v[136:139], v[188:191], v[24:27]
	v_mfma_f32_16x16x32_bf16 v[12:15], v[128:131], v[196:199], v[12:15]
	v_mfma_f32_16x16x32_bf16 v[8:11], v[136:139], v[196:199], v[8:11]
	v_mfma_f32_16x16x32_bf16 v[60:63], v[132:135], v[164:167], v[60:63]
	v_mfma_f32_16x16x32_bf16 v[56:59], v[140:143], v[164:167], v[56:59]
	v_mfma_f32_16x16x32_bf16 v[44:47], v[132:135], v[172:175], v[44:47]
	v_mfma_f32_16x16x32_bf16 v[40:43], v[140:143], v[172:175], v[40:43]
	v_mfma_f32_16x16x32_bf16 v[28:31], v[132:135], v[192:195], v[28:31]
	v_mfma_f32_16x16x32_bf16 v[24:27], v[140:143], v[192:195], v[24:27]
	v_mfma_f32_16x16x32_bf16 v[12:15], v[132:135], v[200:203], v[12:15]
	v_mfma_f32_16x16x32_bf16 v[8:11], v[140:143], v[200:203], v[8:11]
	s_setprio 0
	s_setprio 1
	v_mfma_f32_16x16x32_bf16 v[52:55], v[144:147], v[160:163], v[52:55]
	v_mfma_f32_16x16x32_bf16 v[48:51], v[152:155], v[160:163], v[48:51]
	v_mfma_f32_16x16x32_bf16 v[36:39], v[144:147], v[168:171], v[36:39]
	v_mfma_f32_16x16x32_bf16 v[32:35], v[152:155], v[168:171], v[32:35]
	v_mfma_f32_16x16x32_bf16 v[20:23], v[144:147], v[188:191], v[20:23]
	v_mfma_f32_16x16x32_bf16 v[16:19], v[152:155], v[188:191], v[16:19]
	v_mfma_f32_16x16x32_bf16 v[4:7], v[144:147], v[196:199], v[4:7]
	v_mfma_f32_16x16x32_bf16 v[0:3], v[152:155], v[196:199], v[0:3]
	v_mfma_f32_16x16x32_bf16 v[52:55], v[148:151], v[164:167], v[52:55]
	v_mfma_f32_16x16x32_bf16 v[48:51], v[156:159], v[164:167], v[48:51]
	v_mfma_f32_16x16x32_bf16 v[36:39], v[148:151], v[172:175], v[36:39]
	v_mfma_f32_16x16x32_bf16 v[32:35], v[156:159], v[172:175], v[32:35]
	v_mfma_f32_16x16x32_bf16 v[20:23], v[148:151], v[192:195], v[20:23]
	v_mfma_f32_16x16x32_bf16 v[16:19], v[156:159], v[192:195], v[16:19]
	v_mfma_f32_16x16x32_bf16 v[4:7], v[148:151], v[200:203], v[4:7]
	v_mfma_f32_16x16x32_bf16 v[0:3], v[156:159], v[200:203], v[0:3]
	s_barrier
	s_setprio 0
	s_add_i32 s54, s54, 2
	s_add_u32 s52, s52, 0x100
	s_addc_u32 s53, s53, 0
	s_cmp_gt_u32 s54, 13
	s_mov_b64 s[26:27], s[28:29]
	s_cbranch_scc0 .LBB0_1218
	s_and_b64 vcc, exec, s[12:13]
	s_cbranch_vccz .LBB0_1221
	s_barrier

.LBB0_1300:
	s_lshl_b32 s3, s3, 5
	s_mov_b64 s[8:9], 0x80
	s_and_b32 s14, s3, 0x60
	s_add_i32 m0, s29, 0x18000
	v_lshl_add_u64 v[6:7], v[6:7], 0, s[8:9]
	s_lshl_b32 s11, s1, 13
	s_lshl_b32 s15, s14, 7
	s_mov_b32 s98, 1
	v_mov_b32_e32 v32, 0
	v_mov_b32_e32 v33, 0
	v_mov_b32_e32 v34, 0
	v_mov_b32_e32 v35, 0
	v_mov_b32_e32 v36, 0
	v_mov_b32_e32 v37, 0
	v_mov_b32_e32 v38, 0
	v_mov_b32_e32 v39, 0
	v_mov_b32_e32 v40, 0
	v_mov_b32_e32 v41, 0
	v_mov_b32_e32 v42, 0
	v_mov_b32_e32 v43, 0
	v_mov_b32_e32 v44, 0
	v_mov_b32_e32 v45, 0
	v_mov_b32_e32 v46, 0
	v_mov_b32_e32 v47, 0
	v_mov_b32_e32 v48, 0
	v_mov_b32_e32 v49, 0
	v_mov_b32_e32 v50, 0
	v_mov_b32_e32 v51, 0
	v_mov_b32_e32 v52, 0
	v_mov_b32_e32 v53, 0
	v_mov_b32_e32 v54, 0
	v_mov_b32_e32 v55, 0
	v_mov_b32_e32 v56, 0
	v_mov_b32_e32 v57, 0
	v_mov_b32_e32 v58, 0
	v_mov_b32_e32 v59, 0
	v_mov_b32_e32 v60, 0
	v_mov_b32_e32 v61, 0
	v_mov_b32_e32 v62, 0
	v_mov_b32_e32 v63, 0
	v_mov_b32_e32 v64, 0
	v_mov_b32_e32 v65, 0
	v_mov_b32_e32 v66, 0
	v_mov_b32_e32 v67, 0
	v_mov_b32_e32 v68, 0
	v_mov_b32_e32 v69, 0
	v_mov_b32_e32 v70, 0
	v_mov_b32_e32 v71, 0
	v_mov_b32_e32 v72, 0
	v_mov_b32_e32 v73, 0
	v_mov_b32_e32 v74, 0
	v_mov_b32_e32 v75, 0
	v_mov_b32_e32 v76, 0
	v_mov_b32_e32 v77, 0
	v_mov_b32_e32 v78, 0
	v_mov_b32_e32 v79, 0
	v_mov_b32_e32 v80, 0
	v_mov_b32_e32 v81, 0
	v_mov_b32_e32 v82, 0
	v_mov_b32_e32 v83, 0
	v_mov_b32_e32 v84, 0
	v_mov_b32_e32 v85, 0
	v_mov_b32_e32 v86, 0
	v_mov_b32_e32 v87, 0
	v_mov_b32_e32 v88, 0
	v_mov_b32_e32 v89, 0
	v_mov_b32_e32 v90, 0
	v_mov_b32_e32 v91, 0
	v_mov_b32_e32 v92, 0
	v_mov_b32_e32 v93, 0
	v_mov_b32_e32 v94, 0
	v_mov_b32_e32 v95, 0
	v_mov_b32_e32 v96, 0
	v_mov_b32_e32 v97, 0
	v_mov_b32_e32 v98, 0
	v_mov_b32_e32 v99, 0
	v_mov_b32_e32 v100, 0
	v_mov_b32_e32 v101, 0
	v_mov_b32_e32 v102, 0
	v_mov_b32_e32 v103, 0
	v_mov_b32_e32 v104, 0
	v_mov_b32_e32 v105, 0
	v_mov_b32_e32 v106, 0
	v_mov_b32_e32 v107, 0
	v_mov_b32_e32 v108, 0
	v_mov_b32_e32 v109, 0
	v_mov_b32_e32 v110, 0
	v_mov_b32_e32 v111, 0
	v_mov_b32_e32 v112, 0
	v_mov_b32_e32 v113, 0
	v_mov_b32_e32 v114, 0
	v_mov_b32_e32 v115, 0
	v_mov_b32_e32 v116, 0
	v_mov_b32_e32 v117, 0
	v_mov_b32_e32 v118, 0
	v_mov_b32_e32 v119, 0
	v_mov_b32_e32 v120, 0
	v_mov_b32_e32 v121, 0
	v_mov_b32_e32 v122, 0
	v_mov_b32_e32 v123, 0
	v_mov_b32_e32 v124, 0
	v_mov_b32_e32 v125, 0
	v_mov_b32_e32 v126, 0
	v_mov_b32_e32 v127, 0
	s_nop 0
	s_nop 0
	s_nop 0
	s_nop 0
	s_nop 0
	s_nop 0
	s_nop 0
	s_nop 0
	s_nop 0
	s_nop 0
	s_nop 0
	s_nop 0
	s_waitcnt vmcnt(2)
	s_barrier
	global_load_lds_dwordx4 v[6:7], off
	v_lshl_add_u64 v[4:5], v[4:5], 0, s[8:9]
	s_add_i32 m0, s29, 0x1a000
	s_add_i32 s49, s29, 0x8000
	s_add_i32 s50, s29, 0xa000
	global_load_lds_dwordx4 v[4:5], off
	v_lshl_add_u64 v[0:1], v[0:1], 0, s[8:9]
	s_mov_b32 m0, s49
	s_add_u32 s12, s34, 0x40080
	global_load_lds_dwordx4 v[0:1], off
	v_lshl_add_u64 v[0:1], v[2:3], 0, s[8:9]
	s_mov_b32 m0, s50
	s_addc_u32 s13, s35, 0
	global_load_lds_dwordx4 v[0:1], off
	s_add_i32 m0, s29, 0x1c000
	v_lshl_add_u64 v[0:1], s[12:13], 0, v[130:131]
	global_load_lds_dwordx4 v[0:1], off
	v_lshl_add_u64 v[0:1], s[12:13], 0, v[134:135]
	s_add_i32 m0, s29, 0x1e000
	s_cmpk_lt_u32 s10, 0x100
	global_load_lds_dwordx4 v[0:1], off
	v_lshrrev_b32_e32 v1, 1, v8
	v_and_b32_e32 v1, 24, v1
	v_and_b32_e32 v0, 15, v8
	v_lshlrev_b32_e32 v2, 1, v1
	v_lshl_or_b32 v152, s1, 6, v0
	v_lshl_or_b32 v0, v0, 6, v2
	v_lshlrev_b32_e32 v2, 2, v8
	v_and_b32_e32 v2, 32, v2
	v_bitop3_b32 v3, v0, s11, v2 bitop3:0xde
	v_bitop3_b32 v153, v0, s15, v2 bitop3:0xde
	v_lshlrev_b32_e32 v0, 14, v9
	v_and_b32_e32 v0, 0xffff8000, v0
	v_or_b32_e32 v154, s14, v1
	v_lshl_add_u32 v0, v10, 11, v0
	v_and_b32_e32 v1, 1, v9
	v_lshl_or_b32 v0, v1, 6, v0
	v_lshl_add_u32 v136, v11, 1, v0
	v_lshlrev_b32_e32 v0, 14, v12
	v_and_b32_e32 v0, 0xffff8000, v0
	s_waitcnt vmcnt(6)
	v_lshl_add_u32 v0, v13, 11, v0
	v_and_b32_e32 v1, 1, v12
	s_cselect_b64 s[10:11], -1, 0
	v_lshl_or_b32 v0, v1, 6, v0
	s_add_i32 s52, 0, 0x10000
	s_add_i32 s53, 0, 0x14000
	s_sext_i32_i8 s3, s0
	s_ashr_i32 s51, s33, 31
	v_mov_b32_e32 v137, v131
	v_lshl_add_u32 v138, v14, 1, v0
	v_mov_b32_e32 v139, v131
	v_mov_b64_e32 v[140:141], 0x400
	v_mov_b64_e32 v[142:143], 0x3ff
	v_add_u32_e32 v155, s52, v153
	v_add_u32_e32 v156, s53, v153
	v_add_u32_e32 v157, 0, v3
	v_mov_b32_e32 v158, 0x358637bd
	s_mov_b64 s[12:13], 0x100000
	s_mov_b32 s54, 0x100000
	s_mov_b64 s[14:15], 0x120000
	s_mov_b32 s55, 0x120000
	s_mov_b64 s[16:17], 0x140000
	s_mov_b32 s56, 0x140000
	s_mov_b64 s[18:19], 0x160000
	s_mov_b32 s57, 0x160000
	s_barrier
	s_branch .LBB0_1303

.LBB0_1309:
	s_ashr_i32 s23, s22, 31
	s_lshl_b64 s[24:25], s[22:23], 19
	s_add_u32 s24, s82, s24
	s_addc_u32 s25, s83, s25
	s_and_b64 s[26:27], s[0:1], exec
	s_cselect_b32 s23, s25, s31
	s_cselect_b32 s58, s24, s30
	s_ashr_i32 s21, s20, 31
	s_lshl_b64 s[26:27], s[20:21], 19
	s_add_u32 s26, s40, s26
	s_addc_u32 s27, s41, s27
	s_and_b64 s[36:37], s[0:1], exec
	s_cselect_b32 s21, s27, s35
	s_cselect_b32 s59, s26, s34
	s_add_u32 s30, s30, 0x40080
	s_addc_u32 s31, s31, 0
	s_add_u32 s60, s34, 0x100
	v_mov_b32_e32 v0, 0
	s_addc_u32 s61, s35, 0
	s_mov_b32 s62, -2
	v_mov_b32_e32 v1, v0
	v_mov_b32_e32 v2, v0
	v_mov_b32_e32 v3, v0
	v_mov_b32_e32 v4, v0
	v_mov_b32_e32 v5, v0
	v_mov_b32_e32 v6, v0
	v_mov_b32_e32 v7, v0
	v_mov_b32_e32 v8, v0
	v_mov_b32_e32 v9, v0
	v_mov_b32_e32 v10, v0
	v_mov_b32_e32 v11, v0
	v_mov_b32_e32 v12, v0
	v_mov_b32_e32 v13, v0
	v_mov_b32_e32 v14, v0
	v_mov_b32_e32 v15, v0
	v_mov_b32_e32 v16, v0
	v_mov_b32_e32 v17, v0
	v_mov_b32_e32 v18, v0
	v_mov_b32_e32 v19, v0
	v_mov_b32_e32 v20, v0
	v_mov_b32_e32 v21, v0
	v_mov_b32_e32 v22, v0
	v_mov_b32_e32 v23, v0
	v_mov_b32_e32 v24, v0
	v_mov_b32_e32 v25, v0
	v_mov_b32_e32 v26, v0
	v_mov_b32_e32 v27, v0
	v_mov_b32_e32 v28, v0
	v_mov_b32_e32 v29, v0
	v_mov_b32_e32 v30, v0
	v_mov_b32_e32 v31, v0
	s_cmp_eq_u32 s98, 1
	s_mov_b32 s98, 0
	s_cbranch_scc1 .Lzskip_7
	v_mov_b32_e32 v32, v0
	v_mov_b32_e32 v33, v0
	v_mov_b32_e32 v34, v0
	v_mov_b32_e32 v35, v0
	v_mov_b32_e32 v36, v0
	v_mov_b32_e32 v37, v0
	v_mov_b32_e32 v38, v0
	v_mov_b32_e32 v39, v0
	v_mov_b32_e32 v40, v0
	v_mov_b32_e32 v41, v0
	v_mov_b32_e32 v42, v0
	v_mov_b32_e32 v43, v0
	v_mov_b32_e32 v44, v0
	v_mov_b32_e32 v45, v0
	v_mov_b32_e32 v46, v0
	v_mov_b32_e32 v47, v0
	v_mov_b32_e32 v48, v0
	v_mov_b32_e32 v49, v0
	v_mov_b32_e32 v50, v0
	v_mov_b32_e32 v51, v0
	v_mov_b32_e32 v52, v0
	v_mov_b32_e32 v53, v0
	v_mov_b32_e32 v54, v0
	v_mov_b32_e32 v55, v0
	v_mov_b32_e32 v56, v0
	v_mov_b32_e32 v57, v0
	v_mov_b32_e32 v58, v0
	v_mov_b32_e32 v59, v0
	v_mov_b32_e32 v60, v0
	v_mov_b32_e32 v61, v0
	v_mov_b32_e32 v62, v0
	v_mov_b32_e32 v63, v0
	v_mov_b32_e32 v64, v0
	v_mov_b32_e32 v65, v0
	v_mov_b32_e32 v66, v0
	v_mov_b32_e32 v67, v0
	v_mov_b32_e32 v68, v0
	v_mov_b32_e32 v69, v0
	v_mov_b32_e32 v70, v0
	v_mov_b32_e32 v71, v0
	v_mov_b32_e32 v72, v0
	v_mov_b32_e32 v73, v0
	v_mov_b32_e32 v74, v0
	v_mov_b32_e32 v75, v0
	v_mov_b32_e32 v76, v0
	v_mov_b32_e32 v77, v0
	v_mov_b32_e32 v78, v0
	v_mov_b32_e32 v79, v0
	v_mov_b32_e32 v80, v0
	v_mov_b32_e32 v81, v0
	v_mov_b32_e32 v82, v0
	v_mov_b32_e32 v83, v0
	v_mov_b32_e32 v84, v0
	v_mov_b32_e32 v85, v0
	v_mov_b32_e32 v86, v0
	v_mov_b32_e32 v87, v0
	v_mov_b32_e32 v88, v0
	v_mov_b32_e32 v89, v0
	v_mov_b32_e32 v90, v0
	v_mov_b32_e32 v91, v0
	v_mov_b32_e32 v92, v0
	v_mov_b32_e32 v93, v0
	v_mov_b32_e32 v94, v0
	v_mov_b32_e32 v95, v0
	v_mov_b32_e32 v96, v0
	v_mov_b32_e32 v97, v0
	v_mov_b32_e32 v98, v0
	v_mov_b32_e32 v99, v0
	v_mov_b32_e32 v100, v0
	v_mov_b32_e32 v101, v0
	v_mov_b32_e32 v102, v0
	v_mov_b32_e32 v103, v0
	v_mov_b32_e32 v104, v0
	v_mov_b32_e32 v105, v0
	v_mov_b32_e32 v106, v0
	v_mov_b32_e32 v107, v0
	v_mov_b32_e32 v108, v0
	v_mov_b32_e32 v109, v0
	v_mov_b32_e32 v110, v0
	v_mov_b32_e32 v111, v0
	v_mov_b32_e32 v112, v0
	v_mov_b32_e32 v113, v0
	v_mov_b32_e32 v114, v0
	v_mov_b32_e32 v115, v0
	v_mov_b32_e32 v116, v0
	v_mov_b32_e32 v117, v0
	v_mov_b32_e32 v118, v0
	v_mov_b32_e32 v119, v0
	v_mov_b32_e32 v120, v0
	v_mov_b32_e32 v121, v0
	v_mov_b32_e32 v122, v0
	v_mov_b32_e32 v123, v0
	v_mov_b32_e32 v124, v0
	v_mov_b32_e32 v125, v0
	v_mov_b32_e32 v126, v0
	v_mov_b32_e32 v127, v0
.Lzskip_7:
.LBB0_1310:
	ds_read_b128 v[144:147], v155
	ds_read_b128 v[148:151], v155 offset:1024
	ds_read_b128 v[160:163], v155 offset:2048
	ds_read_b128 v[164:167], v155 offset:3072
	ds_read_b128 v[168:171], v156
	ds_read_b128 v[172:175], v156 offset:1024
	ds_read_b128 v[176:179], v156 offset:2048
	ds_read_b128 v[180:183], v156 offset:3072
	s_add_u32 s34, s30, 0xfffc0080
	s_addc_u32 s35, s31, -1
	s_cmp_eq_u32 s62, 12
	s_cselect_b32 s37, s23, s35
	s_cselect_b32 s36, s58, s34
	s_cselect_b32 s35, s21, s61
	s_cselect_b32 s34, s59, s60
	v_lshl_add_u64 v[204:205], s[30:31], 0, v[136:137]
	s_add_i32 m0, s29, 0xc000
	ds_read_b128 v[184:187], v157
	ds_read_b128 v[188:191], v157 offset:1024
	ds_read_b128 v[192:195], v157 offset:2048
	ds_read_b128 v[196:199], v157 offset:3072
	ds_read_b128 v[200:203], v157 offset:4096
	ds_read_b128 v[210:213], v157 offset:5120
	ds_read_b128 v[214:217], v157 offset:6144
	ds_read_b128 v[218:221], v157 offset:7168
	global_load_lds_dwordx4 v[204:205], off
	v_lshl_add_u64 v[204:205], s[30:31], 0, v[138:139]
	s_add_i32 m0, s29, 0xe000
	s_nop 0
	global_load_lds_dwordx4 v[204:205], off
	s_waitcnt vmcnt(8)
	s_waitcnt lgkmcnt(0)
	s_setprio 1
	s_barrier
	v_mfma_f32_16x16x32_bf16 v[124:127], v[144:147], v[184:187], v[124:127]
	v_mfma_f32_16x16x32_bf16 v[120:123], v[160:163], v[184:187], v[120:123]
	v_mfma_f32_16x16x32_bf16 v[116:119], v[144:147], v[192:195], v[116:119]
	v_mfma_f32_16x16x32_bf16 v[104:107], v[160:163], v[192:195], v[104:107]
	v_mfma_f32_16x16x32_bf16 v[92:95], v[144:147], v[200:203], v[92:95]
	v_mfma_f32_16x16x32_bf16 v[88:91], v[160:163], v[200:203], v[88:91]
	v_mfma_f32_16x16x32_bf16 v[76:79], v[144:147], v[214:217], v[76:79]
	v_mfma_f32_16x16x32_bf16 v[72:75], v[160:163], v[214:217], v[72:75]
	v_mfma_f32_16x16x32_bf16 v[124:127], v[148:151], v[188:191], v[124:127]
	v_mfma_f32_16x16x32_bf16 v[120:123], v[164:167], v[188:191], v[120:123]
	v_mfma_f32_16x16x32_bf16 v[116:119], v[148:151], v[196:199], v[116:119]
	v_mfma_f32_16x16x32_bf16 v[104:107], v[164:167], v[196:199], v[104:107]
	v_mfma_f32_16x16x32_bf16 v[92:95], v[148:151], v[210:213], v[92:95]
	v_mfma_f32_16x16x32_bf16 v[88:91], v[164:167], v[210:213], v[88:91]
	v_mfma_f32_16x16x32_bf16 v[76:79], v[148:151], v[218:221], v[76:79]
	v_mfma_f32_16x16x32_bf16 v[72:75], v[164:167], v[218:221], v[72:75]
	s_setprio 0
	s_setprio 1
	v_mfma_f32_16x16x32_bf16 v[112:115], v[168:171], v[184:187], v[112:115]
	v_mfma_f32_16x16x32_bf16 v[108:111], v[176:179], v[184:187], v[108:111]
	v_mfma_f32_16x16x32_bf16 v[100:103], v[168:171], v[192:195], v[100:103]
	v_mfma_f32_16x16x32_bf16 v[96:99], v[176:179], v[192:195], v[96:99]
	v_mfma_f32_16x16x32_bf16 v[84:87], v[168:171], v[200:203], v[84:87]
	v_mfma_f32_16x16x32_bf16 v[80:83], v[176:179], v[200:203], v[80:83]
	v_mfma_f32_16x16x32_bf16 v[68:71], v[168:171], v[214:217], v[68:71]
	v_mfma_f32_16x16x32_bf16 v[64:67], v[176:179], v[214:217], v[64:67]
	v_mfma_f32_16x16x32_bf16 v[112:115], v[172:175], v[188:191], v[112:115]
	v_mfma_f32_16x16x32_bf16 v[108:111], v[180:183], v[188:191], v[108:111]
	v_mfma_f32_16x16x32_bf16 v[100:103], v[172:175], v[196:199], v[100:103]
	v_mfma_f32_16x16x32_bf16 v[96:99], v[180:183], v[196:199], v[96:99]
	v_mfma_f32_16x16x32_bf16 v[84:87], v[172:175], v[210:213], v[84:87]
	v_mfma_f32_16x16x32_bf16 v[80:83], v[180:183], v[210:213], v[80:83]
	v_mfma_f32_16x16x32_bf16 v[68:71], v[172:175], v[218:221], v[68:71]
	v_mfma_f32_16x16x32_bf16 v[64:67], v[180:183], v[218:221], v[64:67]
	s_barrier
	s_setprio 0
	s_add_i32 s63, s52, s42
	v_lshl_add_u64 v[204:205], s[34:35], 0, v[130:131]
	s_mov_b32 m0, s63
	ds_read_b128 v[184:187], v157 offset:16384
	ds_read_b128 v[188:191], v157 offset:17408
	ds_read_b128 v[192:195], v157 offset:18432
	ds_read_b128 v[196:199], v157 offset:19456
	ds_read_b128 v[200:203], v157 offset:20480
	ds_read_b128 v[210:213], v157 offset:21504
	ds_read_b128 v[214:217], v157 offset:22528
	ds_read_b128 v[218:221], v157 offset:23552
	global_load_lds_dwordx4 v[204:205], off
	s_add_i32 m0, s63, 0x2000
	s_add_u32 s64, s34, 0x40000
	v_lshl_add_u64 v[222:223], s[34:35], 0, v[134:135]
	s_addc_u32 s65, s35, 0
	s_add_i32 s63, s53, s42
	global_load_lds_dwordx4 v[222:223], off
	v_lshl_add_u64 v[224:225], s[64:65], 0, v[130:131]
	s_mov_b32 m0, s63
	v_lshl_add_u64 v[226:227], s[36:37], 0, v[132:133]
	global_load_lds_dwordx4 v[224:225], off
	v_lshl_add_u64 v[224:225], s[64:65], 0, v[134:135]
	s_add_i32 m0, s63, 0x2000
	s_nop 0
	global_load_lds_dwordx4 v[224:225], off
	v_lshl_add_u64 v[224:225], s[36:37], 0, v[128:129]
	s_mov_b32 m0, s29
	s_nop 0
	global_load_lds_dwordx4 v[224:225], off
	s_mov_b32 m0, s43
	s_nop 0
	global_load_lds_dwordx4 v[226:227], off
	s_waitcnt vmcnt(8)
	s_waitcnt lgkmcnt(0)
	s_setprio 1
	s_barrier
	v_mfma_f32_16x16x32_bf16 v[60:63], v[144:147], v[184:187], v[60:63]
	v_mfma_f32_16x16x32_bf16 v[56:59], v[160:163], v[184:187], v[56:59]
	v_mfma_f32_16x16x32_bf16 v[44:47], v[144:147], v[192:195], v[44:47]
	v_mfma_f32_16x16x32_bf16 v[40:43], v[160:163], v[192:195], v[40:43]
	v_mfma_f32_16x16x32_bf16 v[28:31], v[144:147], v[200:203], v[28:31]
	v_mfma_f32_16x16x32_bf16 v[24:27], v[160:163], v[200:203], v[24:27]
	v_mfma_f32_16x16x32_bf16 v[12:15], v[144:147], v[214:217], v[12:15]
	v_mfma_f32_16x16x32_bf16 v[8:11], v[160:163], v[214:217], v[8:11]
	v_mfma_f32_16x16x32_bf16 v[60:63], v[148:151], v[188:191], v[60:63]
	v_mfma_f32_16x16x32_bf16 v[56:59], v[164:167], v[188:191], v[56:59]
	v_mfma_f32_16x16x32_bf16 v[44:47], v[148:151], v[196:199], v[44:47]
	v_mfma_f32_16x16x32_bf16 v[40:43], v[164:167], v[196:199], v[40:43]
	v_mfma_f32_16x16x32_bf16 v[28:31], v[148:151], v[210:213], v[28:31]
	v_mfma_f32_16x16x32_bf16 v[24:27], v[164:167], v[210:213], v[24:27]
	v_mfma_f32_16x16x32_bf16 v[12:15], v[148:151], v[218:221], v[12:15]
	v_mfma_f32_16x16x32_bf16 v[8:11], v[164:167], v[218:221], v[8:11]
	s_setprio 0
	s_setprio 1
	v_mfma_f32_16x16x32_bf16 v[52:55], v[168:171], v[184:187], v[52:55]
	v_mfma_f32_16x16x32_bf16 v[48:51], v[176:179], v[184:187], v[48:51]
	v_mfma_f32_16x16x32_bf16 v[36:39], v[168:171], v[192:195], v[36:39]
	v_mfma_f32_16x16x32_bf16 v[32:35], v[176:179], v[192:195], v[32:35]
	v_mfma_f32_16x16x32_bf16 v[20:23], v[168:171], v[200:203], v[20:23]
	v_mfma_f32_16x16x32_bf16 v[16:19], v[176:179], v[200:203], v[16:19]
	v_mfma_f32_16x16x32_bf16 v[4:7], v[168:171], v[214:217], v[4:7]
	v_mfma_f32_16x16x32_bf16 v[0:3], v[176:179], v[214:217], v[0:3]
	v_mfma_f32_16x16x32_bf16 v[52:55], v[172:175], v[188:191], v[52:55]
	v_mfma_f32_16x16x32_bf16 v[48:51], v[180:183], v[188:191], v[48:51]
	v_mfma_f32_16x16x32_bf16 v[36:39], v[172:175], v[196:199], v[36:39]
	v_mfma_f32_16x16x32_bf16 v[32:35], v[180:183], v[196:199], v[32:35]
	v_mfma_f32_16x16x32_bf16 v[20:23], v[172:175], v[210:213], v[20:23]
	v_mfma_f32_16x16x32_bf16 v[16:19], v[180:183], v[210:213], v[16:19]
	v_mfma_f32_16x16x32_bf16 v[4:7], v[172:175], v[218:221], v[4:7]
	v_mfma_f32_16x16x32_bf16 v[0:3], v[180:183], v[218:221], v[0:3]
	s_barrier
	s_setprio 0
	s_add_i32 s63, 0, 0x18000
	v_add_u32_e32 v159, s63, v153
	s_add_i32 s64, 0, 0x1c000
	ds_read_b128 v[144:147], v159
	ds_read_b128 v[148:151], v159 offset:1024
	ds_read_b128 v[160:163], v159 offset:2048
	ds_read_b128 v[164:167], v159 offset:3072
	v_add_u32_e32 v159, s64, v153
	ds_read_b128 v[168:171], v159
	ds_read_b128 v[172:175], v159 offset:1024
	ds_read_b128 v[176:179], v159 offset:2048
	ds_read_b128 v[180:183], v159 offset:3072
	s_add_u32 s36, s36, 0x40000
	s_addc_u32 s37, s37, 0
	s_mov_b32 m0, s44
	v_lshl_add_u64 v[228:229], s[36:37], 0, v[128:129]
	ds_read_b128 v[184:187], v157 offset:32768
	ds_read_b128 v[188:191], v157 offset:33792
	ds_read_b128 v[192:195], v157 offset:34816
	ds_read_b128 v[196:199], v157 offset:35840
	ds_read_b128 v[200:203], v157 offset:36864
	ds_read_b128 v[210:213], v157 offset:37888
	ds_read_b128 v[214:217], v157 offset:38912
	ds_read_b128 v[218:221], v157 offset:39936
	global_load_lds_dwordx4 v[228:229], off
	v_lshl_add_u64 v[228:229], s[36:37], 0, v[132:133]
	s_mov_b32 m0, s45
	s_nop 0
	global_load_lds_dwordx4 v[228:229], off
	s_waitcnt vmcnt(8)
	s_waitcnt lgkmcnt(0)
	s_setprio 1
	s_barrier
	v_mfma_f32_16x16x32_bf16 v[124:127], v[144:147], v[184:187], v[124:127]
	v_mfma_f32_16x16x32_bf16 v[120:123], v[160:163], v[184:187], v[120:123]
	v_mfma_f32_16x16x32_bf16 v[116:119], v[144:147], v[192:195], v[116:119]
	v_mfma_f32_16x16x32_bf16 v[104:107], v[160:163], v[192:195], v[104:107]
	v_mfma_f32_16x16x32_bf16 v[92:95], v[144:147], v[200:203], v[92:95]
	v_mfma_f32_16x16x32_bf16 v[88:91], v[160:163], v[200:203], v[88:91]
	v_mfma_f32_16x16x32_bf16 v[76:79], v[144:147], v[214:217], v[76:79]
	v_mfma_f32_16x16x32_bf16 v[72:75], v[160:163], v[214:217], v[72:75]
	v_mfma_f32_16x16x32_bf16 v[124:127], v[148:151], v[188:191], v[124:127]
	v_mfma_f32_16x16x32_bf16 v[120:123], v[164:167], v[188:191], v[120:123]
	v_mfma_f32_16x16x32_bf16 v[116:119], v[148:151], v[196:199], v[116:119]
	v_mfma_f32_16x16x32_bf16 v[104:107], v[164:167], v[196:199], v[104:107]
	v_mfma_f32_16x16x32_bf16 v[92:95], v[148:151], v[210:213], v[92:95]
	v_mfma_f32_16x16x32_bf16 v[88:91], v[164:167], v[210:213], v[88:91]
	v_mfma_f32_16x16x32_bf16 v[76:79], v[148:151], v[218:221], v[76:79]
	v_mfma_f32_16x16x32_bf16 v[72:75], v[164:167], v[218:221], v[72:75]
	s_setprio 0
	s_setprio 1
	v_mfma_f32_16x16x32_bf16 v[112:115], v[168:171], v[184:187], v[112:115]
	v_mfma_f32_16x16x32_bf16 v[108:111], v[176:179], v[184:187], v[108:111]
	v_mfma_f32_16x16x32_bf16 v[100:103], v[168:171], v[192:195], v[100:103]
	v_mfma_f32_16x16x32_bf16 v[96:99], v[176:179], v[192:195], v[96:99]
	v_mfma_f32_16x16x32_bf16 v[84:87], v[168:171], v[200:203], v[84:87]
	v_mfma_f32_16x16x32_bf16 v[80:83], v[176:179], v[200:203], v[80:83]
	v_mfma_f32_16x16x32_bf16 v[68:71], v[168:171], v[214:217], v[68:71]
	v_mfma_f32_16x16x32_bf16 v[64:67], v[176:179], v[214:217], v[64:67]
	v_mfma_f32_16x16x32_bf16 v[112:115], v[172:175], v[188:191], v[112:115]
	v_mfma_f32_16x16x32_bf16 v[108:111], v[180:183], v[188:191], v[108:111]
	v_mfma_f32_16x16x32_bf16 v[100:103], v[172:175], v[196:199], v[100:103]
	v_mfma_f32_16x16x32_bf16 v[96:99], v[180:183], v[196:199], v[96:99]
	v_mfma_f32_16x16x32_bf16 v[84:87], v[172:175], v[210:213], v[84:87]
	v_mfma_f32_16x16x32_bf16 v[80:83], v[180:183], v[210:213], v[80:83]
	v_mfma_f32_16x16x32_bf16 v[68:71], v[172:175], v[218:221], v[68:71]
	v_mfma_f32_16x16x32_bf16 v[64:67], v[180:183], v[218:221], v[64:67]
	s_barrier
	s_setprio 0
	s_add_i32 s36, s63, s42
	v_lshl_add_u64 v[204:205], v[204:205], 0, s[8:9]
	s_mov_b32 m0, s36
	ds_read_b128 v[184:187], v157 offset:49152
	ds_read_b128 v[188:191], v157 offset:50176
	ds_read_b128 v[192:195], v157 offset:51200
	ds_read_b128 v[196:199], v157 offset:52224
	ds_read_b128 v[200:203], v157 offset:53248
	ds_read_b128 v[210:213], v157 offset:54272
	ds_read_b128 v[214:217], v157 offset:55296
	ds_read_b128 v[218:221], v157 offset:56320
	global_load_lds_dwordx4 v[204:205], off
	s_add_i32 m0, s36, 0x2000
	s_add_u32 s34, s34, 0x40080
	v_lshl_add_u64 v[204:205], v[222:223], 0, s[8:9]
	s_addc_u32 s35, s35, 0
	s_add_i32 s36, s64, s42
	global_load_lds_dwordx4 v[204:205], off
	v_lshl_add_u64 v[204:205], s[34:35], 0, v[130:131]
	s_mov_b32 m0, s36
	s_nop 0
	global_load_lds_dwordx4 v[204:205], off
	v_lshl_add_u64 v[204:205], s[34:35], 0, v[134:135]
	s_add_i32 m0, s36, 0x2000
	s_nop 0
	global_load_lds_dwordx4 v[204:205], off
	v_lshl_add_u64 v[204:205], v[224:225], 0, s[8:9]
	s_mov_b32 m0, s49
	s_nop 0
	global_load_lds_dwordx4 v[204:205], off
	v_lshl_add_u64 v[204:205], v[226:227], 0, s[8:9]
	s_mov_b32 m0, s50
	s_nop 0
	global_load_lds_dwordx4 v[204:205], off
	s_waitcnt vmcnt(8)
	s_waitcnt lgkmcnt(0)
	s_setprio 1
	s_barrier
	v_mfma_f32_16x16x32_bf16 v[60:63], v[144:147], v[184:187], v[60:63]
	v_mfma_f32_16x16x32_bf16 v[56:59], v[160:163], v[184:187], v[56:59]
	v_mfma_f32_16x16x32_bf16 v[44:47], v[144:147], v[192:195], v[44:47]
	v_mfma_f32_16x16x32_bf16 v[40:43], v[160:163], v[192:195], v[40:43]
	v_mfma_f32_16x16x32_bf16 v[28:31], v[144:147], v[200:203], v[28:31]
	v_mfma_f32_16x16x32_bf16 v[24:27], v[160:163], v[200:203], v[24:27]
	v_mfma_f32_16x16x32_bf16 v[12:15], v[144:147], v[214:217], v[12:15]
	v_mfma_f32_16x16x32_bf16 v[8:11], v[160:163], v[214:217], v[8:11]
	v_mfma_f32_16x16x32_bf16 v[60:63], v[148:151], v[188:191], v[60:63]
	v_mfma_f32_16x16x32_bf16 v[56:59], v[164:167], v[188:191], v[56:59]
	v_mfma_f32_16x16x32_bf16 v[44:47], v[148:151], v[196:199], v[44:47]
	v_mfma_f32_16x16x32_bf16 v[40:43], v[164:167], v[196:199], v[40:43]
	v_mfma_f32_16x16x32_bf16 v[28:31], v[148:151], v[210:213], v[28:31]
	v_mfma_f32_16x16x32_bf16 v[24:27], v[164:167], v[210:213], v[24:27]
	v_mfma_f32_16x16x32_bf16 v[12:15], v[148:151], v[218:221], v[12:15]
	v_mfma_f32_16x16x32_bf16 v[8:11], v[164:167], v[218:221], v[8:11]
	s_setprio 0
	s_setprio 1
	v_mfma_f32_16x16x32_bf16 v[52:55], v[168:171], v[184:187], v[52:55]
	v_mfma_f32_16x16x32_bf16 v[48:51], v[176:179], v[184:187], v[48:51]
	v_mfma_f32_16x16x32_bf16 v[36:39], v[168:171], v[192:195], v[36:39]
	v_mfma_f32_16x16x32_bf16 v[32:35], v[176:179], v[192:195], v[32:35]
	v_mfma_f32_16x16x32_bf16 v[20:23], v[168:171], v[200:203], v[20:23]
	v_mfma_f32_16x16x32_bf16 v[16:19], v[176:179], v[200:203], v[16:19]
	v_mfma_f32_16x16x32_bf16 v[4:7], v[168:171], v[214:217], v[4:7]
	v_mfma_f32_16x16x32_bf16 v[0:3], v[176:179], v[214:217], v[0:3]
	v_mfma_f32_16x16x32_bf16 v[52:55], v[172:175], v[188:191], v[52:55]
	v_mfma_f32_16x16x32_bf16 v[48:51], v[180:183], v[188:191], v[48:51]
	v_mfma_f32_16x16x32_bf16 v[36:39], v[172:175], v[196:199], v[36:39]
	v_mfma_f32_16x16x32_bf16 v[32:35], v[180:183], v[196:199], v[32:35]
	v_mfma_f32_16x16x32_bf16 v[20:23], v[172:175], v[210:213], v[20:23]
	v_mfma_f32_16x16x32_bf16 v[16:19], v[180:183], v[210:213], v[16:19]
	v_mfma_f32_16x16x32_bf16 v[4:7], v[172:175], v[218:221], v[4:7]
	v_mfma_f32_16x16x32_bf16 v[0:3], v[180:183], v[218:221], v[0:3]
	s_barrier
	s_setprio 0
	s_add_i32 s62, s62, 2
	s_add_u32 s30, s30, 0x100
	s_addc_u32 s31, s31, 0
	s_add_u32 s60, s60, 0x100
	s_addc_u32 s61, s61, 0
	s_cmp_gt_u32 s62, 13
	s_cbranch_scc0 .LBB0_1310
	s_and_b64 vcc, exec, s[10:11]
	s_cbranch_vccz .LBB0_1313
	s_barrier

.LBB0_1379:
	s_lshl_b32 s1, s1, 5
	s_mov_b64 s[12:13], 0x80
	s_and_b32 s16, s1, 0x60
	s_add_i32 m0, s27, 0x18000
	v_lshl_add_u64 v[6:7], v[6:7], 0, s[12:13]
	s_lshl_b32 s14, s0, 13
	s_lshl_b32 s1, s16, 7
	s_mov_b32 s98, 1
	v_mov_b32_e32 v32, 0
	v_mov_b32_e32 v33, 0
	v_mov_b32_e32 v34, 0
	v_mov_b32_e32 v35, 0
	v_mov_b32_e32 v36, 0
	v_mov_b32_e32 v37, 0
	v_mov_b32_e32 v38, 0
	v_mov_b32_e32 v39, 0
	v_mov_b32_e32 v40, 0
	v_mov_b32_e32 v41, 0
	v_mov_b32_e32 v42, 0
	v_mov_b32_e32 v43, 0
	v_mov_b32_e32 v44, 0
	v_mov_b32_e32 v45, 0
	v_mov_b32_e32 v46, 0
	v_mov_b32_e32 v47, 0
	v_mov_b32_e32 v48, 0
	v_mov_b32_e32 v49, 0
	v_mov_b32_e32 v50, 0
	v_mov_b32_e32 v51, 0
	v_mov_b32_e32 v52, 0
	v_mov_b32_e32 v53, 0
	v_mov_b32_e32 v54, 0
	v_mov_b32_e32 v55, 0
	v_mov_b32_e32 v56, 0
	v_mov_b32_e32 v57, 0
	v_mov_b32_e32 v58, 0
	v_mov_b32_e32 v59, 0
	v_mov_b32_e32 v60, 0
	v_mov_b32_e32 v61, 0
	v_mov_b32_e32 v62, 0
	v_mov_b32_e32 v63, 0
	v_mov_b32_e32 v64, 0
	v_mov_b32_e32 v65, 0
	v_mov_b32_e32 v66, 0
	v_mov_b32_e32 v67, 0
	v_mov_b32_e32 v68, 0
	v_mov_b32_e32 v69, 0
	v_mov_b32_e32 v70, 0
	v_mov_b32_e32 v71, 0
	v_mov_b32_e32 v72, 0
	v_mov_b32_e32 v73, 0
	v_mov_b32_e32 v74, 0
	v_mov_b32_e32 v75, 0
	v_mov_b32_e32 v76, 0
	v_mov_b32_e32 v77, 0
	v_mov_b32_e32 v78, 0
	v_mov_b32_e32 v79, 0
	v_mov_b32_e32 v80, 0
	v_mov_b32_e32 v81, 0
	v_mov_b32_e32 v82, 0
	v_mov_b32_e32 v83, 0
	v_mov_b32_e32 v84, 0
	v_mov_b32_e32 v85, 0
	v_mov_b32_e32 v86, 0
	v_mov_b32_e32 v87, 0
	v_mov_b32_e32 v88, 0
	v_mov_b32_e32 v89, 0
	v_mov_b32_e32 v90, 0
	v_mov_b32_e32 v91, 0
	v_mov_b32_e32 v92, 0
	v_mov_b32_e32 v93, 0
	v_mov_b32_e32 v94, 0
	v_mov_b32_e32 v95, 0
	v_mov_b32_e32 v96, 0
	v_mov_b32_e32 v97, 0
	v_mov_b32_e32 v98, 0
	v_mov_b32_e32 v99, 0
	v_mov_b32_e32 v100, 0
	v_mov_b32_e32 v101, 0
	v_mov_b32_e32 v102, 0
	v_mov_b32_e32 v103, 0
	v_mov_b32_e32 v104, 0
	v_mov_b32_e32 v105, 0
	v_mov_b32_e32 v106, 0
	v_mov_b32_e32 v107, 0
	v_mov_b32_e32 v108, 0
	v_mov_b32_e32 v109, 0
	v_mov_b32_e32 v110, 0
	v_mov_b32_e32 v111, 0
	v_mov_b32_e32 v112, 0
	v_mov_b32_e32 v113, 0
	v_mov_b32_e32 v114, 0
	v_mov_b32_e32 v115, 0
	v_mov_b32_e32 v116, 0
	v_mov_b32_e32 v117, 0
	v_mov_b32_e32 v118, 0
	v_mov_b32_e32 v119, 0
	v_mov_b32_e32 v120, 0
	v_mov_b32_e32 v121, 0
	v_mov_b32_e32 v122, 0
	v_mov_b32_e32 v123, 0
	v_mov_b32_e32 v124, 0
	v_mov_b32_e32 v125, 0
	v_mov_b32_e32 v126, 0
	v_mov_b32_e32 v127, 0
	s_nop 0
	s_nop 0
	s_nop 0
	s_nop 0
	s_nop 0
	s_nop 0
	s_nop 0
	s_nop 0
	s_nop 0
	s_nop 0
	s_nop 0
	s_nop 0
	s_waitcnt vmcnt(2)
	s_barrier
	global_load_lds_dwordx4 v[6:7], off
	v_lshl_add_u64 v[4:5], v[4:5], 0, s[12:13]
	s_add_i32 m0, s27, 0x1a000
	s_add_i32 s45, s27, 0x8000
	s_add_i32 s48, s27, 0xa000
	global_load_lds_dwordx4 v[4:5], off
	v_lshl_add_u64 v[0:1], v[0:1], 0, s[12:13]
	s_mov_b32 m0, s45
	s_add_u32 s4, s30, 0x100080
	global_load_lds_dwordx4 v[0:1], off
	v_lshl_add_u64 v[0:1], v[2:3], 0, s[12:13]
	s_mov_b32 m0, s48
	s_addc_u32 s5, s31, 0
	global_load_lds_dwordx4 v[0:1], off
	s_add_i32 m0, s27, 0x1c000
	v_lshl_add_u64 v[0:1], s[4:5], 0, v[176:177]
	global_load_lds_dwordx4 v[0:1], off
	v_lshl_add_u64 v[0:1], s[4:5], 0, v[178:179]
	s_add_i32 m0, s27, 0x1e000
	s_mov_b64 s[4:5], 0x100080
	global_load_lds_dwordx4 v[0:1], off
	v_bfe_u32 v0, v8, 4, 2
	v_and_b32_e32 v1, 15, v8
	v_lshlrev_b32_e32 v2, 4, v0
	v_lshl_or_b32 v209, s0, 6, v1
	v_lshl_or_b32 v1, v1, 6, v2
	v_lshlrev_b32_e32 v2, 2, v8
	v_and_b32_e32 v2, 32, v2
	v_bitop3_b32 v210, v1, s1, v2 bitop3:0xde
	v_cmp_eq_u32_e64 s[0:1], 0, v0
	v_lshl_or_b32 v211, v0, 2, s16
	v_lshlrev_b32_e32 v0, 15, v9
	v_and_b32_e32 v0, 0x7fff0000, v0
	v_lshl_add_u32 v0, v10, 12, v0
	v_or_b32_e32 v0, v0, v11
	v_bitop3_b32 v3, v1, s14, v2 bitop3:0xde
	v_add_lshl_u32 v0, v0, v12, 1
	v_mov_b32_e32 v1, v177
	v_lshl_add_u64 v[180:181], v[0:1], 0, s[4:5]
	v_lshlrev_b32_e32 v0, 15, v13
	v_and_b32_e32 v0, 0x7fff0000, v0
	v_lshl_add_u32 v0, v14, 12, v0
	s_waitcnt vmcnt(6)
	s_cmpk_lt_u32 s3, 0x100
	v_or_b32_e32 v0, v0, v15
	s_cselect_b64 s[14:15], -1, 0
	v_add_lshl_u32 v0, v0, v16, 1
	s_add_i32 s51, 0, 0x10000
	s_add_i32 s53, 0, 0x14000
	s_ashr_i32 s49, s39, 31
	s_ashr_i32 s50, s38, 31
	v_lshl_add_u64 v[182:183], v[0:1], 0, s[4:5]
	v_mov_b64_e32 v[184:185], 0x100
	v_mov_b64_e32 v[186:187], 0xff
	v_add_u32_e32 v212, s51, v210
	v_add_u32_e32 v213, s53, v210
	v_add_u32_e32 v214, 0, v3
	s_barrier
	s_branch .LBB0_1382

.LBB0_1388:
	s_ashr_i32 s19, s18, 31
	s_lshl_b64 s[20:21], s[18:19], 21
	s_add_u32 s20, s80, s20
	s_addc_u32 s21, s81, s21
	s_and_b64 s[22:23], s[4:5], exec
	s_cselect_b32 s3, s21, s29
	s_cselect_b32 s19, s20, s28
	s_ashr_i32 s17, s16, 31
	s_lshl_b64 s[22:23], s[16:17], 21
	s_add_u32 s22, s33, s22
	s_addc_u32 s23, s52, s23
	s_and_b64 s[34:35], s[4:5], exec
	s_cselect_b32 s17, s23, s31
	s_cselect_b32 s25, s22, s30
	s_add_u32 s54, s30, 0x100
	v_mov_b32_e32 v0, 0
	s_addc_u32 s55, s31, 0
	s_mov_b32 s56, -2
	s_waitcnt lgkmcnt(0)
	v_mov_b32_e32 v1, v0
	v_mov_b32_e32 v2, v0
	v_mov_b32_e32 v3, v0
	v_mov_b32_e32 v4, v0
	v_mov_b32_e32 v5, v0
	v_mov_b32_e32 v6, v0
	v_mov_b32_e32 v7, v0
	v_mov_b32_e32 v8, v0
	v_mov_b32_e32 v9, v0
	v_mov_b32_e32 v10, v0
	v_mov_b32_e32 v11, v0
	v_mov_b32_e32 v12, v0
	v_mov_b32_e32 v13, v0
	v_mov_b32_e32 v14, v0
	v_mov_b32_e32 v15, v0
	v_mov_b32_e32 v16, v0
	v_mov_b32_e32 v17, v0
	v_mov_b32_e32 v18, v0
	v_mov_b32_e32 v19, v0
	v_mov_b32_e32 v20, v0
	v_mov_b32_e32 v21, v0
	v_mov_b32_e32 v22, v0
	v_mov_b32_e32 v23, v0
	v_mov_b32_e32 v24, v0
	v_mov_b32_e32 v25, v0
	v_mov_b32_e32 v26, v0
	v_mov_b32_e32 v27, v0
	v_mov_b32_e32 v28, v0
	v_mov_b32_e32 v29, v0
	v_mov_b32_e32 v30, v0
	v_mov_b32_e32 v31, v0
	s_cmp_eq_u32 s98, 1
	s_mov_b32 s98, 0
	s_cbranch_scc1 .Lzskip_8
	v_mov_b32_e32 v32, v0
	v_mov_b32_e32 v33, v0
	v_mov_b32_e32 v34, v0
	v_mov_b32_e32 v35, v0
	v_mov_b32_e32 v36, v0
	v_mov_b32_e32 v37, v0
	v_mov_b32_e32 v38, v0
	v_mov_b32_e32 v39, v0
	v_mov_b32_e32 v40, v0
	v_mov_b32_e32 v41, v0
	v_mov_b32_e32 v42, v0
	v_mov_b32_e32 v43, v0
	v_mov_b32_e32 v44, v0
	v_mov_b32_e32 v45, v0
	v_mov_b32_e32 v46, v0
	v_mov_b32_e32 v47, v0
	v_mov_b32_e32 v48, v0
	v_mov_b32_e32 v49, v0
	v_mov_b32_e32 v50, v0
	v_mov_b32_e32 v51, v0
	v_mov_b32_e32 v52, v0
	v_mov_b32_e32 v53, v0
	v_mov_b32_e32 v54, v0
	v_mov_b32_e32 v55, v0
	v_mov_b32_e32 v56, v0
	v_mov_b32_e32 v57, v0
	v_mov_b32_e32 v58, v0
	v_mov_b32_e32 v59, v0
	v_mov_b32_e32 v60, v0
	v_mov_b32_e32 v61, v0
	v_mov_b32_e32 v62, v0
	v_mov_b32_e32 v63, v0
	v_mov_b32_e32 v64, v0
	v_mov_b32_e32 v65, v0
	v_mov_b32_e32 v66, v0
	v_mov_b32_e32 v67, v0
	v_mov_b32_e32 v68, v0
	v_mov_b32_e32 v69, v0
	v_mov_b32_e32 v70, v0
	v_mov_b32_e32 v71, v0
	v_mov_b32_e32 v72, v0
	v_mov_b32_e32 v73, v0
	v_mov_b32_e32 v74, v0
	v_mov_b32_e32 v75, v0
	v_mov_b32_e32 v76, v0
	v_mov_b32_e32 v77, v0
	v_mov_b32_e32 v78, v0
	v_mov_b32_e32 v79, v0
	v_mov_b32_e32 v80, v0
	v_mov_b32_e32 v81, v0
	v_mov_b32_e32 v82, v0
	v_mov_b32_e32 v83, v0
	v_mov_b32_e32 v84, v0
	v_mov_b32_e32 v85, v0
	v_mov_b32_e32 v86, v0
	v_mov_b32_e32 v87, v0
	v_mov_b32_e32 v88, v0
	v_mov_b32_e32 v89, v0
	v_mov_b32_e32 v90, v0
	v_mov_b32_e32 v91, v0
	v_mov_b32_e32 v92, v0
	v_mov_b32_e32 v93, v0
	v_mov_b32_e32 v94, v0
	v_mov_b32_e32 v95, v0
	v_mov_b32_e32 v96, v0
	v_mov_b32_e32 v97, v0
	v_mov_b32_e32 v98, v0
	v_mov_b32_e32 v99, v0
	v_mov_b32_e32 v100, v0
	v_mov_b32_e32 v101, v0
	v_mov_b32_e32 v102, v0
	v_mov_b32_e32 v103, v0
	v_mov_b32_e32 v104, v0
	v_mov_b32_e32 v105, v0
	v_mov_b32_e32 v106, v0
	v_mov_b32_e32 v107, v0
	v_mov_b32_e32 v108, v0
	v_mov_b32_e32 v109, v0
	v_mov_b32_e32 v110, v0
	v_mov_b32_e32 v111, v0
	v_mov_b32_e32 v112, v0
	v_mov_b32_e32 v113, v0
	v_mov_b32_e32 v114, v0
	v_mov_b32_e32 v115, v0
	v_mov_b32_e32 v116, v0
	v_mov_b32_e32 v117, v0
	v_mov_b32_e32 v118, v0
	v_mov_b32_e32 v119, v0
	v_mov_b32_e32 v120, v0
	v_mov_b32_e32 v121, v0
	v_mov_b32_e32 v122, v0
	v_mov_b32_e32 v123, v0
	v_mov_b32_e32 v124, v0
	v_mov_b32_e32 v125, v0
	v_mov_b32_e32 v126, v0
	v_mov_b32_e32 v127, v0
.Lzskip_8:
.LBB0_1389:
	ds_read_b128 v[128:131], v212
	ds_read_b128 v[132:135], v212 offset:1024
	ds_read_b128 v[136:139], v212 offset:2048
	ds_read_b128 v[140:143], v212 offset:3072
	ds_read_b128 v[144:147], v213
	ds_read_b128 v[148:151], v213 offset:1024
	ds_read_b128 v[152:155], v213 offset:2048
	ds_read_b128 v[156:159], v213 offset:3072
	s_add_u32 s30, s28, 0x100
	s_addc_u32 s31, s29, 0
	s_cmp_eq_u32 s56, 60
	s_cselect_b32 s37, s3, s31
	s_cselect_b32 s36, s19, s30
	s_cselect_b32 s35, s17, s55
	s_cselect_b32 s34, s25, s54
	v_lshl_add_u64 v[204:205], s[28:29], 0, v[180:181]
	s_add_i32 m0, s27, 0xc000
	ds_read_b128 v[160:163], v214
	ds_read_b128 v[164:167], v214 offset:1024
	ds_read_b128 v[168:171], v214 offset:2048
	ds_read_b128 v[172:175], v214 offset:3072
	ds_read_b128 v[188:191], v214 offset:4096
	ds_read_b128 v[192:195], v214 offset:5120
	ds_read_b128 v[196:199], v214 offset:6144
	ds_read_b128 v[200:203], v214 offset:7168
	global_load_lds_dwordx4 v[204:205], off
	v_lshl_add_u64 v[204:205], s[28:29], 0, v[182:183]
	s_add_i32 m0, s27, 0xe000
	s_nop 0
	global_load_lds_dwordx4 v[204:205], off
	s_waitcnt vmcnt(8)
	s_waitcnt lgkmcnt(0)
	s_setprio 1
	s_barrier
	v_mfma_f32_16x16x32_bf16 v[124:127], v[128:131], v[160:163], v[124:127]
	v_mfma_f32_16x16x32_bf16 v[120:123], v[136:139], v[160:163], v[120:123]
	v_mfma_f32_16x16x32_bf16 v[108:111], v[128:131], v[168:171], v[108:111]
	v_mfma_f32_16x16x32_bf16 v[104:107], v[136:139], v[168:171], v[104:107]
	v_mfma_f32_16x16x32_bf16 v[92:95], v[128:131], v[188:191], v[92:95]
	v_mfma_f32_16x16x32_bf16 v[88:91], v[136:139], v[188:191], v[88:91]
	v_mfma_f32_16x16x32_bf16 v[76:79], v[128:131], v[196:199], v[76:79]
	v_mfma_f32_16x16x32_bf16 v[72:75], v[136:139], v[196:199], v[72:75]
	v_mfma_f32_16x16x32_bf16 v[124:127], v[132:135], v[164:167], v[124:127]
	v_mfma_f32_16x16x32_bf16 v[120:123], v[140:143], v[164:167], v[120:123]
	v_mfma_f32_16x16x32_bf16 v[108:111], v[132:135], v[172:175], v[108:111]
	v_mfma_f32_16x16x32_bf16 v[104:107], v[140:143], v[172:175], v[104:107]
	v_mfma_f32_16x16x32_bf16 v[92:95], v[132:135], v[192:195], v[92:95]
	v_mfma_f32_16x16x32_bf16 v[88:91], v[140:143], v[192:195], v[88:91]
	v_mfma_f32_16x16x32_bf16 v[76:79], v[132:135], v[200:203], v[76:79]
	v_mfma_f32_16x16x32_bf16 v[72:75], v[140:143], v[200:203], v[72:75]
	s_setprio 0
	s_setprio 1
	v_mfma_f32_16x16x32_bf16 v[116:119], v[144:147], v[160:163], v[116:119]
	v_mfma_f32_16x16x32_bf16 v[112:115], v[152:155], v[160:163], v[112:115]
	v_mfma_f32_16x16x32_bf16 v[100:103], v[144:147], v[168:171], v[100:103]
	v_mfma_f32_16x16x32_bf16 v[96:99], v[152:155], v[168:171], v[96:99]
	v_mfma_f32_16x16x32_bf16 v[84:87], v[144:147], v[188:191], v[84:87]
	v_mfma_f32_16x16x32_bf16 v[80:83], v[152:155], v[188:191], v[80:83]
	v_mfma_f32_16x16x32_bf16 v[68:71], v[144:147], v[196:199], v[68:71]
	v_mfma_f32_16x16x32_bf16 v[64:67], v[152:155], v[196:199], v[64:67]
	v_mfma_f32_16x16x32_bf16 v[116:119], v[148:151], v[164:167], v[116:119]
	v_mfma_f32_16x16x32_bf16 v[112:115], v[156:159], v[164:167], v[112:115]
	v_mfma_f32_16x16x32_bf16 v[100:103], v[148:151], v[172:175], v[100:103]
	v_mfma_f32_16x16x32_bf16 v[96:99], v[156:159], v[172:175], v[96:99]
	v_mfma_f32_16x16x32_bf16 v[84:87], v[148:151], v[192:195], v[84:87]
	v_mfma_f32_16x16x32_bf16 v[80:83], v[156:159], v[192:195], v[80:83]
	v_mfma_f32_16x16x32_bf16 v[68:71], v[148:151], v[200:203], v[68:71]
	v_mfma_f32_16x16x32_bf16 v[64:67], v[156:159], v[200:203], v[64:67]
	s_barrier
	s_setprio 0
	s_add_i32 s28, s51, s40
	v_lshl_add_u64 v[204:205], s[34:35], 0, v[176:177]
	s_mov_b32 m0, s28
	ds_read_b128 v[160:163], v214 offset:16384
	ds_read_b128 v[164:167], v214 offset:17408
	ds_read_b128 v[168:171], v214 offset:18432
	ds_read_b128 v[172:175], v214 offset:19456
	ds_read_b128 v[188:191], v214 offset:20480
	ds_read_b128 v[192:195], v214 offset:21504
	ds_read_b128 v[196:199], v214 offset:22528
	ds_read_b128 v[200:203], v214 offset:23552
	global_load_lds_dwordx4 v[204:205], off
	s_add_i32 m0, s28, 0x2000
	s_add_u32 s28, s34, 0x100000
	v_lshl_add_u64 v[216:217], s[34:35], 0, v[178:179]
	s_addc_u32 s29, s35, 0
	s_add_i32 s57, s53, s40
	global_load_lds_dwordx4 v[216:217], off
	v_lshl_add_u64 v[218:219], s[28:29], 0, v[176:177]
	s_mov_b32 m0, s57
	v_lshl_add_u64 v[220:221], s[36:37], 0, v[178:179]
	global_load_lds_dwordx4 v[218:219], off
	v_lshl_add_u64 v[218:219], s[28:29], 0, v[178:179]
	s_add_i32 m0, s57, 0x2000
	s_nop 0
	global_load_lds_dwordx4 v[218:219], off
	v_lshl_add_u64 v[218:219], s[36:37], 0, v[176:177]
	s_mov_b32 m0, s27
	s_nop 0
	global_load_lds_dwordx4 v[218:219], off
	s_mov_b32 m0, s41
	s_nop 0
	global_load_lds_dwordx4 v[220:221], off
	s_waitcnt vmcnt(8)
	s_waitcnt lgkmcnt(0)
	s_setprio 1
	s_barrier
	v_mfma_f32_16x16x32_bf16 v[60:63], v[128:131], v[160:163], v[60:63]
	v_mfma_f32_16x16x32_bf16 v[56:59], v[136:139], v[160:163], v[56:59]
	v_mfma_f32_16x16x32_bf16 v[44:47], v[128:131], v[168:171], v[44:47]
	v_mfma_f32_16x16x32_bf16 v[40:43], v[136:139], v[168:171], v[40:43]
	v_mfma_f32_16x16x32_bf16 v[28:31], v[128:131], v[188:191], v[28:31]
	v_mfma_f32_16x16x32_bf16 v[24:27], v[136:139], v[188:191], v[24:27]
	v_mfma_f32_16x16x32_bf16 v[12:15], v[128:131], v[196:199], v[12:15]
	v_mfma_f32_16x16x32_bf16 v[8:11], v[136:139], v[196:199], v[8:11]
	v_mfma_f32_16x16x32_bf16 v[60:63], v[132:135], v[164:167], v[60:63]
	v_mfma_f32_16x16x32_bf16 v[56:59], v[140:143], v[164:167], v[56:59]
	v_mfma_f32_16x16x32_bf16 v[44:47], v[132:135], v[172:175], v[44:47]
	v_mfma_f32_16x16x32_bf16 v[40:43], v[140:143], v[172:175], v[40:43]
	v_mfma_f32_16x16x32_bf16 v[28:31], v[132:135], v[192:195], v[28:31]
	v_mfma_f32_16x16x32_bf16 v[24:27], v[140:143], v[192:195], v[24:27]
	v_mfma_f32_16x16x32_bf16 v[12:15], v[132:135], v[200:203], v[12:15]
	v_mfma_f32_16x16x32_bf16 v[8:11], v[140:143], v[200:203], v[8:11]
	s_setprio 0
	s_setprio 1
	v_mfma_f32_16x16x32_bf16 v[52:55], v[144:147], v[160:163], v[52:55]
	v_mfma_f32_16x16x32_bf16 v[48:51], v[152:155], v[160:163], v[48:51]
	v_mfma_f32_16x16x32_bf16 v[36:39], v[144:147], v[168:171], v[36:39]
	v_mfma_f32_16x16x32_bf16 v[32:35], v[152:155], v[168:171], v[32:35]
	v_mfma_f32_16x16x32_bf16 v[20:23], v[144:147], v[188:191], v[20:23]
	v_mfma_f32_16x16x32_bf16 v[16:19], v[152:155], v[188:191], v[16:19]
	v_mfma_f32_16x16x32_bf16 v[4:7], v[144:147], v[196:199], v[4:7]
	v_mfma_f32_16x16x32_bf16 v[0:3], v[152:155], v[196:199], v[0:3]
	v_mfma_f32_16x16x32_bf16 v[52:55], v[148:151], v[164:167], v[52:55]
	v_mfma_f32_16x16x32_bf16 v[48:51], v[156:159], v[164:167], v[48:51]
	v_mfma_f32_16x16x32_bf16 v[36:39], v[148:151], v[172:175], v[36:39]
	v_mfma_f32_16x16x32_bf16 v[32:35], v[156:159], v[172:175], v[32:35]
	v_mfma_f32_16x16x32_bf16 v[20:23], v[148:151], v[192:195], v[20:23]
	v_mfma_f32_16x16x32_bf16 v[16:19], v[156:159], v[192:195], v[16:19]
	v_mfma_f32_16x16x32_bf16 v[4:7], v[148:151], v[200:203], v[4:7]
	v_mfma_f32_16x16x32_bf16 v[0:3], v[156:159], v[200:203], v[0:3]
	s_barrier
	s_setprio 0
	s_add_i32 s57, 0, 0x18000
	s_add_i32 s58, 0, 0x1c000
	v_add_u32_e32 v140, s57, v210
	v_add_u32_e32 v156, s58, v210
	ds_read_b128 v[128:131], v140
	ds_read_b128 v[132:135], v140 offset:1024
	ds_read_b128 v[136:139], v140 offset:2048
	ds_read_b128 v[140:143], v140 offset:3072
	ds_read_b128 v[144:147], v156
	ds_read_b128 v[148:151], v156 offset:1024
	ds_read_b128 v[152:155], v156 offset:2048
	ds_read_b128 v[156:159], v156 offset:3072
	s_add_u32 s28, s36, 0x100000
	s_addc_u32 s29, s37, 0
	s_mov_b32 m0, s42
	v_lshl_add_u64 v[222:223], s[28:29], 0, v[176:177]
	ds_read_b128 v[160:163], v214 offset:32768
	ds_read_b128 v[164:167], v214 offset:33792
	ds_read_b128 v[168:171], v214 offset:34816
	ds_read_b128 v[172:175], v214 offset:35840
	ds_read_b128 v[188:191], v214 offset:36864
	ds_read_b128 v[192:195], v214 offset:37888
	ds_read_b128 v[196:199], v214 offset:38912
	ds_read_b128 v[200:203], v214 offset:39936
	global_load_lds_dwordx4 v[222:223], off
	v_lshl_add_u64 v[222:223], s[28:29], 0, v[178:179]
	s_mov_b32 m0, s43
	s_nop 0
	global_load_lds_dwordx4 v[222:223], off
	s_waitcnt vmcnt(8)
	s_waitcnt lgkmcnt(0)
	s_setprio 1
	s_barrier
	v_mfma_f32_16x16x32_bf16 v[124:127], v[128:131], v[160:163], v[124:127]
	v_mfma_f32_16x16x32_bf16 v[120:123], v[136:139], v[160:163], v[120:123]
	v_mfma_f32_16x16x32_bf16 v[108:111], v[128:131], v[168:171], v[108:111]
	v_mfma_f32_16x16x32_bf16 v[104:107], v[136:139], v[168:171], v[104:107]
	v_mfma_f32_16x16x32_bf16 v[92:95], v[128:131], v[188:191], v[92:95]
	v_mfma_f32_16x16x32_bf16 v[88:91], v[136:139], v[188:191], v[88:91]
	v_mfma_f32_16x16x32_bf16 v[76:79], v[128:131], v[196:199], v[76:79]
	v_mfma_f32_16x16x32_bf16 v[72:75], v[136:139], v[196:199], v[72:75]
	v_mfma_f32_16x16x32_bf16 v[124:127], v[132:135], v[164:167], v[124:127]
	v_mfma_f32_16x16x32_bf16 v[120:123], v[140:143], v[164:167], v[120:123]
	v_mfma_f32_16x16x32_bf16 v[108:111], v[132:135], v[172:175], v[108:111]
	v_mfma_f32_16x16x32_bf16 v[104:107], v[140:143], v[172:175], v[104:107]
	v_mfma_f32_16x16x32_bf16 v[92:95], v[132:135], v[192:195], v[92:95]
	v_mfma_f32_16x16x32_bf16 v[88:91], v[140:143], v[192:195], v[88:91]
	v_mfma_f32_16x16x32_bf16 v[76:79], v[132:135], v[200:203], v[76:79]
	v_mfma_f32_16x16x32_bf16 v[72:75], v[140:143], v[200:203], v[72:75]
	s_setprio 0
	s_setprio 1
	v_mfma_f32_16x16x32_bf16 v[116:119], v[144:147], v[160:163], v[116:119]
	v_mfma_f32_16x16x32_bf16 v[112:115], v[152:155], v[160:163], v[112:115]
	v_mfma_f32_16x16x32_bf16 v[100:103], v[144:147], v[168:171], v[100:103]
	v_mfma_f32_16x16x32_bf16 v[96:99], v[152:155], v[168:171], v[96:99]
	v_mfma_f32_16x16x32_bf16 v[84:87], v[144:147], v[188:191], v[84:87]
	v_mfma_f32_16x16x32_bf16 v[80:83], v[152:155], v[188:191], v[80:83]
	v_mfma_f32_16x16x32_bf16 v[68:71], v[144:147], v[196:199], v[68:71]
	v_mfma_f32_16x16x32_bf16 v[64:67], v[152:155], v[196:199], v[64:67]
	v_mfma_f32_16x16x32_bf16 v[116:119], v[148:151], v[164:167], v[116:119]
	v_mfma_f32_16x16x32_bf16 v[112:115], v[156:159], v[164:167], v[112:115]
	v_mfma_f32_16x16x32_bf16 v[100:103], v[148:151], v[172:175], v[100:103]
	v_mfma_f32_16x16x32_bf16 v[96:99], v[156:159], v[172:175], v[96:99]
	v_mfma_f32_16x16x32_bf16 v[84:87], v[148:151], v[192:195], v[84:87]
	v_mfma_f32_16x16x32_bf16 v[80:83], v[156:159], v[192:195], v[80:83]
	v_mfma_f32_16x16x32_bf16 v[68:71], v[148:151], v[200:203], v[68:71]
	v_mfma_f32_16x16x32_bf16 v[64:67], v[156:159], v[200:203], v[64:67]
	s_barrier
	s_setprio 0
	s_add_i32 s28, s57, s40
	v_lshl_add_u64 v[204:205], v[204:205], 0, s[12:13]
	s_mov_b32 m0, s28
	ds_read_b128 v[160:163], v214 offset:49152
	ds_read_b128 v[164:167], v214 offset:50176
	ds_read_b128 v[168:171], v214 offset:51200
	ds_read_b128 v[172:175], v214 offset:52224
	ds_read_b128 v[188:191], v214 offset:53248
	ds_read_b128 v[192:195], v214 offset:54272
	ds_read_b128 v[196:199], v214 offset:55296
	ds_read_b128 v[200:203], v214 offset:56320
	global_load_lds_dwordx4 v[204:205], off
	s_add_i32 m0, s28, 0x2000
	s_add_u32 s28, s34, 0x100080
	v_lshl_add_u64 v[204:205], v[216:217], 0, s[12:13]
	s_addc_u32 s29, s35, 0
	s_add_i32 s34, s58, s40
	global_load_lds_dwordx4 v[204:205], off
	v_lshl_add_u64 v[204:205], s[28:29], 0, v[176:177]
	s_mov_b32 m0, s34
	s_nop 0
	global_load_lds_dwordx4 v[204:205], off
	v_lshl_add_u64 v[204:205], s[28:29], 0, v[178:179]
	s_add_i32 m0, s34, 0x2000
	s_nop 0
	global_load_lds_dwordx4 v[204:205], off
	v_lshl_add_u64 v[204:205], v[218:219], 0, s[12:13]
	s_mov_b32 m0, s45
	s_nop 0
	global_load_lds_dwordx4 v[204:205], off
	v_lshl_add_u64 v[204:205], v[220:221], 0, s[12:13]
	s_mov_b32 m0, s48
	s_nop 0
	global_load_lds_dwordx4 v[204:205], off
	s_waitcnt vmcnt(8)
	s_waitcnt lgkmcnt(0)
	s_setprio 1
	s_barrier
	v_mfma_f32_16x16x32_bf16 v[60:63], v[128:131], v[160:163], v[60:63]
	v_mfma_f32_16x16x32_bf16 v[56:59], v[136:139], v[160:163], v[56:59]
	v_mfma_f32_16x16x32_bf16 v[44:47], v[128:131], v[168:171], v[44:47]
	v_mfma_f32_16x16x32_bf16 v[40:43], v[136:139], v[168:171], v[40:43]
	v_mfma_f32_16x16x32_bf16 v[28:31], v[128:131], v[188:191], v[28:31]
	v_mfma_f32_16x16x32_bf16 v[24:27], v[136:139], v[188:191], v[24:27]
	v_mfma_f32_16x16x32_bf16 v[12:15], v[128:131], v[196:199], v[12:15]
	v_mfma_f32_16x16x32_bf16 v[8:11], v[136:139], v[196:199], v[8:11]
	v_mfma_f32_16x16x32_bf16 v[60:63], v[132:135], v[164:167], v[60:63]
	v_mfma_f32_16x16x32_bf16 v[56:59], v[140:143], v[164:167], v[56:59]
	v_mfma_f32_16x16x32_bf16 v[44:47], v[132:135], v[172:175], v[44:47]
	v_mfma_f32_16x16x32_bf16 v[40:43], v[140:143], v[172:175], v[40:43]
	v_mfma_f32_16x16x32_bf16 v[28:31], v[132:135], v[192:195], v[28:31]
	v_mfma_f32_16x16x32_bf16 v[24:27], v[140:143], v[192:195], v[24:27]
	v_mfma_f32_16x16x32_bf16 v[12:15], v[132:135], v[200:203], v[12:15]
	v_mfma_f32_16x16x32_bf16 v[8:11], v[140:143], v[200:203], v[8:11]
	s_setprio 0
	s_setprio 1
	v_mfma_f32_16x16x32_bf16 v[52:55], v[144:147], v[160:163], v[52:55]
	v_mfma_f32_16x16x32_bf16 v[48:51], v[152:155], v[160:163], v[48:51]
	v_mfma_f32_16x16x32_bf16 v[36:39], v[144:147], v[168:171], v[36:39]
	v_mfma_f32_16x16x32_bf16 v[32:35], v[152:155], v[168:171], v[32:35]
	v_mfma_f32_16x16x32_bf16 v[20:23], v[144:147], v[188:191], v[20:23]
	v_mfma_f32_16x16x32_bf16 v[16:19], v[152:155], v[188:191], v[16:19]
	v_mfma_f32_16x16x32_bf16 v[4:7], v[144:147], v[196:199], v[4:7]
	v_mfma_f32_16x16x32_bf16 v[0:3], v[152:155], v[196:199], v[0:3]
	v_mfma_f32_16x16x32_bf16 v[52:55], v[148:151], v[164:167], v[52:55]
	v_mfma_f32_16x16x32_bf16 v[48:51], v[156:159], v[164:167], v[48:51]
	v_mfma_f32_16x16x32_bf16 v[36:39], v[148:151], v[172:175], v[36:39]
	v_mfma_f32_16x16x32_bf16 v[32:35], v[156:159], v[172:175], v[32:35]
	v_mfma_f32_16x16x32_bf16 v[20:23], v[148:151], v[192:195], v[20:23]
	v_mfma_f32_16x16x32_bf16 v[16:19], v[156:159], v[192:195], v[16:19]
	v_mfma_f32_16x16x32_bf16 v[4:7], v[148:151], v[200:203], v[4:7]
	v_mfma_f32_16x16x32_bf16 v[0:3], v[156:159], v[200:203], v[0:3]
	s_barrier
	s_setprio 0
	s_add_i32 s56, s56, 2
	s_add_u32 s54, s54, 0x100
	s_addc_u32 s55, s55, 0
	s_cmp_gt_u32 s56, 61
	s_mov_b64 s[28:29], s[30:31]
	s_cbranch_scc0 .LBB0_1389
	s_and_b64 vcc, exec, s[14:15]
	s_cbranch_vccz .LBB0_1392
	s_barrier
